# v030 + MLA rescale compare issued right after row-sum (branch no longer waits on VALU->VCC latency)
# baseline (speedup 1.0000x reference)
.LBB0_893:
	ds_read_b128 v[118:121], v181 offset:32
	ds_read_b128 v[138:141], v181 offset:6688
	s_waitcnt lgkmcnt(3)
	v_mfma_f32_32x32x16_bf16 v[80:95], v[64:67], v[144:147], v[32:47]
	v_exp_f32_e32 v117, v122
	v_exp_f32_e32 v142, v123
	v_exp_f32_e32 v143, v124
	v_exp_f32_e32 v202, v125
	v_exp_f32_e32 v126, v126
	v_exp_f32_e32 v127, v127
	s_waitcnt lgkmcnt(2)
	v_mfma_f32_32x32x16_bf16 v[64:79], v[112:115], v[144:147], v[32:47]
	ds_read_b128 v[112:115], v181 offset:64
	ds_read_b128 v[122:125], v181 offset:6720
	s_waitcnt lgkmcnt(3)
	v_mfma_f32_32x32x16_bf16 v[80:95], v[118:121], v[148:151], v[80:95]
	v_cvt_pk_bf16_f32 v118, v117, v142
	v_add_f32_e32 v117, v143, v117
	v_add_f32_e32 v120, v202, v142
	v_add_f32_e32 v117, v126, v117
	s_waitcnt lgkmcnt(2)
	v_mfma_f32_32x32x16_bf16 v[64:79], v[138:141], v[148:151], v[64:79]
	v_add_f32_e32 v121, v127, v120
	v_exp_f32_e32 v203, v128
	v_exp_f32_e32 v204, v129
	v_exp_f32_e32 v205, v130
	v_exp_f32_e32 v213, v131
	v_exp_f32_e32 v214, v132
	v_exp_f32_e32 v215, v133
	v_cvt_pk_bf16_f32 v119, v143, v202
	v_cvt_pk_bf16_f32 v120, v126, v127
	ds_read_b128 v[126:129], v181 offset:96
	ds_read_b128 v[130:133], v181 offset:6752
	s_waitcnt lgkmcnt(3)
	v_mfma_f32_32x32x16_bf16 v[80:95], v[112:115], v[152:155], v[80:95]
	v_add_f32_e32 v112, v203, v117
	v_add_f32_e32 v113, v204, v121
	v_add_f32_e32 v114, v205, v112
	v_add_f32_e32 v113, v213, v113
	v_add_f32_e32 v114, v214, v114
	v_add_f32_e32 v115, v215, v113
	s_waitcnt lgkmcnt(2)
	v_mfma_f32_32x32x16_bf16 v[64:79], v[122:125], v[152:155], v[64:79]
	v_exp_f32_e32 v138, v134
	v_exp_f32_e32 v139, v135
	v_exp_f32_e32 v140, v136
	v_exp_f32_e32 v141, v137
	v_cvt_pk_bf16_f32 v121, v203, v204
	v_cvt_pk_bf16_f32 v112, v205, v213
	v_cvt_pk_bf16_f32 v113, v214, v215
	ds_read_b128 v[122:125], v181 offset:128
	ds_read_b128 v[134:137], v181 offset:6784
	s_waitcnt lgkmcnt(3)
	v_mfma_f32_32x32x16_bf16 v[80:95], v[126:129], v[156:159], v[80:95]
	v_exp_f32_e32 v117, v96
	v_exp_f32_e32 v142, v97
	v_add_f32_e32 v96, v138, v114
	v_add_f32_e32 v97, v139, v115
	v_exp_f32_e32 v203, v100
	v_exp_f32_e32 v204, v101
	s_waitcnt lgkmcnt(2)
	v_mfma_f32_32x32x16_bf16 v[64:79], v[130:133], v[156:159], v[64:79]
	v_add_f32_e32 v100, v140, v96
	v_add_f32_e32 v101, v141, v97
	v_exp_f32_e32 v143, v98
	v_exp_f32_e32 v202, v99
	v_cvt_pk_bf16_f32 v114, v138, v139
	v_cvt_pk_bf16_f32 v115, v140, v141
	ds_read_b128 v[96:99], v181 offset:160
	ds_read_b128 v[126:129], v181 offset:6816
	s_waitcnt lgkmcnt(3)
	v_mfma_f32_32x32x16_bf16 v[80:95], v[122:125], v[160:163], v[80:95]
	v_exp_f32_e32 v130, v102
	v_add_f32_e32 v102, v117, v100
	v_add_f32_e32 v101, v142, v101
	v_exp_f32_e32 v131, v104
	v_add_f32_e32 v102, v143, v102
	v_add_f32_e32 v104, v202, v101
	s_waitcnt lgkmcnt(2)
	v_mfma_f32_32x32x16_bf16 v[64:79], v[134:137], v[160:163], v[64:79]
	v_cvt_pk_bf16_f32 v100, v117, v142
	v_add_f32_e32 v117, v203, v102
	v_add_f32_e32 v134, v204, v104
	v_exp_f32_e32 v103, v103
	v_exp_f32_e32 v132, v105
	v_exp_f32_e32 v133, v106
	v_exp_f32_e32 v138, v107
	v_cvt_pk_bf16_f32 v101, v143, v202
	v_cvt_pk_bf16_f32 v102, v203, v204
	ds_read_b128 v[104:107], v211 offset:27648
	ds_read_b128 v[122:125], v211 offset:32256
	s_waitcnt lgkmcnt(3)
	v_mfma_f32_32x32x16_bf16 v[80:95], v[96:99], v[164:167], v[80:95]
	v_add_f32_e32 v96, v130, v117
	v_add_f32_e32 v97, v103, v134
	v_add_f32_e32 v98, v131, v96
	v_add_f32_e32 v97, v132, v97
	v_add_f32_e32 v98, v133, v98
	v_add_f32_e32 v99, v138, v97
	s_waitcnt lgkmcnt(2)
	v_mfma_f32_32x32x16_bf16 v[64:79], v[126:129], v[164:167], v[64:79]
	v_exp_f32_e32 v135, v108
	v_exp_f32_e32 v136, v109
	v_exp_f32_e32 v137, v110
	v_exp_f32_e32 v139, v111
	v_cvt_pk_bf16_f32 v103, v130, v103
	v_cvt_pk_bf16_f32 v96, v131, v132
	v_cvt_pk_bf16_f32 v97, v133, v138
	ds_read_b128 v[108:111], v211 offset:27680
	ds_read_b128 v[126:129], v211 offset:32288
	s_waitcnt lgkmcnt(3)
	v_mfma_f32_32x32x16_bf16 v[0:15], v[104:107], v[118:121], v[0:15]
	v_add_f32_e32 v104, v135, v98
	v_add_f32_e32 v99, v136, v99
	v_add_f32_e32 v117, v137, v104
	v_add_f32_e32 v130, v139, v99
	v_cvt_pk_bf16_f32 v98, v135, v136
	v_cvt_pk_bf16_f32 v99, v137, v139
	s_waitcnt lgkmcnt(2)
	v_mfma_f32_32x32x16_bf16 v[16:31], v[122:125], v[118:121], v[16:31]
	ds_read_b128 v[104:107], v211 offset:27712
	s_waitcnt lgkmcnt(2)
	v_mfma_f32_32x32x16_bf16 v[0:15], v[108:111], v[112:115], v[0:15]
	ds_read_b128 v[108:111], v211 offset:32320
	s_waitcnt lgkmcnt(2)
	v_mfma_f32_32x32x16_bf16 v[16:31], v[126:129], v[112:115], v[16:31]
	ds_read_b128 v[112:115], v211 offset:27744
	ds_read_b128 v[118:121], v211 offset:32352
	s_waitcnt lgkmcnt(3)
	v_mfma_f32_32x32x16_bf16 v[0:15], v[104:107], v[100:103], v[0:15]
	s_waitcnt lgkmcnt(2)
	v_mfma_f32_32x32x16_bf16 v[16:31], v[108:111], v[100:103], v[16:31]
	s_waitcnt lgkmcnt(1)
	v_mfma_f32_32x32x16_bf16 v[0:15], v[112:115], v[96:99], v[0:15]
	v_add_f32_e32 v221, v117, v130
	v_cmp_lt_f32_e32 vcc, s58, v221
	v_add_f32_e32 v116, v116, v221
	s_waitcnt lgkmcnt(0)
	v_mfma_f32_32x32x16_bf16 v[16:31], v[118:121], v[96:99], v[16:31]
	s_waitcnt vmcnt(0)
	s_add_u32 s10, s10, 0x400
	s_addc_u32 s11, s11, 0
	v_lshl_add_u64 v[200:201], v[200:201], 0, v[168:169]
	s_cmpk_lt_u32 s16, 0x78
	v_lshl_add_u64 v[196:197], v[196:197], 0, v[198:199]
	s_barrier
	s_cbranch_scc0 .LBB0_873
.LBB0_894:
	ds_read_b128 v[96:99], v181 offset:13312
	ds_read_b128 v[112:115], v181 offset:19968
	s_cmp_eq_u32 s10, 0
	s_cbranch_scc1 .LBB0_947
	s_mov_b64 s[14:15], 0
	s_mov_b64 s[12:13], 0
	s_cbranch_vccz .LBB0_897
	v_mov_b32_e32 v222, v221
	v_mov_b32_e32 v223, v221
	s_nop 1
	v_permlane32_swap_b32_e32 v222, v223
	v_add_f32_e32 v222, v222, v223
	v_log_f32_e32 v222, v222
	s_nop 0
	v_max_f32_e32 v101, 0, v222
	s_mov_b64 s[12:13], -1

.LBB0_905:
	ds_read_b128 v[118:121], v181 offset:13344
	ds_read_b128 v[122:125], v181 offset:20000
	s_waitcnt lgkmcnt(3)
	v_mfma_f32_32x32x16_bf16 v[128:143], v[96:99], v[144:147], v[32:47]
	v_exp_f32_e32 v117, v80
	v_exp_f32_e32 v126, v81
	v_exp_f32_e32 v127, v82
	v_exp_f32_e32 v213, v83
	v_exp_f32_e32 v214, v84
	v_exp_f32_e32 v215, v85
	s_waitcnt lgkmcnt(2)
	v_mfma_f32_32x32x16_bf16 v[96:111], v[112:115], v[144:147], v[32:47]
	ds_read_b128 v[80:83], v181 offset:13376
	ds_read_b128 v[112:115], v181 offset:20032
	s_waitcnt lgkmcnt(3)
	v_mfma_f32_32x32x16_bf16 v[128:143], v[118:121], v[148:151], v[128:143]
	v_exp_f32_e32 v216, v86
	v_exp_f32_e32 v217, v88
	v_add_f32_e32 v88, v127, v117
	v_add_f32_e32 v86, v213, v126
	s_waitcnt lgkmcnt(2)
	v_mfma_f32_32x32x16_bf16 v[96:111], v[122:125], v[148:151], v[96:111]
	v_cvt_pk_bf16_f32 v84, v117, v126
	v_add_f32_e32 v117, v214, v88
	v_add_f32_e32 v122, v215, v86
	v_exp_f32_e32 v87, v87
	v_exp_f32_e32 v218, v89
	v_exp_f32_e32 v219, v90
	v_exp_f32_e32 v220, v91
	v_cvt_pk_bf16_f32 v85, v127, v213
	v_cvt_pk_bf16_f32 v86, v214, v215
	ds_read_b128 v[88:91], v181 offset:13408
	ds_read_b128 v[118:121], v181 offset:20064
	s_waitcnt lgkmcnt(3)
	v_mfma_f32_32x32x16_bf16 v[128:143], v[80:83], v[152:155], v[128:143]
	v_add_f32_e32 v80, v216, v117
	v_add_f32_e32 v81, v87, v122
	v_add_f32_e32 v82, v217, v80
	v_add_f32_e32 v81, v218, v81
	v_add_f32_e32 v82, v219, v82
	v_add_f32_e32 v83, v220, v81
	s_waitcnt lgkmcnt(2)
	v_mfma_f32_32x32x16_bf16 v[96:111], v[112:115], v[152:155], v[96:111]
	v_exp_f32_e32 v123, v92
	v_exp_f32_e32 v124, v93
	v_exp_f32_e32 v125, v94
	v_exp_f32_e32 v126, v95
	v_cvt_pk_bf16_f32 v87, v216, v87
	v_cvt_pk_bf16_f32 v80, v217, v218
	v_cvt_pk_bf16_f32 v81, v219, v220
	ds_read_b128 v[92:95], v181 offset:13440
	ds_read_b128 v[112:115], v181 offset:20096
	s_waitcnt lgkmcnt(3)
	v_mfma_f32_32x32x16_bf16 v[128:143], v[88:91], v[156:159], v[128:143]
	v_exp_f32_e32 v117, v64
	v_exp_f32_e32 v122, v65
	v_add_f32_e32 v64, v123, v82
	v_add_f32_e32 v65, v124, v83
	v_exp_f32_e32 v214, v68
	v_exp_f32_e32 v215, v69
	s_waitcnt lgkmcnt(2)
	v_mfma_f32_32x32x16_bf16 v[96:111], v[118:121], v[156:159], v[96:111]
	v_add_f32_e32 v68, v125, v64
	v_add_f32_e32 v69, v126, v65
	v_exp_f32_e32 v127, v66
	v_exp_f32_e32 v213, v67
	v_cvt_pk_bf16_f32 v82, v123, v124
	v_cvt_pk_bf16_f32 v83, v125, v126
	ds_read_b128 v[64:67], v181 offset:13472
	ds_read_b128 v[88:91], v181 offset:20128
	s_waitcnt lgkmcnt(3)
	v_mfma_f32_32x32x16_bf16 v[128:143], v[92:95], v[160:163], v[128:143]
	v_exp_f32_e32 v118, v70
	v_add_f32_e32 v70, v117, v68
	v_add_f32_e32 v69, v122, v69
	v_exp_f32_e32 v119, v72
	v_add_f32_e32 v70, v127, v70
	v_add_f32_e32 v72, v213, v69
	s_waitcnt lgkmcnt(2)
	v_mfma_f32_32x32x16_bf16 v[96:111], v[112:115], v[160:163], v[96:111]
	v_add_f32_e32 v112, v214, v70
	v_add_f32_e32 v113, v215, v72
	v_exp_f32_e32 v71, v71
	v_exp_f32_e32 v120, v73
	v_exp_f32_e32 v121, v74
	v_exp_f32_e32 v123, v75
	v_cvt_pk_bf16_f32 v68, v117, v122
	v_cvt_pk_bf16_f32 v69, v127, v213
	v_cvt_pk_bf16_f32 v70, v214, v215
	ds_read_b128 v[72:75], v210 offset:53248
	ds_read_b128 v[92:95], v210 offset:57856
	s_waitcnt lgkmcnt(3)
	v_mfma_f32_32x32x16_bf16 v[128:143], v[64:67], v[164:167], v[128:143]
	v_add_f32_e32 v64, v118, v112
	v_add_f32_e32 v65, v71, v113
	v_add_f32_e32 v66, v119, v64
	v_add_f32_e32 v65, v120, v65
	v_add_f32_e32 v66, v121, v66
	v_add_f32_e32 v67, v123, v65
	s_waitcnt lgkmcnt(2)
	v_mfma_f32_32x32x16_bf16 v[96:111], v[88:91], v[164:167], v[96:111]
	v_exp_f32_e32 v114, v76
	v_exp_f32_e32 v115, v77
	v_exp_f32_e32 v117, v78
	v_exp_f32_e32 v122, v79
	v_cvt_pk_bf16_f32 v71, v118, v71
	v_cvt_pk_bf16_f32 v64, v119, v120
	v_cvt_pk_bf16_f32 v65, v121, v123
	ds_read_b128 v[76:79], v210 offset:53280
	ds_read_b128 v[88:91], v210 offset:57888
	s_waitcnt lgkmcnt(3)
	v_mfma_f32_32x32x16_bf16 v[0:15], v[72:75], v[84:87], v[0:15]
	v_add_f32_e32 v72, v114, v66
	v_add_f32_e32 v67, v115, v67
	v_add_f32_e32 v112, v117, v72
	v_add_f32_e32 v113, v122, v67
	v_cvt_pk_bf16_f32 v66, v114, v115
	v_cvt_pk_bf16_f32 v67, v117, v122
	s_waitcnt lgkmcnt(2)
	v_mfma_f32_32x32x16_bf16 v[16:31], v[92:95], v[84:87], v[16:31]
	ds_read_b128 v[72:75], v210 offset:53312
	s_waitcnt lgkmcnt(2)
	v_mfma_f32_32x32x16_bf16 v[0:15], v[76:79], v[80:83], v[0:15]
	ds_read_b128 v[76:79], v210 offset:57920
	s_waitcnt lgkmcnt(2)
	v_mfma_f32_32x32x16_bf16 v[16:31], v[88:91], v[80:83], v[16:31]
	ds_read_b128 v[80:83], v210 offset:53344
	ds_read_b128 v[88:91], v210 offset:57952
	s_waitcnt lgkmcnt(3)
	v_mfma_f32_32x32x16_bf16 v[0:15], v[72:75], v[68:71], v[0:15]
	s_waitcnt lgkmcnt(2)
	v_mfma_f32_32x32x16_bf16 v[16:31], v[76:79], v[68:71], v[16:31]
	s_waitcnt lgkmcnt(1)
	v_mfma_f32_32x32x16_bf16 v[0:15], v[80:83], v[64:67], v[0:15]
	v_add_f32_e32 v221, v112, v113
	v_cmp_lt_f32_e32 vcc, s58, v221
	v_add_f32_e32 v86, v116, v221
	s_waitcnt lgkmcnt(0)
	v_mfma_f32_32x32x16_bf16 v[16:31], v[88:91], v[64:67], v[16:31]
	ds_read_b128 v[64:67], v181 offset:26624
	ds_read_b128 v[80:83], v181 offset:33280
	s_cbranch_vccz .LBB0_907
	v_mov_b32_e32 v222, v221
	v_mov_b32_e32 v223, v221
	s_nop 1
	v_permlane32_swap_b32_e32 v222, v223
	v_add_f32_e32 v222, v222, v223
	v_log_f32_e32 v222, v222
	s_nop 0
	v_max_f32_e32 v33, 0, v222
	v_exp_f32_e64 v34, -v33
	v_add_f32_e32 v212, v212, v33
	v_xor_b32_e32 v32, 0x80000000, v212
	v_sub_f32_e32 v143, v143, v33
	v_pk_mul_f32 v[14:15], v[14:15], v[34:35] op_sel_hi:[1,0]
	v_pk_mul_f32 v[12:13], v[12:13], v[34:35] op_sel_hi:[1,0]
	v_pk_mul_f32 v[10:11], v[10:11], v[34:35] op_sel_hi:[1,0]
	v_pk_mul_f32 v[8:9], v[8:9], v[34:35] op_sel_hi:[1,0]
	v_pk_mul_f32 v[6:7], v[6:7], v[34:35] op_sel_hi:[1,0]
	v_pk_mul_f32 v[4:5], v[4:5], v[34:35] op_sel_hi:[1,0]
	v_pk_mul_f32 v[2:3], v[2:3], v[34:35] op_sel_hi:[1,0]
	v_pk_mul_f32 v[0:1], v[0:1], v[34:35] op_sel_hi:[1,0]
	v_pk_mul_f32 v[30:31], v[30:31], v[34:35] op_sel_hi:[1,0]
	v_pk_mul_f32 v[28:29], v[28:29], v[34:35] op_sel_hi:[1,0]
	v_pk_mul_f32 v[26:27], v[26:27], v[34:35] op_sel_hi:[1,0]
	v_pk_mul_f32 v[24:25], v[24:25], v[34:35] op_sel_hi:[1,0]
	v_pk_mul_f32 v[22:23], v[22:23], v[34:35] op_sel_hi:[1,0]
	v_pk_mul_f32 v[20:21], v[20:21], v[34:35] op_sel_hi:[1,0]
	v_pk_mul_f32 v[18:19], v[18:19], v[34:35] op_sel_hi:[1,0]
	v_pk_mul_f32 v[16:17], v[16:17], v[34:35] op_sel_hi:[1,0]
	v_sub_f32_e32 v142, v142, v33
	v_sub_f32_e32 v141, v141, v33
	v_sub_f32_e32 v140, v140, v33
	v_sub_f32_e32 v139, v139, v33
	v_sub_f32_e32 v138, v138, v33
	v_sub_f32_e32 v137, v137, v33
	v_sub_f32_e32 v136, v136, v33
	v_sub_f32_e32 v135, v135, v33
	v_sub_f32_e32 v134, v134, v33
	v_sub_f32_e32 v133, v133, v33
	v_sub_f32_e32 v132, v132, v33
	v_sub_f32_e32 v131, v131, v33
	v_sub_f32_e32 v130, v130, v33
	v_sub_f32_e32 v129, v129, v33
	v_sub_f32_e32 v128, v128, v33
	v_sub_f32_e32 v111, v111, v33
	v_sub_f32_e32 v110, v110, v33
	v_sub_f32_e32 v109, v109, v33
	v_sub_f32_e32 v108, v108, v33
	v_sub_f32_e32 v107, v107, v33
	v_sub_f32_e32 v106, v106, v33
	v_sub_f32_e32 v105, v105, v33
	v_sub_f32_e32 v104, v104, v33
	v_sub_f32_e32 v103, v103, v33
	v_sub_f32_e32 v102, v102, v33
	v_sub_f32_e32 v101, v101, v33
	v_sub_f32_e32 v100, v100, v33
	v_sub_f32_e32 v99, v99, v33
	v_sub_f32_e32 v98, v98, v33
	v_sub_f32_e32 v97, v97, v33
	v_sub_f32_e32 v96, v96, v33
	v_mul_f32_e32 v86, v86, v34
	v_mov_b32_e32 v33, v32
	v_mov_b32_e32 v34, v32
	v_mov_b32_e32 v35, v32
	v_mov_b32_e32 v36, v32
	v_mov_b32_e32 v37, v32
	v_mov_b32_e32 v38, v32
	v_mov_b32_e32 v39, v32
	v_mov_b32_e32 v40, v32
	v_mov_b32_e32 v41, v32
	v_mov_b32_e32 v42, v32
	v_mov_b32_e32 v43, v32
	v_mov_b32_e32 v44, v32
	v_mov_b32_e32 v45, v32
	v_mov_b32_e32 v46, v32
	v_mov_b32_e32 v47, v32
	v_mov_b32_e32 v48, v32
	v_mov_b32_e32 v49, v32
	v_mov_b32_e32 v50, v32
	v_mov_b32_e32 v51, v32
	v_mov_b32_e32 v52, v32
	v_mov_b32_e32 v53, v32
	v_mov_b32_e32 v54, v32
	v_mov_b32_e32 v55, v32
	v_mov_b32_e32 v56, v32
	v_mov_b32_e32 v57, v32
	v_mov_b32_e32 v58, v32
	v_mov_b32_e32 v59, v32
	v_mov_b32_e32 v60, v32
	v_mov_b32_e32 v61, v32
	v_mov_b32_e32 v62, v32
	v_mov_b32_e32 v63, v32

.LBB0_911:
	ds_read_b128 v[88:91], v181 offset:26656
	ds_read_b128 v[92:95], v181 offset:33312
	s_waitcnt lgkmcnt(3)
	v_mfma_f32_32x32x16_bf16 v[112:127], v[64:67], v[144:147], v[32:47]
	v_exp_f32_e32 v87, v128
	v_exp_f32_e32 v213, v129
	v_exp_f32_e32 v214, v130
	v_exp_f32_e32 v215, v131
	v_exp_f32_e32 v132, v132
	v_exp_f32_e32 v133, v133
	s_waitcnt lgkmcnt(2)
	v_mfma_f32_32x32x16_bf16 v[64:79], v[80:83], v[144:147], v[32:47]
	ds_read_b128 v[80:83], v181 offset:26688
	ds_read_b128 v[128:131], v181 offset:33344
	s_waitcnt lgkmcnt(3)
	v_mfma_f32_32x32x16_bf16 v[112:127], v[88:91], v[148:151], v[112:127]
	v_cvt_pk_bf16_f32 v88, v87, v213
	v_add_f32_e32 v87, v214, v87
	v_add_f32_e32 v90, v215, v213
	v_add_f32_e32 v87, v132, v87
	s_waitcnt lgkmcnt(2)
	v_mfma_f32_32x32x16_bf16 v[64:79], v[92:95], v[148:151], v[64:79]
	v_add_f32_e32 v91, v133, v90
	v_exp_f32_e32 v216, v134
	v_exp_f32_e32 v217, v135
	v_exp_f32_e32 v136, v136
	v_exp_f32_e32 v137, v137
	v_exp_f32_e32 v138, v138
	v_exp_f32_e32 v139, v139
	v_cvt_pk_bf16_f32 v89, v214, v215
	v_cvt_pk_bf16_f32 v90, v132, v133
	ds_read_b128 v[92:95], v181 offset:26720
	ds_read_b128 v[132:135], v181 offset:33376
	s_waitcnt lgkmcnt(3)
	v_mfma_f32_32x32x16_bf16 v[112:127], v[80:83], v[152:155], v[112:127]
	v_add_f32_e32 v80, v216, v87
	v_add_f32_e32 v81, v217, v91
	v_add_f32_e32 v82, v136, v80
	v_add_f32_e32 v81, v137, v81
	v_add_f32_e32 v82, v138, v82
	v_add_f32_e32 v83, v139, v81
	s_waitcnt lgkmcnt(2)
	v_mfma_f32_32x32x16_bf16 v[64:79], v[128:131], v[152:155], v[64:79]
	v_exp_f32_e32 v140, v140
	v_exp_f32_e32 v141, v141
	v_exp_f32_e32 v142, v142
	v_exp_f32_e32 v143, v143
	v_cvt_pk_bf16_f32 v91, v216, v217
	v_cvt_pk_bf16_f32 v80, v136, v137
	v_cvt_pk_bf16_f32 v81, v138, v139
	ds_read_b128 v[128:131], v181 offset:26752
	ds_read_b128 v[136:139], v181 offset:33408
	s_waitcnt lgkmcnt(3)
	v_mfma_f32_32x32x16_bf16 v[112:127], v[92:95], v[156:159], v[112:127]
	v_exp_f32_e32 v87, v96
	v_add_f32_e32 v92, v140, v82
	v_add_f32_e32 v83, v141, v83
	v_exp_f32_e32 v216, v100
	v_exp_f32_e32 v217, v101
	v_add_f32_e32 v100, v142, v92
	s_waitcnt lgkmcnt(2)
	v_mfma_f32_32x32x16_bf16 v[64:79], v[132:135], v[156:159], v[64:79]
	v_add_f32_e32 v101, v143, v83
	v_exp_f32_e32 v213, v97
	v_exp_f32_e32 v214, v98
	v_exp_f32_e32 v215, v99
	v_cvt_pk_bf16_f32 v82, v140, v141
	v_cvt_pk_bf16_f32 v83, v142, v143
	ds_read_b128 v[92:95], v181 offset:26784
	ds_read_b128 v[96:99], v181 offset:33440
	s_waitcnt lgkmcnt(3)
	v_mfma_f32_32x32x16_bf16 v[112:127], v[128:131], v[160:163], v[112:127]
	v_exp_f32_e32 v132, v102
	v_add_f32_e32 v102, v87, v100
	v_add_f32_e32 v101, v213, v101
	v_cvt_pk_bf16_f32 v100, v87, v213
	v_add_f32_e32 v87, v214, v102
	v_add_f32_e32 v102, v215, v101
	s_waitcnt lgkmcnt(2)
	v_mfma_f32_32x32x16_bf16 v[64:79], v[136:139], v[160:163], v[64:79]
	v_add_f32_e32 v87, v216, v87
	v_add_f32_e32 v136, v217, v102
	v_exp_f32_e32 v103, v103
	v_exp_f32_e32 v133, v104
	v_exp_f32_e32 v134, v105
	v_exp_f32_e32 v135, v106
	v_exp_f32_e32 v140, v107
	v_cvt_pk_bf16_f32 v101, v214, v215
	v_cvt_pk_bf16_f32 v102, v216, v217
	ds_read_b128 v[104:107], v210 offset:62464
	ds_read_b128 v[128:131], v211 offset:13824
	s_waitcnt lgkmcnt(3)
	v_mfma_f32_32x32x16_bf16 v[112:127], v[92:95], v[164:167], v[112:127]
	v_add_f32_e32 v87, v132, v87
	v_add_f32_e32 v92, v103, v136
	v_add_f32_e32 v87, v133, v87
	v_add_f32_e32 v93, v134, v92
	v_add_f32_e32 v87, v135, v87
	v_add_f32_e32 v94, v140, v93
	s_waitcnt lgkmcnt(2)
	v_mfma_f32_32x32x16_bf16 v[64:79], v[96:99], v[164:167], v[64:79]
	v_exp_f32_e32 v137, v108
	v_exp_f32_e32 v138, v109
	v_exp_f32_e32 v139, v110
	v_exp_f32_e32 v141, v111
	v_cvt_pk_bf16_f32 v103, v132, v103
	v_cvt_pk_bf16_f32 v92, v133, v134
	v_cvt_pk_bf16_f32 v93, v135, v140
	ds_read_b128 v[96:99], v210 offset:62496
	ds_read_b128 v[108:111], v211 offset:13856
	s_waitcnt lgkmcnt(3)
	v_mfma_f32_32x32x16_bf16 v[0:15], v[104:107], v[88:91], v[0:15]
	v_add_f32_e32 v87, v137, v87
	v_add_f32_e32 v95, v138, v94
	v_add_f32_e32 v132, v139, v87
	v_add_f32_e32 v133, v141, v95
	v_cvt_pk_bf16_f32 v94, v137, v138
	v_cvt_pk_bf16_f32 v95, v139, v141
	s_waitcnt lgkmcnt(2)
	v_mfma_f32_32x32x16_bf16 v[16:31], v[128:131], v[88:91], v[16:31]
	ds_read_b128 v[88:91], v210 offset:62528
	s_waitcnt lgkmcnt(2)
	v_mfma_f32_32x32x16_bf16 v[0:15], v[96:99], v[80:83], v[0:15]
	ds_read_b128 v[96:99], v211 offset:13888
	s_waitcnt lgkmcnt(2)
	v_mfma_f32_32x32x16_bf16 v[16:31], v[108:111], v[80:83], v[16:31]
	ds_read_b128 v[80:83], v210 offset:62560
	ds_read_b128 v[104:107], v211 offset:13920
	s_waitcnt lgkmcnt(3)
	v_mfma_f32_32x32x16_bf16 v[0:15], v[88:91], v[100:103], v[0:15]
	s_waitcnt lgkmcnt(2)
	v_mfma_f32_32x32x16_bf16 v[16:31], v[96:99], v[100:103], v[16:31]
	s_waitcnt lgkmcnt(1)
	v_mfma_f32_32x32x16_bf16 v[0:15], v[80:83], v[92:95], v[0:15]
	v_add_f32_e32 v221, v132, v133
	v_cmp_lt_f32_e32 vcc, s58, v221
	v_add_f32_e32 v102, v86, v221
	s_waitcnt lgkmcnt(0)
	v_mfma_f32_32x32x16_bf16 v[16:31], v[104:107], v[92:95], v[16:31]
	s_waitcnt vmcnt(0)
	s_barrier
	ds_read_b128 v[80:83], v181 offset:39936
	ds_read_b128 v[96:99], v181 offset:46592
	s_cbranch_vccz .LBB0_913
	v_mov_b32_e32 v222, v221
	v_mov_b32_e32 v223, v221
	s_nop 1
	v_permlane32_swap_b32_e32 v222, v223
	v_add_f32_e32 v222, v222, v223
	v_log_f32_e32 v222, v222
	s_nop 0
	v_max_f32_e32 v33, 0, v222
	v_exp_f32_e64 v34, -v33
	v_add_f32_e32 v212, v212, v33
	v_xor_b32_e32 v32, 0x80000000, v212
	v_sub_f32_e32 v127, v127, v33
	v_pk_mul_f32 v[14:15], v[14:15], v[34:35] op_sel_hi:[1,0]
	v_pk_mul_f32 v[12:13], v[12:13], v[34:35] op_sel_hi:[1,0]
	v_pk_mul_f32 v[10:11], v[10:11], v[34:35] op_sel_hi:[1,0]
	v_pk_mul_f32 v[8:9], v[8:9], v[34:35] op_sel_hi:[1,0]
	v_pk_mul_f32 v[6:7], v[6:7], v[34:35] op_sel_hi:[1,0]
	v_pk_mul_f32 v[4:5], v[4:5], v[34:35] op_sel_hi:[1,0]
	v_pk_mul_f32 v[2:3], v[2:3], v[34:35] op_sel_hi:[1,0]
	v_pk_mul_f32 v[0:1], v[0:1], v[34:35] op_sel_hi:[1,0]
	v_pk_mul_f32 v[30:31], v[30:31], v[34:35] op_sel_hi:[1,0]
	v_pk_mul_f32 v[28:29], v[28:29], v[34:35] op_sel_hi:[1,0]
	v_pk_mul_f32 v[26:27], v[26:27], v[34:35] op_sel_hi:[1,0]
	v_pk_mul_f32 v[24:25], v[24:25], v[34:35] op_sel_hi:[1,0]
	v_pk_mul_f32 v[22:23], v[22:23], v[34:35] op_sel_hi:[1,0]
	v_pk_mul_f32 v[20:21], v[20:21], v[34:35] op_sel_hi:[1,0]
	v_pk_mul_f32 v[18:19], v[18:19], v[34:35] op_sel_hi:[1,0]
	v_pk_mul_f32 v[16:17], v[16:17], v[34:35] op_sel_hi:[1,0]
	v_sub_f32_e32 v126, v126, v33
	v_sub_f32_e32 v125, v125, v33
	v_sub_f32_e32 v124, v124, v33
	v_sub_f32_e32 v123, v123, v33
	v_sub_f32_e32 v122, v122, v33
	v_sub_f32_e32 v121, v121, v33
	v_sub_f32_e32 v120, v120, v33
	v_sub_f32_e32 v119, v119, v33
	v_sub_f32_e32 v118, v118, v33
	v_sub_f32_e32 v117, v117, v33
	v_sub_f32_e32 v116, v116, v33
	v_sub_f32_e32 v115, v115, v33
	v_sub_f32_e32 v114, v114, v33
	v_sub_f32_e32 v113, v113, v33
	v_sub_f32_e32 v112, v112, v33
	v_sub_f32_e32 v79, v79, v33
	v_sub_f32_e32 v78, v78, v33
	v_sub_f32_e32 v77, v77, v33
	v_sub_f32_e32 v76, v76, v33
	v_sub_f32_e32 v75, v75, v33
	v_sub_f32_e32 v74, v74, v33
	v_sub_f32_e32 v73, v73, v33
	v_sub_f32_e32 v72, v72, v33
	v_sub_f32_e32 v71, v71, v33
	v_sub_f32_e32 v70, v70, v33
	v_sub_f32_e32 v69, v69, v33
	v_sub_f32_e32 v68, v68, v33
	v_sub_f32_e32 v67, v67, v33
	v_sub_f32_e32 v66, v66, v33
	v_sub_f32_e32 v65, v65, v33
	v_sub_f32_e32 v64, v64, v33
	v_mul_f32_e32 v102, v102, v34
	v_mov_b32_e32 v33, v32
	v_mov_b32_e32 v34, v32
	v_mov_b32_e32 v35, v32
	v_mov_b32_e32 v36, v32
	v_mov_b32_e32 v37, v32
	v_mov_b32_e32 v38, v32
	v_mov_b32_e32 v39, v32
	v_mov_b32_e32 v40, v32
	v_mov_b32_e32 v41, v32
	v_mov_b32_e32 v42, v32
	v_mov_b32_e32 v43, v32
	v_mov_b32_e32 v44, v32
	v_mov_b32_e32 v45, v32
	v_mov_b32_e32 v46, v32
	v_mov_b32_e32 v47, v32
	v_mov_b32_e32 v48, v32
	v_mov_b32_e32 v49, v32
	v_mov_b32_e32 v50, v32
	v_mov_b32_e32 v51, v32
	v_mov_b32_e32 v52, v32
	v_mov_b32_e32 v53, v32
	v_mov_b32_e32 v54, v32
	v_mov_b32_e32 v55, v32
	v_mov_b32_e32 v56, v32
	v_mov_b32_e32 v57, v32
	v_mov_b32_e32 v58, v32
	v_mov_b32_e32 v59, v32
	v_mov_b32_e32 v60, v32
	v_mov_b32_e32 v61, v32
	v_mov_b32_e32 v62, v32
	v_mov_b32_e32 v63, v32

; __device__ __forceinline__ unsigned pk2(float lo, float hi) { return pg8::cvt_pk_bf16(lo, hi); }
; template <int LO, int HI> __device__ __forceinline__ void g_exp(f32x16& X) {
; #pragma unroll
;     for (int r = LO; r < HI; ++r) X[r] = __builtin_amdgcn_exp2f(X[r]);
; }
; template <int LO, int HI> __device__ __forceinline__ void g_sumpk(const f32x16& X, float& psa, float& psb, u32x4& pwlo, u32x4& pwhi) {
; #pragma unroll
;     for (int r = LO; r < HI; r += 2) { psa += X[r]; psb += X[r + 1]; const unsigned w = pk2(X[r], X[r + 1]); if (r < 8) pwlo[(r >> 1) & 3] = w; else pwhi[(r >> 1) & 3] = w; }
;     asm volatile("" : "+v"(psa), "+v"(psb));
; }
.LBB0_917:
	ds_read_b128 v[104:107], v181 offset:39968
	ds_read_b128 v[108:111], v181 offset:46624
	s_waitcnt lgkmcnt(3)
	v_mfma_f32_32x32x16_bf16 v[128:143], v[80:83], v[144:147], v[32:47]
	v_exp_f32_e32 v103, v112
	v_exp_f32_e32 v213, v113
	v_exp_f32_e32 v214, v114
	v_exp_f32_e32 v215, v115
	v_exp_f32_e32 v116, v116
	v_exp_f32_e32 v117, v117
	s_waitcnt lgkmcnt(2)
	v_mfma_f32_32x32x16_bf16 v[80:95], v[96:99], v[144:147], v[32:47]
	ds_read_b128 v[96:99], v181 offset:40000
	ds_read_b128 v[112:115], v181 offset:46656
	s_waitcnt lgkmcnt(3)
	v_mfma_f32_32x32x16_bf16 v[128:143], v[104:107], v[148:151], v[128:143]
	v_cvt_pk_bf16_f32 v104, v103, v213
	v_add_f32_e32 v103, v214, v103
	v_add_f32_e32 v106, v215, v213
	v_add_f32_e32 v103, v116, v103
	s_waitcnt lgkmcnt(2)
	v_mfma_f32_32x32x16_bf16 v[80:95], v[108:111], v[148:151], v[80:95]
	v_add_f32_e32 v107, v117, v106
	v_exp_f32_e32 v216, v118
	v_exp_f32_e32 v217, v119
	v_exp_f32_e32 v120, v120
	v_exp_f32_e32 v121, v121
	v_exp_f32_e32 v122, v122
	v_exp_f32_e32 v123, v123
	v_cvt_pk_bf16_f32 v105, v214, v215
	v_cvt_pk_bf16_f32 v106, v116, v117
	ds_read_b128 v[108:111], v181 offset:40032
	ds_read_b128 v[116:119], v181 offset:46688
	s_waitcnt lgkmcnt(3)
	v_mfma_f32_32x32x16_bf16 v[128:143], v[96:99], v[152:155], v[128:143]
	v_add_f32_e32 v96, v216, v103
	v_add_f32_e32 v97, v217, v107
	v_add_f32_e32 v98, v120, v96
	v_add_f32_e32 v97, v121, v97
	v_add_f32_e32 v98, v122, v98
	v_add_f32_e32 v99, v123, v97
	s_waitcnt lgkmcnt(2)
	v_mfma_f32_32x32x16_bf16 v[80:95], v[112:115], v[152:155], v[80:95]
	v_exp_f32_e32 v124, v124
	v_exp_f32_e32 v125, v125
	v_exp_f32_e32 v126, v126
	v_exp_f32_e32 v127, v127
	v_cvt_pk_bf16_f32 v107, v216, v217
	v_cvt_pk_bf16_f32 v96, v120, v121
	v_cvt_pk_bf16_f32 v97, v122, v123
	ds_read_b128 v[112:115], v181 offset:40064
	ds_read_b128 v[120:123], v181 offset:46720
	s_waitcnt lgkmcnt(3)
	v_mfma_f32_32x32x16_bf16 v[128:143], v[108:111], v[156:159], v[128:143]
	v_exp_f32_e32 v103, v64
	v_exp_f32_e32 v213, v65
	v_add_f32_e32 v64, v124, v98
	v_add_f32_e32 v65, v125, v99
	v_exp_f32_e32 v216, v68
	v_exp_f32_e32 v217, v69
	s_waitcnt lgkmcnt(2)
	v_mfma_f32_32x32x16_bf16 v[80:95], v[116:119], v[156:159], v[80:95]
	v_add_f32_e32 v68, v126, v64
	v_add_f32_e32 v69, v127, v65
	v_exp_f32_e32 v214, v66
	v_exp_f32_e32 v215, v67
	v_cvt_pk_bf16_f32 v98, v124, v125
	v_cvt_pk_bf16_f32 v99, v126, v127
	ds_read_b128 v[64:67], v181 offset:40096
	ds_read_b128 v[108:111], v181 offset:46752
	s_waitcnt lgkmcnt(3)
	v_mfma_f32_32x32x16_bf16 v[128:143], v[112:115], v[160:163], v[128:143]
	v_exp_f32_e32 v118, v73
	v_exp_f32_e32 v116, v70
	v_add_f32_e32 v70, v103, v68
	v_add_f32_e32 v69, v213, v69
	v_exp_f32_e32 v117, v72
	v_add_f32_e32 v70, v214, v70
	s_waitcnt lgkmcnt(2)
	v_mfma_f32_32x32x16_bf16 v[80:95], v[120:123], v[160:163], v[80:95]
	v_add_f32_e32 v72, v215, v69
	v_cvt_pk_bf16_f32 v68, v103, v213
	v_add_f32_e32 v103, v216, v70
	v_add_f32_e32 v120, v217, v72
	v_exp_f32_e32 v71, v71
	v_exp_f32_e32 v119, v74
	v_exp_f32_e32 v124, v75
	v_cvt_pk_bf16_f32 v69, v214, v215
	v_cvt_pk_bf16_f32 v70, v216, v217
	ds_read_b128 v[72:75], v211 offset:18432
	ds_read_b128 v[112:115], v211 offset:23040
	s_waitcnt lgkmcnt(3)
	v_mfma_f32_32x32x16_bf16 v[128:143], v[64:67], v[164:167], v[128:143]
	v_add_f32_e32 v64, v116, v103
	v_add_f32_e32 v65, v71, v120
	v_add_f32_e32 v66, v117, v64
	v_add_f32_e32 v65, v118, v65
	v_add_f32_e32 v66, v119, v66
	v_add_f32_e32 v67, v124, v65
	s_waitcnt lgkmcnt(2)
	v_mfma_f32_32x32x16_bf16 v[80:95], v[108:111], v[164:167], v[80:95]
	v_exp_f32_e32 v121, v76
	v_exp_f32_e32 v122, v77
	v_exp_f32_e32 v123, v78
	v_exp_f32_e32 v125, v79
	v_cvt_pk_bf16_f32 v71, v116, v71
	v_cvt_pk_bf16_f32 v64, v117, v118
	v_cvt_pk_bf16_f32 v65, v119, v124
	ds_read_b128 v[76:79], v211 offset:18464
	ds_read_b128 v[108:111], v211 offset:23072
	s_waitcnt lgkmcnt(3)
	v_mfma_f32_32x32x16_bf16 v[0:15], v[72:75], v[104:107], v[0:15]
	v_add_f32_e32 v72, v121, v66
	v_add_f32_e32 v67, v122, v67
	v_add_f32_e32 v103, v123, v72
	v_add_f32_e32 v116, v125, v67
	v_cvt_pk_bf16_f32 v66, v121, v122
	v_cvt_pk_bf16_f32 v67, v123, v125
	s_waitcnt lgkmcnt(2)
	v_mfma_f32_32x32x16_bf16 v[16:31], v[112:115], v[104:107], v[16:31]
	ds_read_b128 v[72:75], v211 offset:18496
	s_waitcnt lgkmcnt(2)
	v_mfma_f32_32x32x16_bf16 v[0:15], v[76:79], v[96:99], v[0:15]
	ds_read_b128 v[76:79], v211 offset:23104
	s_waitcnt lgkmcnt(2)
	v_mfma_f32_32x32x16_bf16 v[16:31], v[108:111], v[96:99], v[16:31]
	ds_read_b128 v[96:99], v211 offset:18528
	ds_read_b128 v[104:107], v211 offset:23136
	s_waitcnt lgkmcnt(3)
	v_mfma_f32_32x32x16_bf16 v[0:15], v[72:75], v[68:71], v[0:15]
	s_waitcnt lgkmcnt(2)
	v_mfma_f32_32x32x16_bf16 v[16:31], v[76:79], v[68:71], v[16:31]
	s_waitcnt lgkmcnt(1)
	v_mfma_f32_32x32x16_bf16 v[0:15], v[96:99], v[64:67], v[0:15]
	v_add_f32_e32 v221, v103, v116
	v_cmp_lt_f32_e32 vcc, s58, v221
	v_add_f32_e32 v118, v102, v221
	s_waitcnt lgkmcnt(0)
	v_mfma_f32_32x32x16_bf16 v[16:31], v[104:107], v[64:67], v[16:31]
	ds_read_b128 v[64:67], v181
	ds_read_b128 v[112:115], v181 offset:6656
	s_cbranch_vccz .LBB0_919
	v_mov_b32_e32 v222, v221
	v_mov_b32_e32 v223, v221
	s_nop 1
	v_permlane32_swap_b32_e32 v222, v223
	v_add_f32_e32 v222, v222, v223
	v_log_f32_e32 v222, v222
	s_nop 0
	v_max_f32_e32 v33, 0, v222
	v_exp_f32_e64 v34, -v33
	v_add_f32_e32 v212, v212, v33
	v_xor_b32_e32 v32, 0x80000000, v212
	v_sub_f32_e32 v143, v143, v33
	v_pk_mul_f32 v[14:15], v[14:15], v[34:35] op_sel_hi:[1,0]
	v_pk_mul_f32 v[12:13], v[12:13], v[34:35] op_sel_hi:[1,0]
	v_pk_mul_f32 v[10:11], v[10:11], v[34:35] op_sel_hi:[1,0]
	v_pk_mul_f32 v[8:9], v[8:9], v[34:35] op_sel_hi:[1,0]
	v_pk_mul_f32 v[6:7], v[6:7], v[34:35] op_sel_hi:[1,0]
	v_pk_mul_f32 v[4:5], v[4:5], v[34:35] op_sel_hi:[1,0]
	v_pk_mul_f32 v[2:3], v[2:3], v[34:35] op_sel_hi:[1,0]
	v_pk_mul_f32 v[0:1], v[0:1], v[34:35] op_sel_hi:[1,0]
	v_pk_mul_f32 v[30:31], v[30:31], v[34:35] op_sel_hi:[1,0]
	v_pk_mul_f32 v[28:29], v[28:29], v[34:35] op_sel_hi:[1,0]
	v_pk_mul_f32 v[26:27], v[26:27], v[34:35] op_sel_hi:[1,0]
	v_pk_mul_f32 v[24:25], v[24:25], v[34:35] op_sel_hi:[1,0]
	v_pk_mul_f32 v[22:23], v[22:23], v[34:35] op_sel_hi:[1,0]
	v_pk_mul_f32 v[20:21], v[20:21], v[34:35] op_sel_hi:[1,0]
	v_pk_mul_f32 v[18:19], v[18:19], v[34:35] op_sel_hi:[1,0]
	v_pk_mul_f32 v[16:17], v[16:17], v[34:35] op_sel_hi:[1,0]
	v_sub_f32_e32 v142, v142, v33
	v_sub_f32_e32 v141, v141, v33
	v_sub_f32_e32 v140, v140, v33
	v_sub_f32_e32 v139, v139, v33
	v_sub_f32_e32 v138, v138, v33
	v_sub_f32_e32 v137, v137, v33
	v_sub_f32_e32 v136, v136, v33
	v_sub_f32_e32 v135, v135, v33
	v_sub_f32_e32 v134, v134, v33
	v_sub_f32_e32 v133, v133, v33
	v_sub_f32_e32 v132, v132, v33
	v_sub_f32_e32 v131, v131, v33
	v_sub_f32_e32 v130, v130, v33
	v_sub_f32_e32 v129, v129, v33
	v_sub_f32_e32 v128, v128, v33
	v_sub_f32_e32 v95, v95, v33
	v_sub_f32_e32 v94, v94, v33
	v_sub_f32_e32 v93, v93, v33
	v_sub_f32_e32 v92, v92, v33
	v_sub_f32_e32 v91, v91, v33
	v_sub_f32_e32 v90, v90, v33
	v_sub_f32_e32 v89, v89, v33
	v_sub_f32_e32 v88, v88, v33
	v_sub_f32_e32 v87, v87, v33
	v_sub_f32_e32 v86, v86, v33
	v_sub_f32_e32 v85, v85, v33
	v_sub_f32_e32 v84, v84, v33
	v_sub_f32_e32 v83, v83, v33
	v_sub_f32_e32 v82, v82, v33
	v_sub_f32_e32 v81, v81, v33
	v_sub_f32_e32 v80, v80, v33
	v_mul_f32_e32 v118, v118, v34
	v_mov_b32_e32 v33, v32
	v_mov_b32_e32 v34, v32
	v_mov_b32_e32 v35, v32
	v_mov_b32_e32 v36, v32
	v_mov_b32_e32 v37, v32
	v_mov_b32_e32 v38, v32
	v_mov_b32_e32 v39, v32
	v_mov_b32_e32 v40, v32
	v_mov_b32_e32 v41, v32
	v_mov_b32_e32 v42, v32
	v_mov_b32_e32 v43, v32
	v_mov_b32_e32 v44, v32
	v_mov_b32_e32 v45, v32
	v_mov_b32_e32 v46, v32
	v_mov_b32_e32 v47, v32
	v_mov_b32_e32 v48, v32
	v_mov_b32_e32 v49, v32
	v_mov_b32_e32 v50, v32
	v_mov_b32_e32 v51, v32
	v_mov_b32_e32 v52, v32
	v_mov_b32_e32 v53, v32
	v_mov_b32_e32 v54, v32
	v_mov_b32_e32 v55, v32
	v_mov_b32_e32 v56, v32
	v_mov_b32_e32 v57, v32
	v_mov_b32_e32 v58, v32
	v_mov_b32_e32 v59, v32
	v_mov_b32_e32 v60, v32
	v_mov_b32_e32 v61, v32
	v_mov_b32_e32 v62, v32
	v_mov_b32_e32 v63, v32

; __device__ __forceinline__ unsigned pk2(float lo, float hi) { return pg8::cvt_pk_bf16(lo, hi); }
; template <int LO, int HI> __device__ __forceinline__ void g_exp(f32x16& X) {
; #pragma unroll
;     for (int r = LO; r < HI; ++r) X[r] = __builtin_amdgcn_exp2f(X[r]);
; }
; template <int LO, int HI> __device__ __forceinline__ void g_sumpk(const f32x16& X, float& psa, float& psb, u32x4& pwlo, u32x4& pwhi) {
; #pragma unroll
;     for (int r = LO; r < HI; r += 2) { psa += X[r]; psb += X[r + 1]; const unsigned w = pk2(X[r], X[r + 1]); if (r < 8) pwlo[(r >> 1) & 3] = w; else pwhi[(r >> 1) & 3] = w; }
;     asm volatile("" : "+v"(psa), "+v"(psb));
; }
.LBB0_923:
	ds_read_b128 v[120:123], v181 offset:32
	ds_read_b128 v[124:127], v181 offset:6688
	s_waitcnt lgkmcnt(3)
	v_mfma_f32_32x32x16_bf16 v[96:111], v[64:67], v[144:147], v[32:47]
	v_exp_f32_e32 v119, v128
	v_exp_f32_e32 v213, v129
	v_exp_f32_e32 v214, v130
	v_exp_f32_e32 v215, v131
	v_exp_f32_e32 v132, v132
	v_exp_f32_e32 v133, v133
	s_waitcnt lgkmcnt(2)
	v_mfma_f32_32x32x16_bf16 v[64:79], v[112:115], v[144:147], v[32:47]
	ds_read_b128 v[112:115], v181 offset:64
	ds_read_b128 v[128:131], v181 offset:6720
	s_waitcnt lgkmcnt(3)
	v_mfma_f32_32x32x16_bf16 v[96:111], v[120:123], v[148:151], v[96:111]
	v_cvt_pk_bf16_f32 v120, v119, v213
	v_add_f32_e32 v119, v214, v119
	v_add_f32_e32 v122, v215, v213
	v_add_f32_e32 v119, v132, v119
	s_waitcnt lgkmcnt(2)
	v_mfma_f32_32x32x16_bf16 v[64:79], v[124:127], v[148:151], v[64:79]
	v_add_f32_e32 v123, v133, v122
	v_exp_f32_e32 v216, v134
	v_exp_f32_e32 v217, v135
	v_exp_f32_e32 v136, v136
	v_exp_f32_e32 v137, v137
	v_exp_f32_e32 v138, v138
	v_exp_f32_e32 v139, v139
	v_cvt_pk_bf16_f32 v121, v214, v215
	v_cvt_pk_bf16_f32 v122, v132, v133
	ds_read_b128 v[124:127], v181 offset:96
	ds_read_b128 v[132:135], v181 offset:6752
	s_waitcnt lgkmcnt(3)
	v_mfma_f32_32x32x16_bf16 v[96:111], v[112:115], v[152:155], v[96:111]
	v_add_f32_e32 v112, v216, v119
	v_add_f32_e32 v113, v217, v123
	v_add_f32_e32 v114, v136, v112
	v_add_f32_e32 v113, v137, v113
	v_add_f32_e32 v114, v138, v114
	v_add_f32_e32 v115, v139, v113
	s_waitcnt lgkmcnt(2)
	v_mfma_f32_32x32x16_bf16 v[64:79], v[128:131], v[152:155], v[64:79]
	v_exp_f32_e32 v140, v140
	v_exp_f32_e32 v141, v141
	v_exp_f32_e32 v142, v142
	v_exp_f32_e32 v143, v143
	v_cvt_pk_bf16_f32 v123, v216, v217
	v_cvt_pk_bf16_f32 v112, v136, v137
	v_cvt_pk_bf16_f32 v113, v138, v139
	ds_read_b128 v[128:131], v181 offset:128
	ds_read_b128 v[136:139], v181 offset:6784
	s_waitcnt lgkmcnt(3)
	v_mfma_f32_32x32x16_bf16 v[96:111], v[124:127], v[156:159], v[96:111]
	v_exp_f32_e32 v119, v80
	v_exp_f32_e32 v213, v81
	v_add_f32_e32 v80, v140, v114
	v_add_f32_e32 v81, v141, v115
	v_exp_f32_e32 v216, v84
	v_exp_f32_e32 v217, v85
	s_waitcnt lgkmcnt(2)
	v_mfma_f32_32x32x16_bf16 v[64:79], v[132:135], v[156:159], v[64:79]
	v_add_f32_e32 v84, v142, v80
	v_add_f32_e32 v85, v143, v81
	v_exp_f32_e32 v214, v82
	v_exp_f32_e32 v215, v83
	v_cvt_pk_bf16_f32 v114, v140, v141
	v_cvt_pk_bf16_f32 v115, v142, v143
	ds_read_b128 v[80:83], v181 offset:160
	ds_read_b128 v[124:127], v181 offset:6816
	s_waitcnt lgkmcnt(3)
	v_mfma_f32_32x32x16_bf16 v[96:111], v[128:131], v[160:163], v[96:111]
	v_exp_f32_e32 v132, v86
	v_add_f32_e32 v86, v119, v84
	v_add_f32_e32 v85, v213, v85
	v_exp_f32_e32 v133, v88
	v_add_f32_e32 v86, v214, v86
	v_add_f32_e32 v88, v215, v85
	s_waitcnt lgkmcnt(2)
	v_mfma_f32_32x32x16_bf16 v[64:79], v[136:139], v[160:163], v[64:79]
	v_cvt_pk_bf16_f32 v84, v119, v213
	v_add_f32_e32 v119, v216, v86
	v_add_f32_e32 v136, v217, v88
	v_exp_f32_e32 v87, v87
	v_exp_f32_e32 v134, v89
	v_exp_f32_e32 v135, v90
	v_exp_f32_e32 v140, v91
	v_cvt_pk_bf16_f32 v85, v214, v215
	v_cvt_pk_bf16_f32 v86, v216, v217
	ds_read_b128 v[88:91], v211 offset:27648
	ds_read_b128 v[128:131], v211 offset:32256
	s_waitcnt lgkmcnt(3)
	v_mfma_f32_32x32x16_bf16 v[96:111], v[80:83], v[164:167], v[96:111]
	v_add_f32_e32 v80, v132, v119
	v_add_f32_e32 v81, v87, v136
	v_add_f32_e32 v82, v133, v80
	v_add_f32_e32 v81, v134, v81
	v_add_f32_e32 v82, v135, v82
	v_add_f32_e32 v83, v140, v81
	s_waitcnt lgkmcnt(2)
	v_mfma_f32_32x32x16_bf16 v[64:79], v[124:127], v[164:167], v[64:79]
	v_exp_f32_e32 v137, v92
	v_exp_f32_e32 v138, v93
	v_exp_f32_e32 v139, v94
	v_exp_f32_e32 v141, v95
	v_cvt_pk_bf16_f32 v87, v132, v87
	v_cvt_pk_bf16_f32 v80, v133, v134
	v_cvt_pk_bf16_f32 v81, v135, v140
	ds_read_b128 v[92:95], v211 offset:27680
	ds_read_b128 v[124:127], v211 offset:32288
	s_waitcnt lgkmcnt(3)
	v_mfma_f32_32x32x16_bf16 v[0:15], v[88:91], v[120:123], v[0:15]
	v_add_f32_e32 v88, v137, v82
	v_add_f32_e32 v83, v138, v83
	v_add_f32_e32 v119, v139, v88
	v_add_f32_e32 v132, v141, v83
	v_cvt_pk_bf16_f32 v82, v137, v138
	v_cvt_pk_bf16_f32 v83, v139, v141
	s_waitcnt lgkmcnt(2)
	v_mfma_f32_32x32x16_bf16 v[16:31], v[128:131], v[120:123], v[16:31]
	ds_read_b128 v[88:91], v211 offset:27712
	s_waitcnt lgkmcnt(2)
	v_mfma_f32_32x32x16_bf16 v[0:15], v[92:95], v[112:115], v[0:15]
	ds_read_b128 v[92:95], v211 offset:32320
	s_waitcnt lgkmcnt(2)
	v_mfma_f32_32x32x16_bf16 v[16:31], v[124:127], v[112:115], v[16:31]
	ds_read_b128 v[112:115], v211 offset:27744
	ds_read_b128 v[120:123], v211 offset:32352
	s_waitcnt lgkmcnt(3)
	v_mfma_f32_32x32x16_bf16 v[0:15], v[88:91], v[84:87], v[0:15]
	s_waitcnt lgkmcnt(2)
	v_mfma_f32_32x32x16_bf16 v[16:31], v[92:95], v[84:87], v[16:31]
	s_waitcnt lgkmcnt(1)
	v_mfma_f32_32x32x16_bf16 v[0:15], v[112:115], v[80:83], v[0:15]
	v_add_f32_e32 v221, v119, v132
	v_cmp_lt_f32_e32 vcc, s58, v221
	v_add_f32_e32 v118, v118, v221
	s_waitcnt lgkmcnt(0)
	v_mfma_f32_32x32x16_bf16 v[16:31], v[120:123], v[80:83], v[16:31]
	s_waitcnt vmcnt(0)
	s_barrier
	ds_read_b128 v[80:83], v181 offset:13312
	ds_read_b128 v[112:115], v181 offset:19968
	s_cbranch_vccz .LBB0_925
	v_mov_b32_e32 v222, v221
	v_mov_b32_e32 v223, v221
	s_nop 1
	v_permlane32_swap_b32_e32 v222, v223
	v_add_f32_e32 v222, v222, v223
	v_log_f32_e32 v222, v222
	s_nop 0
	v_max_f32_e32 v33, 0, v222
	v_exp_f32_e64 v34, -v33
	v_add_f32_e32 v212, v212, v33
	v_xor_b32_e32 v32, 0x80000000, v212
	v_sub_f32_e32 v111, v111, v33
	v_pk_mul_f32 v[14:15], v[14:15], v[34:35] op_sel_hi:[1,0]
	v_pk_mul_f32 v[12:13], v[12:13], v[34:35] op_sel_hi:[1,0]
	v_pk_mul_f32 v[10:11], v[10:11], v[34:35] op_sel_hi:[1,0]
	v_pk_mul_f32 v[8:9], v[8:9], v[34:35] op_sel_hi:[1,0]
	v_pk_mul_f32 v[6:7], v[6:7], v[34:35] op_sel_hi:[1,0]
	v_pk_mul_f32 v[4:5], v[4:5], v[34:35] op_sel_hi:[1,0]
	v_pk_mul_f32 v[2:3], v[2:3], v[34:35] op_sel_hi:[1,0]
	v_pk_mul_f32 v[0:1], v[0:1], v[34:35] op_sel_hi:[1,0]
	v_pk_mul_f32 v[30:31], v[30:31], v[34:35] op_sel_hi:[1,0]
	v_pk_mul_f32 v[28:29], v[28:29], v[34:35] op_sel_hi:[1,0]
	v_pk_mul_f32 v[26:27], v[26:27], v[34:35] op_sel_hi:[1,0]
	v_pk_mul_f32 v[24:25], v[24:25], v[34:35] op_sel_hi:[1,0]
	v_pk_mul_f32 v[22:23], v[22:23], v[34:35] op_sel_hi:[1,0]
	v_pk_mul_f32 v[20:21], v[20:21], v[34:35] op_sel_hi:[1,0]
	v_pk_mul_f32 v[18:19], v[18:19], v[34:35] op_sel_hi:[1,0]
	v_pk_mul_f32 v[16:17], v[16:17], v[34:35] op_sel_hi:[1,0]
	v_sub_f32_e32 v110, v110, v33
	v_sub_f32_e32 v109, v109, v33
	v_sub_f32_e32 v108, v108, v33
	v_sub_f32_e32 v107, v107, v33
	v_sub_f32_e32 v106, v106, v33
	v_sub_f32_e32 v105, v105, v33
	v_sub_f32_e32 v104, v104, v33
	v_sub_f32_e32 v103, v103, v33
	v_sub_f32_e32 v102, v102, v33
	v_sub_f32_e32 v101, v101, v33
	v_sub_f32_e32 v100, v100, v33
	v_sub_f32_e32 v99, v99, v33
	v_sub_f32_e32 v98, v98, v33
	v_sub_f32_e32 v97, v97, v33
	v_sub_f32_e32 v96, v96, v33
	v_sub_f32_e32 v79, v79, v33
	v_sub_f32_e32 v78, v78, v33
	v_sub_f32_e32 v77, v77, v33
	v_sub_f32_e32 v76, v76, v33
	v_sub_f32_e32 v75, v75, v33
	v_sub_f32_e32 v74, v74, v33
	v_sub_f32_e32 v73, v73, v33
	v_sub_f32_e32 v72, v72, v33
	v_sub_f32_e32 v71, v71, v33
	v_sub_f32_e32 v70, v70, v33
	v_sub_f32_e32 v69, v69, v33
	v_sub_f32_e32 v68, v68, v33
	v_sub_f32_e32 v67, v67, v33
	v_sub_f32_e32 v66, v66, v33
	v_sub_f32_e32 v65, v65, v33
	v_sub_f32_e32 v64, v64, v33
	v_mul_f32_e32 v118, v118, v34
	v_mov_b32_e32 v33, v32
	v_mov_b32_e32 v34, v32
	v_mov_b32_e32 v35, v32
	v_mov_b32_e32 v36, v32
	v_mov_b32_e32 v37, v32
	v_mov_b32_e32 v38, v32
	v_mov_b32_e32 v39, v32
	v_mov_b32_e32 v40, v32
	v_mov_b32_e32 v41, v32
	v_mov_b32_e32 v42, v32
	v_mov_b32_e32 v43, v32
	v_mov_b32_e32 v44, v32
	v_mov_b32_e32 v45, v32
	v_mov_b32_e32 v46, v32
	v_mov_b32_e32 v47, v32
	v_mov_b32_e32 v48, v32
	v_mov_b32_e32 v49, v32
	v_mov_b32_e32 v50, v32
	v_mov_b32_e32 v51, v32
	v_mov_b32_e32 v52, v32
	v_mov_b32_e32 v53, v32
	v_mov_b32_e32 v54, v32
	v_mov_b32_e32 v55, v32
	v_mov_b32_e32 v56, v32
	v_mov_b32_e32 v57, v32
	v_mov_b32_e32 v58, v32
	v_mov_b32_e32 v59, v32
	v_mov_b32_e32 v60, v32
	v_mov_b32_e32 v61, v32
	v_mov_b32_e32 v62, v32
	v_mov_b32_e32 v63, v32

; __device__ __forceinline__ unsigned pk2(float lo, float hi) { return pg8::cvt_pk_bf16(lo, hi); }
; template <int LO, int HI> __device__ __forceinline__ void g_exp(f32x16& X) {
; #pragma unroll
;     for (int r = LO; r < HI; ++r) X[r] = __builtin_amdgcn_exp2f(X[r]);
; }
; template <int LO, int HI> __device__ __forceinline__ void g_sumpk(const f32x16& X, float& psa, float& psb, u32x4& pwlo, u32x4& pwhi) {
; #pragma unroll
;     for (int r = LO; r < HI; r += 2) { psa += X[r]; psb += X[r + 1]; const unsigned w = pk2(X[r], X[r + 1]); if (r < 8) pwlo[(r >> 1) & 3] = w; else pwhi[(r >> 1) & 3] = w; }
;     asm volatile("" : "+v"(psa), "+v"(psb));
; }
.LBB0_929:
	ds_read_b128 v[138:141], v181 offset:13344
	ds_read_b128 v[214:217], v181 offset:20000
	s_waitcnt lgkmcnt(3)
	v_mfma_f32_32x32x16_bf16 v[122:137], v[80:83], v[144:147], v[32:47]
	v_exp_f32_e32 v116, v96
	v_exp_f32_e32 v117, v97
	v_exp_f32_e32 v119, v98
	v_exp_f32_e32 v120, v99
	v_exp_f32_e32 v121, v100
	v_exp_f32_e32 v142, v101
	s_waitcnt lgkmcnt(2)
	v_mfma_f32_32x32x16_bf16 v[80:95], v[112:115], v[144:147], v[32:47]
	ds_read_b128 v[96:99], v181 offset:13376
	ds_read_b128 v[112:115], v181 offset:20032
	s_waitcnt lgkmcnt(3)
	v_mfma_f32_32x32x16_bf16 v[122:137], v[138:141], v[148:151], v[122:137]
	v_exp_f32_e32 v143, v102
	v_exp_f32_e32 v213, v104
	v_add_f32_e32 v104, v119, v116
	v_add_f32_e32 v102, v120, v117
	s_waitcnt lgkmcnt(2)
	v_mfma_f32_32x32x16_bf16 v[80:95], v[214:217], v[148:151], v[80:95]
	v_cvt_pk_bf16_f32 v100, v116, v117
	v_add_f32_e32 v116, v121, v104
	v_add_f32_e32 v117, v142, v102
	v_exp_f32_e32 v103, v103
	v_exp_f32_e32 v218, v105
	v_exp_f32_e32 v219, v106
	v_exp_f32_e32 v220, v107
	v_cvt_pk_bf16_f32 v101, v119, v120
	v_cvt_pk_bf16_f32 v102, v121, v142
	ds_read_b128 v[104:107], v181 offset:13408
	ds_read_b128 v[138:141], v181 offset:20064
	s_waitcnt lgkmcnt(3)
	v_mfma_f32_32x32x16_bf16 v[122:137], v[96:99], v[152:155], v[122:137]
	v_add_f32_e32 v96, v143, v116
	v_add_f32_e32 v97, v103, v117
	v_add_f32_e32 v98, v213, v96
	v_add_f32_e32 v97, v218, v97
	v_add_f32_e32 v98, v219, v98
	v_add_f32_e32 v99, v220, v97
	s_waitcnt lgkmcnt(2)
	v_mfma_f32_32x32x16_bf16 v[80:95], v[112:115], v[152:155], v[80:95]
	v_exp_f32_e32 v119, v108
	v_exp_f32_e32 v120, v109
	v_exp_f32_e32 v121, v110
	v_exp_f32_e32 v142, v111
	v_cvt_pk_bf16_f32 v103, v143, v103
	v_cvt_pk_bf16_f32 v96, v213, v218
	v_cvt_pk_bf16_f32 v97, v219, v220
	ds_read_b128 v[108:111], v181 offset:13440
	ds_read_b128 v[112:115], v181 offset:20096
	s_waitcnt lgkmcnt(3)
	v_mfma_f32_32x32x16_bf16 v[122:137], v[104:107], v[156:159], v[122:137]
	v_exp_f32_e32 v116, v64
	v_exp_f32_e32 v117, v65
	v_add_f32_e32 v64, v119, v98
	v_add_f32_e32 v65, v120, v99
	v_exp_f32_e32 v214, v68
	v_exp_f32_e32 v215, v69
	s_waitcnt lgkmcnt(2)
	v_mfma_f32_32x32x16_bf16 v[80:95], v[138:141], v[156:159], v[80:95]
	v_add_f32_e32 v68, v121, v64
	v_add_f32_e32 v69, v142, v65
	v_exp_f32_e32 v143, v66
	v_exp_f32_e32 v213, v67
	v_cvt_pk_bf16_f32 v98, v119, v120
	v_cvt_pk_bf16_f32 v99, v121, v142
	ds_read_b128 v[64:67], v181 offset:13472
	ds_read_b128 v[104:107], v181 offset:20128
	s_waitcnt lgkmcnt(3)
	v_mfma_f32_32x32x16_bf16 v[122:137], v[108:111], v[160:163], v[122:137]
	v_exp_f32_e32 v119, v70
	v_add_f32_e32 v70, v116, v68
	v_add_f32_e32 v69, v117, v69
	v_exp_f32_e32 v120, v72
	v_add_f32_e32 v70, v143, v70
	v_add_f32_e32 v72, v213, v69
	s_waitcnt lgkmcnt(2)
	v_mfma_f32_32x32x16_bf16 v[80:95], v[112:115], v[160:163], v[80:95]
	v_add_f32_e32 v112, v214, v70
	v_add_f32_e32 v113, v215, v72
	v_exp_f32_e32 v71, v71
	v_exp_f32_e32 v121, v73
	v_exp_f32_e32 v138, v74
	v_exp_f32_e32 v139, v75
	v_cvt_pk_bf16_f32 v68, v116, v117
	v_cvt_pk_bf16_f32 v69, v143, v213
	v_cvt_pk_bf16_f32 v70, v214, v215
	ds_read_b128 v[72:75], v210 offset:53248
	ds_read_b128 v[108:111], v210 offset:57856
	s_waitcnt lgkmcnt(3)
	v_mfma_f32_32x32x16_bf16 v[122:137], v[64:67], v[164:167], v[122:137]
	v_add_f32_e32 v64, v119, v112
	v_add_f32_e32 v65, v71, v113
	v_add_f32_e32 v66, v120, v64
	v_add_f32_e32 v65, v121, v65
	v_add_f32_e32 v66, v138, v66
	v_add_f32_e32 v67, v139, v65
	s_waitcnt lgkmcnt(2)
	v_mfma_f32_32x32x16_bf16 v[80:95], v[104:107], v[164:167], v[80:95]
	v_exp_f32_e32 v114, v76
	v_exp_f32_e32 v115, v77
	v_exp_f32_e32 v116, v78
	v_exp_f32_e32 v117, v79
	v_cvt_pk_bf16_f32 v71, v119, v71
	v_cvt_pk_bf16_f32 v64, v120, v121
	v_cvt_pk_bf16_f32 v65, v138, v139
	ds_read_b128 v[76:79], v210 offset:53280
	ds_read_b128 v[104:107], v210 offset:57888
	s_waitcnt lgkmcnt(3)
	v_mfma_f32_32x32x16_bf16 v[0:15], v[72:75], v[100:103], v[0:15]
	v_add_f32_e32 v72, v114, v66
	v_add_f32_e32 v67, v115, v67
	v_add_f32_e32 v112, v116, v72
	v_add_f32_e32 v113, v117, v67
	v_cvt_pk_bf16_f32 v66, v114, v115
	v_cvt_pk_bf16_f32 v67, v116, v117
	s_waitcnt lgkmcnt(2)
	v_mfma_f32_32x32x16_bf16 v[16:31], v[108:111], v[100:103], v[16:31]
	ds_read_b128 v[72:75], v210 offset:53312
	s_waitcnt lgkmcnt(2)
	v_mfma_f32_32x32x16_bf16 v[0:15], v[76:79], v[96:99], v[0:15]
	ds_read_b128 v[76:79], v210 offset:57920
	s_waitcnt lgkmcnt(2)
	v_mfma_f32_32x32x16_bf16 v[16:31], v[104:107], v[96:99], v[16:31]
	ds_read_b128 v[96:99], v210 offset:53344
	ds_read_b128 v[102:105], v210 offset:57952
	s_waitcnt lgkmcnt(3)
	v_mfma_f32_32x32x16_bf16 v[0:15], v[72:75], v[68:71], v[0:15]
	s_waitcnt lgkmcnt(2)
	v_mfma_f32_32x32x16_bf16 v[16:31], v[76:79], v[68:71], v[16:31]
	s_waitcnt lgkmcnt(1)
	v_mfma_f32_32x32x16_bf16 v[0:15], v[96:99], v[64:67], v[0:15]
	v_add_f32_e32 v221, v112, v113
	v_cmp_lt_f32_e32 vcc, s58, v221
	v_add_f32_e32 v100, v118, v221
	s_waitcnt lgkmcnt(0)
	v_mfma_f32_32x32x16_bf16 v[16:31], v[102:105], v[64:67], v[16:31]
	ds_read_b128 v[64:67], v181 offset:26624
	ds_read_b128 v[96:99], v181 offset:33280
	s_cbranch_vccz .LBB0_931
	v_mov_b32_e32 v222, v221
	v_mov_b32_e32 v223, v221
	s_nop 1
	v_permlane32_swap_b32_e32 v222, v223
	v_add_f32_e32 v222, v222, v223
	v_log_f32_e32 v222, v222
	s_nop 0
	v_max_f32_e32 v33, 0, v222
	v_exp_f32_e64 v34, -v33
	v_add_f32_e32 v212, v212, v33
	v_xor_b32_e32 v32, 0x80000000, v212
	v_sub_f32_e32 v137, v137, v33
	v_pk_mul_f32 v[14:15], v[14:15], v[34:35] op_sel_hi:[1,0]
	v_pk_mul_f32 v[12:13], v[12:13], v[34:35] op_sel_hi:[1,0]
	v_pk_mul_f32 v[10:11], v[10:11], v[34:35] op_sel_hi:[1,0]
	v_pk_mul_f32 v[8:9], v[8:9], v[34:35] op_sel_hi:[1,0]
	v_pk_mul_f32 v[6:7], v[6:7], v[34:35] op_sel_hi:[1,0]
	v_pk_mul_f32 v[4:5], v[4:5], v[34:35] op_sel_hi:[1,0]
	v_pk_mul_f32 v[2:3], v[2:3], v[34:35] op_sel_hi:[1,0]
	v_pk_mul_f32 v[0:1], v[0:1], v[34:35] op_sel_hi:[1,0]
	v_pk_mul_f32 v[30:31], v[30:31], v[34:35] op_sel_hi:[1,0]
	v_pk_mul_f32 v[28:29], v[28:29], v[34:35] op_sel_hi:[1,0]
	v_pk_mul_f32 v[26:27], v[26:27], v[34:35] op_sel_hi:[1,0]
	v_pk_mul_f32 v[24:25], v[24:25], v[34:35] op_sel_hi:[1,0]
	v_pk_mul_f32 v[22:23], v[22:23], v[34:35] op_sel_hi:[1,0]
	v_pk_mul_f32 v[20:21], v[20:21], v[34:35] op_sel_hi:[1,0]
	v_pk_mul_f32 v[18:19], v[18:19], v[34:35] op_sel_hi:[1,0]
	v_pk_mul_f32 v[16:17], v[16:17], v[34:35] op_sel_hi:[1,0]
	v_sub_f32_e32 v136, v136, v33
	v_sub_f32_e32 v135, v135, v33
	v_sub_f32_e32 v134, v134, v33
	v_sub_f32_e32 v133, v133, v33
	v_sub_f32_e32 v132, v132, v33
	v_sub_f32_e32 v131, v131, v33
	v_sub_f32_e32 v130, v130, v33
	v_sub_f32_e32 v129, v129, v33
	v_sub_f32_e32 v128, v128, v33
	v_sub_f32_e32 v127, v127, v33
	v_sub_f32_e32 v126, v126, v33
	v_sub_f32_e32 v125, v125, v33
	v_sub_f32_e32 v124, v124, v33
	v_sub_f32_e32 v123, v123, v33
	v_sub_f32_e32 v122, v122, v33
	v_sub_f32_e32 v95, v95, v33
	v_sub_f32_e32 v94, v94, v33
	v_sub_f32_e32 v93, v93, v33
	v_sub_f32_e32 v92, v92, v33
	v_sub_f32_e32 v91, v91, v33
	v_sub_f32_e32 v90, v90, v33
	v_sub_f32_e32 v89, v89, v33
	v_sub_f32_e32 v88, v88, v33
	v_sub_f32_e32 v87, v87, v33
	v_sub_f32_e32 v86, v86, v33
	v_sub_f32_e32 v85, v85, v33
	v_sub_f32_e32 v84, v84, v33
	v_sub_f32_e32 v83, v83, v33
	v_sub_f32_e32 v82, v82, v33
	v_sub_f32_e32 v81, v81, v33
	v_sub_f32_e32 v80, v80, v33
	v_mul_f32_e32 v100, v100, v34
	v_mov_b32_e32 v33, v32
	v_mov_b32_e32 v34, v32
	v_mov_b32_e32 v35, v32
	v_mov_b32_e32 v36, v32
	v_mov_b32_e32 v37, v32
	v_mov_b32_e32 v38, v32
	v_mov_b32_e32 v39, v32
	v_mov_b32_e32 v40, v32
	v_mov_b32_e32 v41, v32
	v_mov_b32_e32 v42, v32
	v_mov_b32_e32 v43, v32
	v_mov_b32_e32 v44, v32
	v_mov_b32_e32 v45, v32
	v_mov_b32_e32 v46, v32
	v_mov_b32_e32 v47, v32
	v_mov_b32_e32 v48, v32
	v_mov_b32_e32 v49, v32
	v_mov_b32_e32 v50, v32
	v_mov_b32_e32 v51, v32
	v_mov_b32_e32 v52, v32
	v_mov_b32_e32 v53, v32
	v_mov_b32_e32 v54, v32
	v_mov_b32_e32 v55, v32
	v_mov_b32_e32 v56, v32
	v_mov_b32_e32 v57, v32
	v_mov_b32_e32 v58, v32
	v_mov_b32_e32 v59, v32
	v_mov_b32_e32 v60, v32
	v_mov_b32_e32 v61, v32
	v_mov_b32_e32 v62, v32
	v_mov_b32_e32 v63, v32

; __device__ __forceinline__ unsigned pk2(float lo, float hi) { return pg8::cvt_pk_bf16(lo, hi); }
; template <int LO, int HI> __device__ __forceinline__ void g_exp(f32x16& X) {
; #pragma unroll
;     for (int r = LO; r < HI; ++r) X[r] = __builtin_amdgcn_exp2f(X[r]);
; }
; template <int LO, int HI> __device__ __forceinline__ void g_sumpk(const f32x16& X, float& psa, float& psb, u32x4& pwlo, u32x4& pwhi) {
; #pragma unroll
;     for (int r = LO; r < HI; r += 2) { psa += X[r]; psb += X[r + 1]; const unsigned w = pk2(X[r], X[r + 1]); if (r < 8) pwlo[(r >> 1) & 3] = w; else pwhi[(r >> 1) & 3] = w; }
;     asm volatile("" : "+v"(psa), "+v"(psb));
; }
.LBB0_935:
	ds_read_b128 v[102:105], v181 offset:26656
	ds_read_b128 v[138:141], v181 offset:33312
	s_waitcnt lgkmcnt(3)
	v_mfma_f32_32x32x16_bf16 v[106:121], v[64:67], v[144:147], v[32:47]
	v_exp_f32_e32 v101, v122
	v_exp_f32_e32 v142, v123
	v_exp_f32_e32 v143, v124
	v_exp_f32_e32 v202, v125
	v_exp_f32_e32 v126, v126
	v_exp_f32_e32 v127, v127
	s_waitcnt lgkmcnt(2)
	v_mfma_f32_32x32x16_bf16 v[64:79], v[96:99], v[144:147], v[32:47]
	ds_read_b128 v[96:99], v181 offset:26688
	ds_read_b128 v[122:125], v181 offset:33344
	s_waitcnt lgkmcnt(3)
	v_mfma_f32_32x32x16_bf16 v[106:121], v[102:105], v[148:151], v[106:121]
	v_cvt_pk_bf16_f32 v102, v101, v142
	v_add_f32_e32 v101, v143, v101
	v_add_f32_e32 v104, v202, v142
	v_add_f32_e32 v101, v126, v101
	s_waitcnt lgkmcnt(2)
	v_mfma_f32_32x32x16_bf16 v[64:79], v[138:141], v[148:151], v[64:79]
	v_add_f32_e32 v105, v127, v104
	v_exp_f32_e32 v203, v128
	v_exp_f32_e32 v204, v129
	v_exp_f32_e32 v205, v130
	v_exp_f32_e32 v213, v131
	v_exp_f32_e32 v214, v132
	v_exp_f32_e32 v215, v133
	v_cvt_pk_bf16_f32 v103, v143, v202
	v_cvt_pk_bf16_f32 v104, v126, v127
	ds_read_b128 v[126:129], v181 offset:26720
	ds_read_b128 v[130:133], v181 offset:33376
	s_waitcnt lgkmcnt(3)
	v_mfma_f32_32x32x16_bf16 v[106:121], v[96:99], v[152:155], v[106:121]
	v_add_f32_e32 v96, v203, v101
	v_add_f32_e32 v97, v204, v105
	v_add_f32_e32 v98, v205, v96
	v_add_f32_e32 v97, v213, v97
	v_add_f32_e32 v98, v214, v98
	v_add_f32_e32 v99, v215, v97
	s_waitcnt lgkmcnt(2)
	v_mfma_f32_32x32x16_bf16 v[64:79], v[122:125], v[152:155], v[64:79]
	v_exp_f32_e32 v138, v134
	v_exp_f32_e32 v139, v135
	v_exp_f32_e32 v140, v136
	v_exp_f32_e32 v141, v137
	v_cvt_pk_bf16_f32 v105, v203, v204
	v_cvt_pk_bf16_f32 v96, v205, v213
	v_cvt_pk_bf16_f32 v97, v214, v215
	ds_read_b128 v[122:125], v181 offset:26752
	ds_read_b128 v[134:137], v181 offset:33408
	s_waitcnt lgkmcnt(3)
	v_mfma_f32_32x32x16_bf16 v[106:121], v[126:129], v[156:159], v[106:121]
	v_exp_f32_e32 v101, v80
	v_exp_f32_e32 v142, v81
	v_add_f32_e32 v80, v138, v98
	v_add_f32_e32 v81, v139, v99
	v_exp_f32_e32 v203, v84
	v_exp_f32_e32 v204, v85
	s_waitcnt lgkmcnt(2)
	v_mfma_f32_32x32x16_bf16 v[64:79], v[130:133], v[156:159], v[64:79]
	v_add_f32_e32 v84, v140, v80
	v_add_f32_e32 v85, v141, v81
	v_exp_f32_e32 v143, v82
	v_exp_f32_e32 v202, v83
	v_cvt_pk_bf16_f32 v98, v138, v139
	v_cvt_pk_bf16_f32 v99, v140, v141
	ds_read_b128 v[80:83], v181 offset:26784
	ds_read_b128 v[126:129], v181 offset:33440
	s_waitcnt lgkmcnt(3)
	v_mfma_f32_32x32x16_bf16 v[106:121], v[122:125], v[160:163], v[106:121]
	v_exp_f32_e32 v87, v87
	v_exp_f32_e32 v130, v86
	v_add_f32_e32 v86, v101, v84
	v_add_f32_e32 v85, v142, v85
	v_exp_f32_e32 v131, v88
	v_add_f32_e32 v86, v143, v86
	s_waitcnt lgkmcnt(2)
	v_mfma_f32_32x32x16_bf16 v[64:79], v[134:137], v[160:163], v[64:79]
	v_add_f32_e32 v88, v202, v85
	v_cvt_pk_bf16_f32 v84, v101, v142
	v_add_f32_e32 v101, v203, v86
	v_add_f32_e32 v134, v204, v88
	v_exp_f32_e32 v132, v89
	v_exp_f32_e32 v133, v90
	v_exp_f32_e32 v138, v91
	v_cvt_pk_bf16_f32 v85, v143, v202
	v_cvt_pk_bf16_f32 v86, v203, v204
	ds_read_b128 v[88:91], v210 offset:62464
	ds_read_b128 v[122:125], v211 offset:13824
	s_waitcnt lgkmcnt(3)
	v_mfma_f32_32x32x16_bf16 v[106:121], v[80:83], v[164:167], v[106:121]
	v_add_f32_e32 v80, v130, v101
	v_add_f32_e32 v81, v87, v134
	v_add_f32_e32 v82, v131, v80
	v_add_f32_e32 v81, v132, v81
	v_add_f32_e32 v82, v133, v82
	v_add_f32_e32 v83, v138, v81
	s_waitcnt lgkmcnt(2)
	v_mfma_f32_32x32x16_bf16 v[64:79], v[126:129], v[164:167], v[64:79]
	v_exp_f32_e32 v135, v92
	v_exp_f32_e32 v136, v93
	v_exp_f32_e32 v137, v94
	v_exp_f32_e32 v139, v95
	v_cvt_pk_bf16_f32 v87, v130, v87
	v_cvt_pk_bf16_f32 v80, v131, v132
	v_cvt_pk_bf16_f32 v81, v133, v138
	ds_read_b128 v[92:95], v210 offset:62496
	ds_read_b128 v[126:129], v211 offset:13856
	s_waitcnt lgkmcnt(3)
	v_mfma_f32_32x32x16_bf16 v[0:15], v[88:91], v[102:105], v[0:15]
	v_add_f32_e32 v88, v135, v82
	v_add_f32_e32 v83, v136, v83
	v_add_f32_e32 v101, v137, v88
	v_add_f32_e32 v130, v139, v83
	v_cvt_pk_bf16_f32 v82, v135, v136
	v_cvt_pk_bf16_f32 v83, v137, v139
	s_waitcnt lgkmcnt(2)
	v_mfma_f32_32x32x16_bf16 v[16:31], v[122:125], v[102:105], v[16:31]
	ds_read_b128 v[88:91], v210 offset:62528
	s_waitcnt lgkmcnt(2)
	v_mfma_f32_32x32x16_bf16 v[0:15], v[92:95], v[96:99], v[0:15]
	ds_read_b128 v[92:95], v211 offset:13888
	s_waitcnt lgkmcnt(2)
	v_mfma_f32_32x32x16_bf16 v[16:31], v[126:129], v[96:99], v[16:31]
	ds_read_b128 v[96:99], v210 offset:62560
	ds_read_b128 v[102:105], v211 offset:13920
	s_waitcnt lgkmcnt(3)
	v_mfma_f32_32x32x16_bf16 v[0:15], v[88:91], v[84:87], v[0:15]
	s_waitcnt lgkmcnt(2)
	v_mfma_f32_32x32x16_bf16 v[16:31], v[92:95], v[84:87], v[16:31]
	s_waitcnt lgkmcnt(1)
	v_mfma_f32_32x32x16_bf16 v[0:15], v[96:99], v[80:83], v[0:15]
	v_add_f32_e32 v221, v101, v130
	v_cmp_lt_f32_e32 vcc, s58, v221
	v_add_f32_e32 v88, v100, v221
	s_waitcnt lgkmcnt(0)
	v_mfma_f32_32x32x16_bf16 v[16:31], v[102:105], v[80:83], v[16:31]
	s_waitcnt vmcnt(0)
	s_barrier
	ds_read_b128 v[84:87], v181 offset:39936
	ds_read_b128 v[80:83], v181 offset:46592
	s_cbranch_vccz .LBB0_937
	v_mov_b32_e32 v222, v221
	v_mov_b32_e32 v223, v221
	s_nop 1
	v_permlane32_swap_b32_e32 v222, v223
	v_add_f32_e32 v222, v222, v223
	v_log_f32_e32 v222, v222
	s_nop 0
	v_max_f32_e32 v33, 0, v222
	v_exp_f32_e64 v34, -v33
	v_add_f32_e32 v212, v212, v33
	v_xor_b32_e32 v32, 0x80000000, v212
	v_sub_f32_e32 v121, v121, v33
	v_pk_mul_f32 v[14:15], v[14:15], v[34:35] op_sel_hi:[1,0]
	v_pk_mul_f32 v[12:13], v[12:13], v[34:35] op_sel_hi:[1,0]
	v_pk_mul_f32 v[10:11], v[10:11], v[34:35] op_sel_hi:[1,0]
	v_pk_mul_f32 v[8:9], v[8:9], v[34:35] op_sel_hi:[1,0]
	v_pk_mul_f32 v[6:7], v[6:7], v[34:35] op_sel_hi:[1,0]
	v_pk_mul_f32 v[4:5], v[4:5], v[34:35] op_sel_hi:[1,0]
	v_pk_mul_f32 v[2:3], v[2:3], v[34:35] op_sel_hi:[1,0]
	v_pk_mul_f32 v[0:1], v[0:1], v[34:35] op_sel_hi:[1,0]
	v_pk_mul_f32 v[30:31], v[30:31], v[34:35] op_sel_hi:[1,0]
	v_pk_mul_f32 v[28:29], v[28:29], v[34:35] op_sel_hi:[1,0]
	v_pk_mul_f32 v[26:27], v[26:27], v[34:35] op_sel_hi:[1,0]
	v_pk_mul_f32 v[24:25], v[24:25], v[34:35] op_sel_hi:[1,0]
	v_pk_mul_f32 v[22:23], v[22:23], v[34:35] op_sel_hi:[1,0]
	v_pk_mul_f32 v[20:21], v[20:21], v[34:35] op_sel_hi:[1,0]
	v_pk_mul_f32 v[18:19], v[18:19], v[34:35] op_sel_hi:[1,0]
	v_pk_mul_f32 v[16:17], v[16:17], v[34:35] op_sel_hi:[1,0]
	v_sub_f32_e32 v120, v120, v33
	v_sub_f32_e32 v119, v119, v33
	v_sub_f32_e32 v118, v118, v33
	v_sub_f32_e32 v117, v117, v33
	v_sub_f32_e32 v116, v116, v33
	v_sub_f32_e32 v115, v115, v33
	v_sub_f32_e32 v114, v114, v33
	v_sub_f32_e32 v113, v113, v33
	v_sub_f32_e32 v112, v112, v33
	v_sub_f32_e32 v111, v111, v33
	v_sub_f32_e32 v110, v110, v33
	v_sub_f32_e32 v109, v109, v33
	v_sub_f32_e32 v108, v108, v33
	v_sub_f32_e32 v107, v107, v33
	v_sub_f32_e32 v106, v106, v33
	v_sub_f32_e32 v79, v79, v33
	v_sub_f32_e32 v78, v78, v33
	v_sub_f32_e32 v77, v77, v33
	v_sub_f32_e32 v76, v76, v33
	v_sub_f32_e32 v75, v75, v33
	v_sub_f32_e32 v74, v74, v33
	v_sub_f32_e32 v73, v73, v33
	v_sub_f32_e32 v72, v72, v33
	v_sub_f32_e32 v71, v71, v33
	v_sub_f32_e32 v70, v70, v33
	v_sub_f32_e32 v69, v69, v33
	v_sub_f32_e32 v68, v68, v33
	v_sub_f32_e32 v67, v67, v33
	v_sub_f32_e32 v66, v66, v33
	v_sub_f32_e32 v65, v65, v33
	v_sub_f32_e32 v64, v64, v33
	v_mul_f32_e32 v88, v88, v34
	v_mov_b32_e32 v33, v32
	v_mov_b32_e32 v34, v32
	v_mov_b32_e32 v35, v32
	v_mov_b32_e32 v36, v32
	v_mov_b32_e32 v37, v32
	v_mov_b32_e32 v38, v32
	v_mov_b32_e32 v39, v32
	v_mov_b32_e32 v40, v32
	v_mov_b32_e32 v41, v32
	v_mov_b32_e32 v42, v32
	v_mov_b32_e32 v43, v32
	v_mov_b32_e32 v44, v32
	v_mov_b32_e32 v45, v32
	v_mov_b32_e32 v46, v32
	v_mov_b32_e32 v47, v32
	v_mov_b32_e32 v48, v32
	v_mov_b32_e32 v49, v32
	v_mov_b32_e32 v50, v32
	v_mov_b32_e32 v51, v32
	v_mov_b32_e32 v52, v32
	v_mov_b32_e32 v53, v32
	v_mov_b32_e32 v54, v32
	v_mov_b32_e32 v55, v32
	v_mov_b32_e32 v56, v32
	v_mov_b32_e32 v57, v32
	v_mov_b32_e32 v58, v32
	v_mov_b32_e32 v59, v32
	v_mov_b32_e32 v60, v32
	v_mov_b32_e32 v61, v32
	v_mov_b32_e32 v62, v32
	v_mov_b32_e32 v63, v32

; __device__ __forceinline__ unsigned pk2(float lo, float hi) { return pg8::cvt_pk_bf16(lo, hi); }
; template <int LO, int HI> __device__ __forceinline__ void g_exp(f32x16& X) {
; #pragma unroll
;     for (int r = LO; r < HI; ++r) X[r] = __builtin_amdgcn_exp2f(X[r]);
; }
; template <int LO, int HI> __device__ __forceinline__ void g_sumpk(const f32x16& X, float& psa, float& psb, u32x4& pwlo, u32x4& pwhi) {
; #pragma unroll
;     for (int r = LO; r < HI; r += 2) { psa += X[r]; psb += X[r + 1]; const unsigned w = pk2(X[r], X[r + 1]); if (r < 8) pwlo[(r >> 1) & 3] = w; else pwhi[(r >> 1) & 3] = w; }
;     asm volatile("" : "+v"(psa), "+v"(psb));
; }
.LBB0_941:
	s_waitcnt lgkmcnt(1)
	v_mfma_f32_32x32x16_bf16 v[122:137], v[84:87], v[144:147], v[32:47]
	v_exp_f32_e32 v89, v106
	v_exp_f32_e32 v94, v107
	v_exp_f32_e32 v95, v108
	v_exp_f32_e32 v142, v109
	v_exp_f32_e32 v143, v110
	v_exp_f32_e32 v202, v111
	ds_read_b128 v[84:87], v181 offset:39968
	ds_read_b128 v[90:93], v181 offset:46624
	s_waitcnt lgkmcnt(2)
	v_mfma_f32_32x32x16_bf16 v[96:111], v[80:83], v[144:147], v[32:47]
	ds_read_b128 v[80:83], v181 offset:40000
	ds_read_b128 v[138:141], v181 offset:46656
	s_waitcnt lgkmcnt(3)
	v_mfma_f32_32x32x16_bf16 v[122:137], v[84:87], v[148:151], v[122:137]
	v_exp_f32_e32 v116, v116
	v_add_f32_e32 v87, v95, v89
	v_add_f32_e32 v86, v142, v94
	v_cvt_pk_bf16_f32 v84, v89, v94
	s_waitcnt lgkmcnt(2)
	v_mfma_f32_32x32x16_bf16 v[96:111], v[90:93], v[148:151], v[96:111]
	v_add_f32_e32 v87, v143, v87
	v_add_f32_e32 v89, v202, v86
	v_exp_f32_e32 v203, v112
	v_exp_f32_e32 v204, v113
	v_exp_f32_e32 v205, v114
	v_exp_f32_e32 v213, v115
	v_exp_f32_e32 v117, v117
	v_cvt_pk_bf16_f32 v85, v95, v142
	v_cvt_pk_bf16_f32 v86, v143, v202
	ds_read_b128 v[90:93], v181 offset:40032
	ds_read_b128 v[112:115], v181 offset:46688
	s_waitcnt lgkmcnt(3)
	v_mfma_f32_32x32x16_bf16 v[122:137], v[80:83], v[152:155], v[122:137]
	v_add_f32_e32 v80, v203, v87
	v_add_f32_e32 v81, v204, v89
	v_add_f32_e32 v82, v205, v80
	v_add_f32_e32 v81, v213, v81
	v_add_f32_e32 v82, v116, v82
	v_add_f32_e32 v83, v117, v81
	s_waitcnt lgkmcnt(2)
	v_mfma_f32_32x32x16_bf16 v[96:111], v[138:141], v[152:155], v[96:111]
	v_exp_f32_e32 v94, v118
	v_exp_f32_e32 v95, v119
	v_exp_f32_e32 v120, v120
	v_exp_f32_e32 v121, v121
	v_cvt_pk_bf16_f32 v87, v203, v204
	v_cvt_pk_bf16_f32 v80, v205, v213
	v_cvt_pk_bf16_f32 v81, v116, v117
	ds_read_b128 v[116:119], v181 offset:40064
	ds_read_b128 v[138:141], v181 offset:46720
	s_waitcnt lgkmcnt(3)
	v_mfma_f32_32x32x16_bf16 v[122:137], v[90:93], v[156:159], v[122:137]
	v_exp_f32_e32 v89, v64
	v_exp_f32_e32 v142, v65
	v_add_f32_e32 v64, v94, v82
	v_add_f32_e32 v65, v95, v83
	v_exp_f32_e32 v203, v68
	v_exp_f32_e32 v204, v69
	s_waitcnt lgkmcnt(2)
	v_mfma_f32_32x32x16_bf16 v[96:111], v[112:115], v[156:159], v[96:111]
	v_add_f32_e32 v68, v120, v64
	v_add_f32_e32 v69, v121, v65
	v_exp_f32_e32 v143, v66
	v_exp_f32_e32 v202, v67
	v_cvt_pk_bf16_f32 v82, v94, v95
	v_cvt_pk_bf16_f32 v83, v120, v121
	ds_read_b128 v[64:67], v181 offset:40096
	ds_read_b128 v[90:93], v181 offset:46752
	s_waitcnt lgkmcnt(3)
	v_mfma_f32_32x32x16_bf16 v[122:137], v[116:119], v[160:163], v[122:137]
	v_exp_f32_e32 v116, v74
	v_exp_f32_e32 v94, v70
	v_add_f32_e32 v70, v89, v68
	v_add_f32_e32 v69, v142, v69
	v_exp_f32_e32 v95, v72
	v_add_f32_e32 v70, v143, v70
	s_waitcnt lgkmcnt(2)
	v_mfma_f32_32x32x16_bf16 v[96:111], v[138:141], v[160:163], v[96:111]
	v_add_f32_e32 v72, v202, v69
	v_cvt_pk_bf16_f32 v68, v89, v142
	v_add_f32_e32 v89, v203, v70
	v_add_f32_e32 v118, v204, v72
	v_exp_f32_e32 v71, v71
	v_exp_f32_e32 v120, v73
	v_exp_f32_e32 v117, v75
	v_cvt_pk_bf16_f32 v69, v143, v202
	v_cvt_pk_bf16_f32 v70, v203, v204
	ds_read_b128 v[72:75], v211 offset:18432
	ds_read_b128 v[112:115], v211 offset:23040
	s_waitcnt lgkmcnt(3)
	v_mfma_f32_32x32x16_bf16 v[122:137], v[64:67], v[164:167], v[122:137]
	v_add_f32_e32 v64, v94, v89
	v_add_f32_e32 v65, v71, v118
	v_add_f32_e32 v66, v95, v64
	v_add_f32_e32 v65, v120, v65
	v_add_f32_e32 v66, v116, v66
	v_add_f32_e32 v67, v117, v65
	s_waitcnt lgkmcnt(2)
	v_mfma_f32_32x32x16_bf16 v[96:111], v[90:93], v[164:167], v[96:111]
	v_exp_f32_e32 v119, v76
	v_exp_f32_e32 v121, v77
	v_exp_f32_e32 v138, v78
	v_exp_f32_e32 v139, v79
	v_cvt_pk_bf16_f32 v71, v94, v71
	v_cvt_pk_bf16_f32 v64, v95, v120
	v_cvt_pk_bf16_f32 v65, v116, v117
	ds_read_b128 v[76:79], v211 offset:18464
	ds_read_b128 v[90:93], v211 offset:23072
	s_waitcnt lgkmcnt(3)
	v_mfma_f32_32x32x16_bf16 v[0:15], v[72:75], v[84:87], v[0:15]
	v_add_f32_e32 v72, v119, v66
	v_add_f32_e32 v67, v121, v67
	v_add_f32_e32 v89, v138, v72
	v_add_f32_e32 v94, v139, v67
	v_cvt_pk_bf16_f32 v66, v119, v121
	v_cvt_pk_bf16_f32 v67, v138, v139
	s_waitcnt lgkmcnt(2)
	v_mfma_f32_32x32x16_bf16 v[16:31], v[112:115], v[84:87], v[16:31]
	ds_read_b128 v[72:75], v211 offset:18496
	s_waitcnt lgkmcnt(2)
	v_mfma_f32_32x32x16_bf16 v[0:15], v[76:79], v[80:83], v[0:15]
	ds_read_b128 v[76:79], v211 offset:23104
	s_waitcnt lgkmcnt(2)
	v_mfma_f32_32x32x16_bf16 v[16:31], v[90:93], v[80:83], v[16:31]
	ds_read_b128 v[80:83], v211 offset:18528
	ds_read_b128 v[84:87], v211 offset:23136
	s_waitcnt lgkmcnt(3)
	v_mfma_f32_32x32x16_bf16 v[0:15], v[72:75], v[68:71], v[0:15]
	s_waitcnt lgkmcnt(2)
	v_mfma_f32_32x32x16_bf16 v[16:31], v[76:79], v[68:71], v[16:31]
	s_waitcnt lgkmcnt(1)
	v_mfma_f32_32x32x16_bf16 v[0:15], v[80:83], v[64:67], v[0:15]
	v_add_f32_e32 v221, v89, v94
	v_cmp_lt_f32_e32 vcc, s58, v221
	v_add_f32_e32 v116, v88, v221
	s_waitcnt lgkmcnt(0)
	v_mfma_f32_32x32x16_bf16 v[16:31], v[84:87], v[64:67], v[16:31]
	ds_read_b128 v[64:67], v181
	ds_read_b128 v[112:115], v181 offset:6656
	s_cbranch_vccz .LBB0_943
	v_mov_b32_e32 v222, v221
	v_mov_b32_e32 v223, v221
	s_nop 1
	v_permlane32_swap_b32_e32 v222, v223
	v_add_f32_e32 v222, v222, v223
	v_log_f32_e32 v222, v222
	s_nop 0
	v_max_f32_e32 v33, 0, v222
	v_exp_f32_e64 v34, -v33
	v_add_f32_e32 v212, v212, v33
	v_xor_b32_e32 v32, 0x80000000, v212
	v_sub_f32_e32 v137, v137, v33
	v_pk_mul_f32 v[14:15], v[14:15], v[34:35] op_sel_hi:[1,0]
	v_pk_mul_f32 v[12:13], v[12:13], v[34:35] op_sel_hi:[1,0]
	v_pk_mul_f32 v[10:11], v[10:11], v[34:35] op_sel_hi:[1,0]
	v_pk_mul_f32 v[8:9], v[8:9], v[34:35] op_sel_hi:[1,0]
	v_pk_mul_f32 v[6:7], v[6:7], v[34:35] op_sel_hi:[1,0]
	v_pk_mul_f32 v[4:5], v[4:5], v[34:35] op_sel_hi:[1,0]
	v_pk_mul_f32 v[2:3], v[2:3], v[34:35] op_sel_hi:[1,0]
	v_pk_mul_f32 v[0:1], v[0:1], v[34:35] op_sel_hi:[1,0]
	v_pk_mul_f32 v[30:31], v[30:31], v[34:35] op_sel_hi:[1,0]
	v_pk_mul_f32 v[28:29], v[28:29], v[34:35] op_sel_hi:[1,0]
	v_pk_mul_f32 v[26:27], v[26:27], v[34:35] op_sel_hi:[1,0]
	v_pk_mul_f32 v[24:25], v[24:25], v[34:35] op_sel_hi:[1,0]
	v_pk_mul_f32 v[22:23], v[22:23], v[34:35] op_sel_hi:[1,0]
	v_pk_mul_f32 v[20:21], v[20:21], v[34:35] op_sel_hi:[1,0]
	v_pk_mul_f32 v[18:19], v[18:19], v[34:35] op_sel_hi:[1,0]
	v_pk_mul_f32 v[16:17], v[16:17], v[34:35] op_sel_hi:[1,0]
	v_sub_f32_e32 v136, v136, v33
	v_sub_f32_e32 v135, v135, v33
	v_sub_f32_e32 v134, v134, v33
	v_sub_f32_e32 v133, v133, v33
	v_sub_f32_e32 v132, v132, v33
	v_sub_f32_e32 v131, v131, v33
	v_sub_f32_e32 v130, v130, v33
	v_sub_f32_e32 v129, v129, v33
	v_sub_f32_e32 v128, v128, v33
	v_sub_f32_e32 v127, v127, v33
	v_sub_f32_e32 v126, v126, v33
	v_sub_f32_e32 v125, v125, v33
	v_sub_f32_e32 v124, v124, v33
	v_sub_f32_e32 v123, v123, v33
	v_sub_f32_e32 v122, v122, v33
	v_sub_f32_e32 v111, v111, v33
	v_sub_f32_e32 v110, v110, v33
	v_sub_f32_e32 v109, v109, v33
	v_sub_f32_e32 v108, v108, v33
	v_sub_f32_e32 v107, v107, v33
	v_sub_f32_e32 v106, v106, v33
	v_sub_f32_e32 v105, v105, v33
	v_sub_f32_e32 v104, v104, v33
	v_sub_f32_e32 v103, v103, v33
	v_sub_f32_e32 v102, v102, v33
	v_sub_f32_e32 v101, v101, v33
	v_sub_f32_e32 v100, v100, v33
	v_sub_f32_e32 v99, v99, v33
	v_sub_f32_e32 v98, v98, v33
	v_sub_f32_e32 v97, v97, v33
	v_sub_f32_e32 v96, v96, v33
	v_mul_f32_e32 v116, v116, v34
	v_mov_b32_e32 v33, v32
	v_mov_b32_e32 v34, v32
	v_mov_b32_e32 v35, v32
	v_mov_b32_e32 v36, v32
	v_mov_b32_e32 v37, v32
	v_mov_b32_e32 v38, v32
	v_mov_b32_e32 v39, v32
	v_mov_b32_e32 v40, v32
	v_mov_b32_e32 v41, v32
	v_mov_b32_e32 v42, v32
	v_mov_b32_e32 v43, v32
	v_mov_b32_e32 v44, v32
	v_mov_b32_e32 v45, v32
	v_mov_b32_e32 v46, v32
	v_mov_b32_e32 v47, v32
	v_mov_b32_e32 v48, v32
	v_mov_b32_e32 v49, v32
	v_mov_b32_e32 v50, v32
	v_mov_b32_e32 v51, v32
	v_mov_b32_e32 v52, v32
	v_mov_b32_e32 v53, v32
	v_mov_b32_e32 v54, v32
	v_mov_b32_e32 v55, v32
	v_mov_b32_e32 v56, v32
	v_mov_b32_e32 v57, v32
	v_mov_b32_e32 v58, v32
	v_mov_b32_e32 v59, v32
	v_mov_b32_e32 v60, v32
	v_mov_b32_e32 v61, v32
	v_mov_b32_e32 v62, v32
	v_mov_b32_e32 v63, v32

; template <bool NA>
; __device__ __forceinline__ void attn_unit(LAS unsigned char* lds, const bf16_t* Q, const bf16_t* Kg, const bf16_t* Kr, const bf16_t* Vt, bf16_t* O,
;                                           int h, int seqrow0, int q0, int t0, int NT, int rows, int g0, const float* rpb_h, int wid) {
;     ...
;         for (int t = 0; t < NT; t += 8) {
;             A_STEP(sA0, sA1, tmA, sB0, sB1, tmB, t);
;             A_STEP(sB0, sB1, tmB, sA0, sA1, tmA, t + 1);
;             A_STEP(sA0, sA1, tmA, sB0, sB1, tmB, t + 2);
;             A_STEP(sB0, sB1, tmB, sA0, sA1, tmA, t + 3);
;             A_STEP(sA0, sA1, tmA, sB0, sB1, tmB, t + 4);
;             A_STEP(sB0, sB1, tmB, sA0, sA1, tmA, t + 5);
;             A_STEP(sA0, sA1, tmA, sB0, sB1, tmB, t + 6);
;             A_STEP(sB0, sB1, tmB, sA0, sA1, tmA, t + 7);
;         }
.LBB0_970:
	ds_read_b128 v[118:121], v181 offset:32
	ds_read_b128 v[138:141], v181 offset:6688
	s_waitcnt lgkmcnt(3)
	v_mfma_f32_32x32x16_bf16 v[80:95], v[64:67], v[144:147], v[32:47]
	v_exp_f32_e32 v117, v122
	v_exp_f32_e32 v142, v123
	v_exp_f32_e32 v143, v124
	v_exp_f32_e32 v202, v125
	v_exp_f32_e32 v126, v126
	v_exp_f32_e32 v127, v127
	s_waitcnt lgkmcnt(2)
	v_mfma_f32_32x32x16_bf16 v[64:79], v[112:115], v[144:147], v[32:47]
	ds_read_b128 v[112:115], v181 offset:64
	ds_read_b128 v[122:125], v181 offset:6720
	s_waitcnt lgkmcnt(3)
	v_mfma_f32_32x32x16_bf16 v[80:95], v[118:121], v[148:151], v[80:95]
	v_cvt_pk_bf16_f32 v118, v117, v142
	v_add_f32_e32 v117, v143, v117
	v_add_f32_e32 v120, v202, v142
	v_add_f32_e32 v117, v126, v117
	s_waitcnt lgkmcnt(2)
	v_mfma_f32_32x32x16_bf16 v[64:79], v[138:141], v[148:151], v[64:79]
	v_add_f32_e32 v121, v127, v120
	v_exp_f32_e32 v203, v128
	v_exp_f32_e32 v204, v129
	v_exp_f32_e32 v205, v130
	v_exp_f32_e32 v213, v131
	v_exp_f32_e32 v214, v132
	v_exp_f32_e32 v215, v133
	v_cvt_pk_bf16_f32 v119, v143, v202
	v_cvt_pk_bf16_f32 v120, v126, v127
	ds_read_b128 v[126:129], v181 offset:96
	ds_read_b128 v[130:133], v181 offset:6752
	s_waitcnt lgkmcnt(3)
	v_mfma_f32_32x32x16_bf16 v[80:95], v[112:115], v[152:155], v[80:95]
	v_add_f32_e32 v112, v203, v117
	v_add_f32_e32 v113, v204, v121
	v_add_f32_e32 v114, v205, v112
	v_add_f32_e32 v113, v213, v113
	v_add_f32_e32 v114, v214, v114
	v_add_f32_e32 v115, v215, v113
	s_waitcnt lgkmcnt(2)
	v_mfma_f32_32x32x16_bf16 v[64:79], v[122:125], v[152:155], v[64:79]
	v_exp_f32_e32 v138, v134
	v_exp_f32_e32 v139, v135
	v_exp_f32_e32 v140, v136
	v_exp_f32_e32 v141, v137
	v_cvt_pk_bf16_f32 v121, v203, v204
	v_cvt_pk_bf16_f32 v112, v205, v213
	v_cvt_pk_bf16_f32 v113, v214, v215
	ds_read_b128 v[122:125], v181 offset:128
	ds_read_b128 v[134:137], v181 offset:6784
	s_waitcnt lgkmcnt(3)
	v_mfma_f32_32x32x16_bf16 v[80:95], v[126:129], v[156:159], v[80:95]
	v_exp_f32_e32 v117, v96
	v_exp_f32_e32 v142, v97
	v_add_f32_e32 v96, v138, v114
	v_add_f32_e32 v97, v139, v115
	v_exp_f32_e32 v203, v100
	v_exp_f32_e32 v204, v101
	s_waitcnt lgkmcnt(2)
	v_mfma_f32_32x32x16_bf16 v[64:79], v[130:133], v[156:159], v[64:79]
	v_add_f32_e32 v100, v140, v96
	v_add_f32_e32 v101, v141, v97
	v_exp_f32_e32 v143, v98
	v_exp_f32_e32 v202, v99
	v_cvt_pk_bf16_f32 v114, v138, v139
	v_cvt_pk_bf16_f32 v115, v140, v141
	ds_read_b128 v[96:99], v181 offset:160
	ds_read_b128 v[126:129], v181 offset:6816
	s_waitcnt lgkmcnt(3)
	v_mfma_f32_32x32x16_bf16 v[80:95], v[122:125], v[160:163], v[80:95]
	v_exp_f32_e32 v130, v102
	v_add_f32_e32 v102, v117, v100
	v_add_f32_e32 v101, v142, v101
	v_exp_f32_e32 v131, v104
	v_add_f32_e32 v102, v143, v102
	v_add_f32_e32 v104, v202, v101
	s_waitcnt lgkmcnt(2)
	v_mfma_f32_32x32x16_bf16 v[64:79], v[134:137], v[160:163], v[64:79]
	v_cvt_pk_bf16_f32 v100, v117, v142
	v_add_f32_e32 v117, v203, v102
	v_add_f32_e32 v134, v204, v104
	v_exp_f32_e32 v103, v103
	v_exp_f32_e32 v132, v105
	v_exp_f32_e32 v133, v106
	v_exp_f32_e32 v138, v107
	v_cvt_pk_bf16_f32 v101, v143, v202
	v_cvt_pk_bf16_f32 v102, v203, v204
	ds_read_b128 v[104:107], v211 offset:27648
	ds_read_b128 v[122:125], v211 offset:32256
	s_waitcnt lgkmcnt(3)
	v_mfma_f32_32x32x16_bf16 v[80:95], v[96:99], v[164:167], v[80:95]
	v_add_f32_e32 v96, v130, v117
	v_add_f32_e32 v97, v103, v134
	v_add_f32_e32 v98, v131, v96
	v_add_f32_e32 v97, v132, v97
	v_add_f32_e32 v98, v133, v98
	v_add_f32_e32 v99, v138, v97
	s_waitcnt lgkmcnt(2)
	v_mfma_f32_32x32x16_bf16 v[64:79], v[126:129], v[164:167], v[64:79]
	v_exp_f32_e32 v135, v108
	v_exp_f32_e32 v136, v109
	v_exp_f32_e32 v137, v110
	v_exp_f32_e32 v139, v111
	v_cvt_pk_bf16_f32 v103, v130, v103
	v_cvt_pk_bf16_f32 v96, v131, v132
	v_cvt_pk_bf16_f32 v97, v133, v138
	ds_read_b128 v[108:111], v211 offset:27680
	ds_read_b128 v[126:129], v211 offset:32288
	s_waitcnt lgkmcnt(3)
	v_mfma_f32_32x32x16_bf16 v[0:15], v[104:107], v[118:121], v[0:15]
	v_add_f32_e32 v104, v135, v98
	v_add_f32_e32 v99, v136, v99
	v_add_f32_e32 v117, v137, v104
	v_add_f32_e32 v130, v139, v99
	v_cvt_pk_bf16_f32 v98, v135, v136
	v_cvt_pk_bf16_f32 v99, v137, v139
	s_waitcnt lgkmcnt(2)
	v_mfma_f32_32x32x16_bf16 v[16:31], v[122:125], v[118:121], v[16:31]
	ds_read_b128 v[104:107], v211 offset:27712
	s_waitcnt lgkmcnt(2)
	v_mfma_f32_32x32x16_bf16 v[0:15], v[108:111], v[112:115], v[0:15]
	ds_read_b128 v[108:111], v211 offset:32320
	s_waitcnt lgkmcnt(2)
	v_mfma_f32_32x32x16_bf16 v[16:31], v[126:129], v[112:115], v[16:31]
	ds_read_b128 v[112:115], v211 offset:27744
	ds_read_b128 v[118:121], v211 offset:32352
	s_waitcnt lgkmcnt(3)
	v_mfma_f32_32x32x16_bf16 v[0:15], v[104:107], v[100:103], v[0:15]
	s_waitcnt lgkmcnt(2)
	v_mfma_f32_32x32x16_bf16 v[16:31], v[108:111], v[100:103], v[16:31]
	s_waitcnt lgkmcnt(1)
	v_mfma_f32_32x32x16_bf16 v[0:15], v[112:115], v[96:99], v[0:15]
	v_add_f32_e32 v221, v117, v130
	v_cmp_lt_f32_e32 vcc, s59, v221
	v_add_f32_e32 v116, v116, v221
	s_waitcnt lgkmcnt(0)
	v_mfma_f32_32x32x16_bf16 v[16:31], v[118:121], v[96:99], v[16:31]
	s_waitcnt vmcnt(0)
	s_add_u32 s10, s10, 0x400
	s_addc_u32 s11, s11, 0
	v_lshl_add_u64 v[200:201], v[200:201], 0, v[168:169]
	s_cmpk_lt_u32 s16, 0xf8
	v_lshl_add_u64 v[196:197], v[196:197], 0, v[198:199]
	s_barrier
	s_cbranch_scc0 .LBB0_950

; __device__ __forceinline__ unsigned pk2(float lo, float hi) { return pg8::cvt_pk_bf16(lo, hi); }
; template <int LO, int HI> __device__ __forceinline__ void g_exp(f32x16& X) {
; #pragma unroll
;     for (int r = LO; r < HI; ++r) X[r] = __builtin_amdgcn_exp2f(X[r]);
; }
; template <int LO, int HI> __device__ __forceinline__ void g_sumpk(const f32x16& X, float& psa, float& psb, u32x4& pwlo, u32x4& pwhi) {
; #pragma unroll
;     for (int r = LO; r < HI; r += 2) { psa += X[r]; psb += X[r + 1]; const unsigned w = pk2(X[r], X[r + 1]); if (r < 8) pwlo[(r >> 1) & 3] = w; else pwhi[(r >> 1) & 3] = w; }
;     asm volatile("" : "+v"(psa), "+v"(psb));
; }
.LBB0_982:
	ds_read_b128 v[118:121], v181 offset:13344
	ds_read_b128 v[122:125], v181 offset:20000
	s_waitcnt lgkmcnt(3)
	v_mfma_f32_32x32x16_bf16 v[128:143], v[96:99], v[144:147], v[32:47]
	v_exp_f32_e32 v117, v80
	v_exp_f32_e32 v126, v81
	v_exp_f32_e32 v127, v82
	v_exp_f32_e32 v213, v83
	v_exp_f32_e32 v214, v84
	v_exp_f32_e32 v215, v85
	s_waitcnt lgkmcnt(2)
	v_mfma_f32_32x32x16_bf16 v[96:111], v[112:115], v[144:147], v[32:47]
	ds_read_b128 v[80:83], v181 offset:13376
	ds_read_b128 v[112:115], v181 offset:20032
	s_waitcnt lgkmcnt(3)
	v_mfma_f32_32x32x16_bf16 v[128:143], v[118:121], v[148:151], v[128:143]
	v_exp_f32_e32 v216, v86
	v_exp_f32_e32 v217, v88
	v_add_f32_e32 v88, v127, v117
	v_add_f32_e32 v86, v213, v126
	s_waitcnt lgkmcnt(2)
	v_mfma_f32_32x32x16_bf16 v[96:111], v[122:125], v[148:151], v[96:111]
	v_cvt_pk_bf16_f32 v84, v117, v126
	v_add_f32_e32 v117, v214, v88
	v_add_f32_e32 v122, v215, v86
	v_exp_f32_e32 v87, v87
	v_exp_f32_e32 v218, v89
	v_exp_f32_e32 v219, v90
	v_exp_f32_e32 v220, v91
	v_cvt_pk_bf16_f32 v85, v127, v213
	v_cvt_pk_bf16_f32 v86, v214, v215
	ds_read_b128 v[88:91], v181 offset:13408
	ds_read_b128 v[118:121], v181 offset:20064
	s_waitcnt lgkmcnt(3)
	v_mfma_f32_32x32x16_bf16 v[128:143], v[80:83], v[152:155], v[128:143]
	v_add_f32_e32 v80, v216, v117
	v_add_f32_e32 v81, v87, v122
	v_add_f32_e32 v82, v217, v80
	v_add_f32_e32 v81, v218, v81
	v_add_f32_e32 v82, v219, v82
	v_add_f32_e32 v83, v220, v81
	s_waitcnt lgkmcnt(2)
	v_mfma_f32_32x32x16_bf16 v[96:111], v[112:115], v[152:155], v[96:111]
	v_exp_f32_e32 v123, v92
	v_exp_f32_e32 v124, v93
	v_exp_f32_e32 v125, v94
	v_exp_f32_e32 v126, v95
	v_cvt_pk_bf16_f32 v87, v216, v87
	v_cvt_pk_bf16_f32 v80, v217, v218
	v_cvt_pk_bf16_f32 v81, v219, v220
	ds_read_b128 v[92:95], v181 offset:13440
	ds_read_b128 v[112:115], v181 offset:20096
	s_waitcnt lgkmcnt(3)
	v_mfma_f32_32x32x16_bf16 v[128:143], v[88:91], v[156:159], v[128:143]
	v_exp_f32_e32 v117, v64
	v_exp_f32_e32 v122, v65
	v_add_f32_e32 v64, v123, v82
	v_add_f32_e32 v65, v124, v83
	v_exp_f32_e32 v214, v68
	v_exp_f32_e32 v215, v69
	s_waitcnt lgkmcnt(2)
	v_mfma_f32_32x32x16_bf16 v[96:111], v[118:121], v[156:159], v[96:111]
	v_add_f32_e32 v68, v125, v64
	v_add_f32_e32 v69, v126, v65
	v_exp_f32_e32 v127, v66
	v_exp_f32_e32 v213, v67
	v_cvt_pk_bf16_f32 v82, v123, v124
	v_cvt_pk_bf16_f32 v83, v125, v126
	ds_read_b128 v[64:67], v181 offset:13472
	ds_read_b128 v[88:91], v181 offset:20128
	s_waitcnt lgkmcnt(3)
	v_mfma_f32_32x32x16_bf16 v[128:143], v[92:95], v[160:163], v[128:143]
	v_exp_f32_e32 v118, v70
	v_add_f32_e32 v70, v117, v68
	v_add_f32_e32 v69, v122, v69
	v_exp_f32_e32 v119, v72
	v_add_f32_e32 v70, v127, v70
	v_add_f32_e32 v72, v213, v69
	s_waitcnt lgkmcnt(2)
	v_mfma_f32_32x32x16_bf16 v[96:111], v[112:115], v[160:163], v[96:111]
	v_add_f32_e32 v112, v214, v70
	v_add_f32_e32 v113, v215, v72
	v_exp_f32_e32 v71, v71
	v_exp_f32_e32 v120, v73
	v_exp_f32_e32 v121, v74
	v_exp_f32_e32 v123, v75
	v_cvt_pk_bf16_f32 v68, v117, v122
	v_cvt_pk_bf16_f32 v69, v127, v213
	v_cvt_pk_bf16_f32 v70, v214, v215
	ds_read_b128 v[72:75], v210 offset:53248
	ds_read_b128 v[92:95], v210 offset:57856
	s_waitcnt lgkmcnt(3)
	v_mfma_f32_32x32x16_bf16 v[128:143], v[64:67], v[164:167], v[128:143]
	v_add_f32_e32 v64, v118, v112
	v_add_f32_e32 v65, v71, v113
	v_add_f32_e32 v66, v119, v64
	v_add_f32_e32 v65, v120, v65
	v_add_f32_e32 v66, v121, v66
	v_add_f32_e32 v67, v123, v65
	s_waitcnt lgkmcnt(2)
	v_mfma_f32_32x32x16_bf16 v[96:111], v[88:91], v[164:167], v[96:111]
	v_exp_f32_e32 v114, v76
	v_exp_f32_e32 v115, v77
	v_exp_f32_e32 v117, v78
	v_exp_f32_e32 v122, v79
	v_cvt_pk_bf16_f32 v71, v118, v71
	v_cvt_pk_bf16_f32 v64, v119, v120
	v_cvt_pk_bf16_f32 v65, v121, v123
	ds_read_b128 v[76:79], v210 offset:53280
	ds_read_b128 v[88:91], v210 offset:57888
	s_waitcnt lgkmcnt(3)
	v_mfma_f32_32x32x16_bf16 v[0:15], v[72:75], v[84:87], v[0:15]
	v_add_f32_e32 v72, v114, v66
	v_add_f32_e32 v67, v115, v67
	v_add_f32_e32 v112, v117, v72
	v_add_f32_e32 v113, v122, v67
	v_cvt_pk_bf16_f32 v66, v114, v115
	v_cvt_pk_bf16_f32 v67, v117, v122
	s_waitcnt lgkmcnt(2)
	v_mfma_f32_32x32x16_bf16 v[16:31], v[92:95], v[84:87], v[16:31]
	ds_read_b128 v[72:75], v210 offset:53312
	s_waitcnt lgkmcnt(2)
	v_mfma_f32_32x32x16_bf16 v[0:15], v[76:79], v[80:83], v[0:15]
	ds_read_b128 v[76:79], v210 offset:57920
	s_waitcnt lgkmcnt(2)
	v_mfma_f32_32x32x16_bf16 v[16:31], v[88:91], v[80:83], v[16:31]
	ds_read_b128 v[80:83], v210 offset:53344
	ds_read_b128 v[88:91], v210 offset:57952
	s_waitcnt lgkmcnt(3)
	v_mfma_f32_32x32x16_bf16 v[0:15], v[72:75], v[68:71], v[0:15]
	s_waitcnt lgkmcnt(2)
	v_mfma_f32_32x32x16_bf16 v[16:31], v[76:79], v[68:71], v[16:31]
	s_waitcnt lgkmcnt(1)
	v_mfma_f32_32x32x16_bf16 v[0:15], v[80:83], v[64:67], v[0:15]
	v_add_f32_e32 v221, v112, v113
	v_cmp_lt_f32_e32 vcc, s59, v221
	v_add_f32_e32 v86, v116, v221
	s_waitcnt lgkmcnt(0)
	v_mfma_f32_32x32x16_bf16 v[16:31], v[88:91], v[64:67], v[16:31]
	ds_read_b128 v[64:67], v181 offset:26624
	ds_read_b128 v[80:83], v181 offset:33280
	s_cbranch_vccz .LBB0_984
	v_mov_b32_e32 v222, v221
	v_mov_b32_e32 v223, v221
	s_nop 1
	v_permlane32_swap_b32_e32 v222, v223
	v_add_f32_e32 v222, v222, v223
	v_log_f32_e32 v222, v222
	s_nop 0
	v_max_f32_e32 v33, 0, v222
	v_exp_f32_e64 v34, -v33
	v_add_f32_e32 v212, v212, v33
	v_xor_b32_e32 v32, 0x80000000, v212
	v_sub_f32_e32 v143, v143, v33
	v_pk_mul_f32 v[14:15], v[14:15], v[34:35] op_sel_hi:[1,0]
	v_pk_mul_f32 v[12:13], v[12:13], v[34:35] op_sel_hi:[1,0]
	v_pk_mul_f32 v[10:11], v[10:11], v[34:35] op_sel_hi:[1,0]
	v_pk_mul_f32 v[8:9], v[8:9], v[34:35] op_sel_hi:[1,0]
	v_pk_mul_f32 v[6:7], v[6:7], v[34:35] op_sel_hi:[1,0]
	v_pk_mul_f32 v[4:5], v[4:5], v[34:35] op_sel_hi:[1,0]
	v_pk_mul_f32 v[2:3], v[2:3], v[34:35] op_sel_hi:[1,0]
	v_pk_mul_f32 v[0:1], v[0:1], v[34:35] op_sel_hi:[1,0]
	v_pk_mul_f32 v[30:31], v[30:31], v[34:35] op_sel_hi:[1,0]
	v_pk_mul_f32 v[28:29], v[28:29], v[34:35] op_sel_hi:[1,0]
	v_pk_mul_f32 v[26:27], v[26:27], v[34:35] op_sel_hi:[1,0]
	v_pk_mul_f32 v[24:25], v[24:25], v[34:35] op_sel_hi:[1,0]
	v_pk_mul_f32 v[22:23], v[22:23], v[34:35] op_sel_hi:[1,0]
	v_pk_mul_f32 v[20:21], v[20:21], v[34:35] op_sel_hi:[1,0]
	v_pk_mul_f32 v[18:19], v[18:19], v[34:35] op_sel_hi:[1,0]
	v_pk_mul_f32 v[16:17], v[16:17], v[34:35] op_sel_hi:[1,0]
	v_sub_f32_e32 v142, v142, v33
	v_sub_f32_e32 v141, v141, v33
	v_sub_f32_e32 v140, v140, v33
	v_sub_f32_e32 v139, v139, v33
	v_sub_f32_e32 v138, v138, v33
	v_sub_f32_e32 v137, v137, v33
	v_sub_f32_e32 v136, v136, v33
	v_sub_f32_e32 v135, v135, v33
	v_sub_f32_e32 v134, v134, v33
	v_sub_f32_e32 v133, v133, v33
	v_sub_f32_e32 v132, v132, v33
	v_sub_f32_e32 v131, v131, v33
	v_sub_f32_e32 v130, v130, v33
	v_sub_f32_e32 v129, v129, v33
	v_sub_f32_e32 v128, v128, v33
	v_sub_f32_e32 v111, v111, v33
	v_sub_f32_e32 v110, v110, v33
	v_sub_f32_e32 v109, v109, v33
	v_sub_f32_e32 v108, v108, v33
	v_sub_f32_e32 v107, v107, v33
	v_sub_f32_e32 v106, v106, v33
	v_sub_f32_e32 v105, v105, v33
	v_sub_f32_e32 v104, v104, v33
	v_sub_f32_e32 v103, v103, v33
	v_sub_f32_e32 v102, v102, v33
	v_sub_f32_e32 v101, v101, v33
	v_sub_f32_e32 v100, v100, v33
	v_sub_f32_e32 v99, v99, v33
	v_sub_f32_e32 v98, v98, v33
	v_sub_f32_e32 v97, v97, v33
	v_sub_f32_e32 v96, v96, v33
	v_mul_f32_e32 v86, v86, v34
	v_mov_b32_e32 v33, v32
	v_mov_b32_e32 v34, v32
	v_mov_b32_e32 v35, v32
	v_mov_b32_e32 v36, v32
	v_mov_b32_e32 v37, v32
	v_mov_b32_e32 v38, v32
	v_mov_b32_e32 v39, v32
	v_mov_b32_e32 v40, v32
	v_mov_b32_e32 v41, v32
	v_mov_b32_e32 v42, v32
	v_mov_b32_e32 v43, v32
	v_mov_b32_e32 v44, v32
	v_mov_b32_e32 v45, v32
	v_mov_b32_e32 v46, v32
	v_mov_b32_e32 v47, v32
	v_mov_b32_e32 v48, v32
	v_mov_b32_e32 v49, v32
	v_mov_b32_e32 v50, v32
	v_mov_b32_e32 v51, v32
	v_mov_b32_e32 v52, v32
	v_mov_b32_e32 v53, v32
	v_mov_b32_e32 v54, v32
	v_mov_b32_e32 v55, v32
	v_mov_b32_e32 v56, v32
	v_mov_b32_e32 v57, v32
	v_mov_b32_e32 v58, v32
	v_mov_b32_e32 v59, v32
	v_mov_b32_e32 v60, v32
	v_mov_b32_e32 v61, v32
	v_mov_b32_e32 v62, v32
	v_mov_b32_e32 v63, v32

; __device__ __forceinline__ unsigned pk2(float lo, float hi) { return pg8::cvt_pk_bf16(lo, hi); }
; template <int LO, int HI> __device__ __forceinline__ void g_exp(f32x16& X) {
; #pragma unroll
;     for (int r = LO; r < HI; ++r) X[r] = __builtin_amdgcn_exp2f(X[r]);
; }
; template <int LO, int HI> __device__ __forceinline__ void g_sumpk(const f32x16& X, float& psa, float& psb, u32x4& pwlo, u32x4& pwhi) {
; #pragma unroll
;     for (int r = LO; r < HI; r += 2) { psa += X[r]; psb += X[r + 1]; const unsigned w = pk2(X[r], X[r + 1]); if (r < 8) pwlo[(r >> 1) & 3] = w; else pwhi[(r >> 1) & 3] = w; }
;     asm volatile("" : "+v"(psa), "+v"(psb));
; }
.LBB0_988:
	ds_read_b128 v[88:91], v181 offset:26656
	ds_read_b128 v[92:95], v181 offset:33312
	s_waitcnt lgkmcnt(3)
	v_mfma_f32_32x32x16_bf16 v[112:127], v[64:67], v[144:147], v[32:47]
	v_exp_f32_e32 v87, v128
	v_exp_f32_e32 v213, v129
	v_exp_f32_e32 v214, v130
	v_exp_f32_e32 v215, v131
	v_exp_f32_e32 v132, v132
	v_exp_f32_e32 v133, v133
	s_waitcnt lgkmcnt(2)
	v_mfma_f32_32x32x16_bf16 v[64:79], v[80:83], v[144:147], v[32:47]
	ds_read_b128 v[80:83], v181 offset:26688
	ds_read_b128 v[128:131], v181 offset:33344
	s_waitcnt lgkmcnt(3)
	v_mfma_f32_32x32x16_bf16 v[112:127], v[88:91], v[148:151], v[112:127]
	v_cvt_pk_bf16_f32 v88, v87, v213
	v_add_f32_e32 v87, v214, v87
	v_add_f32_e32 v90, v215, v213
	v_add_f32_e32 v87, v132, v87
	s_waitcnt lgkmcnt(2)
	v_mfma_f32_32x32x16_bf16 v[64:79], v[92:95], v[148:151], v[64:79]
	v_add_f32_e32 v91, v133, v90
	v_exp_f32_e32 v216, v134
	v_exp_f32_e32 v217, v135
	v_exp_f32_e32 v136, v136
	v_exp_f32_e32 v137, v137
	v_exp_f32_e32 v138, v138
	v_exp_f32_e32 v139, v139
	v_cvt_pk_bf16_f32 v89, v214, v215
	v_cvt_pk_bf16_f32 v90, v132, v133
	ds_read_b128 v[92:95], v181 offset:26720
	ds_read_b128 v[132:135], v181 offset:33376
	s_waitcnt lgkmcnt(3)
	v_mfma_f32_32x32x16_bf16 v[112:127], v[80:83], v[152:155], v[112:127]
	v_add_f32_e32 v80, v216, v87
	v_add_f32_e32 v81, v217, v91
	v_add_f32_e32 v82, v136, v80
	v_add_f32_e32 v81, v137, v81
	v_add_f32_e32 v82, v138, v82
	v_add_f32_e32 v83, v139, v81
	s_waitcnt lgkmcnt(2)
	v_mfma_f32_32x32x16_bf16 v[64:79], v[128:131], v[152:155], v[64:79]
	v_exp_f32_e32 v140, v140
	v_exp_f32_e32 v141, v141
	v_exp_f32_e32 v142, v142
	v_exp_f32_e32 v143, v143
	v_cvt_pk_bf16_f32 v91, v216, v217
	v_cvt_pk_bf16_f32 v80, v136, v137
	v_cvt_pk_bf16_f32 v81, v138, v139
	ds_read_b128 v[128:131], v181 offset:26752
	ds_read_b128 v[136:139], v181 offset:33408
	s_waitcnt lgkmcnt(3)
	v_mfma_f32_32x32x16_bf16 v[112:127], v[92:95], v[156:159], v[112:127]
	v_exp_f32_e32 v87, v96
	v_add_f32_e32 v92, v140, v82
	v_add_f32_e32 v83, v141, v83
	v_exp_f32_e32 v216, v100
	v_exp_f32_e32 v217, v101
	v_add_f32_e32 v100, v142, v92
	s_waitcnt lgkmcnt(2)
	v_mfma_f32_32x32x16_bf16 v[64:79], v[132:135], v[156:159], v[64:79]
	v_add_f32_e32 v101, v143, v83
	v_exp_f32_e32 v213, v97
	v_exp_f32_e32 v214, v98
	v_exp_f32_e32 v215, v99
	v_cvt_pk_bf16_f32 v82, v140, v141
	v_cvt_pk_bf16_f32 v83, v142, v143
	ds_read_b128 v[92:95], v181 offset:26784
	ds_read_b128 v[96:99], v181 offset:33440
	s_waitcnt lgkmcnt(3)
	v_mfma_f32_32x32x16_bf16 v[112:127], v[128:131], v[160:163], v[112:127]
	v_exp_f32_e32 v132, v102
	v_add_f32_e32 v102, v87, v100
	v_add_f32_e32 v101, v213, v101
	v_cvt_pk_bf16_f32 v100, v87, v213
	v_add_f32_e32 v87, v214, v102
	v_add_f32_e32 v102, v215, v101
	s_waitcnt lgkmcnt(2)
	v_mfma_f32_32x32x16_bf16 v[64:79], v[136:139], v[160:163], v[64:79]
	v_add_f32_e32 v87, v216, v87
	v_add_f32_e32 v136, v217, v102
	v_exp_f32_e32 v103, v103
	v_exp_f32_e32 v133, v104
	v_exp_f32_e32 v134, v105
	v_exp_f32_e32 v135, v106
	v_exp_f32_e32 v140, v107
	v_cvt_pk_bf16_f32 v101, v214, v215
	v_cvt_pk_bf16_f32 v102, v216, v217
	ds_read_b128 v[104:107], v210 offset:62464
	ds_read_b128 v[128:131], v211 offset:13824
	s_waitcnt lgkmcnt(3)
	v_mfma_f32_32x32x16_bf16 v[112:127], v[92:95], v[164:167], v[112:127]
	v_add_f32_e32 v87, v132, v87
	v_add_f32_e32 v92, v103, v136
	v_add_f32_e32 v87, v133, v87
	v_add_f32_e32 v93, v134, v92
	v_add_f32_e32 v87, v135, v87
	v_add_f32_e32 v94, v140, v93
	s_waitcnt lgkmcnt(2)
	v_mfma_f32_32x32x16_bf16 v[64:79], v[96:99], v[164:167], v[64:79]
	v_exp_f32_e32 v137, v108
	v_exp_f32_e32 v138, v109
	v_exp_f32_e32 v139, v110
	v_exp_f32_e32 v141, v111
	v_cvt_pk_bf16_f32 v103, v132, v103
	v_cvt_pk_bf16_f32 v92, v133, v134
	v_cvt_pk_bf16_f32 v93, v135, v140
	ds_read_b128 v[96:99], v210 offset:62496
	ds_read_b128 v[108:111], v211 offset:13856
	s_waitcnt lgkmcnt(3)
	v_mfma_f32_32x32x16_bf16 v[0:15], v[104:107], v[88:91], v[0:15]
	v_add_f32_e32 v87, v137, v87
	v_add_f32_e32 v95, v138, v94
	v_add_f32_e32 v132, v139, v87
	v_add_f32_e32 v133, v141, v95
	v_cvt_pk_bf16_f32 v94, v137, v138
	v_cvt_pk_bf16_f32 v95, v139, v141
	s_waitcnt lgkmcnt(2)
	v_mfma_f32_32x32x16_bf16 v[16:31], v[128:131], v[88:91], v[16:31]
	ds_read_b128 v[88:91], v210 offset:62528
	s_waitcnt lgkmcnt(2)
	v_mfma_f32_32x32x16_bf16 v[0:15], v[96:99], v[80:83], v[0:15]
	ds_read_b128 v[96:99], v211 offset:13888
	s_waitcnt lgkmcnt(2)
	v_mfma_f32_32x32x16_bf16 v[16:31], v[108:111], v[80:83], v[16:31]
	ds_read_b128 v[80:83], v210 offset:62560
	ds_read_b128 v[104:107], v211 offset:13920
	s_waitcnt lgkmcnt(3)
	v_mfma_f32_32x32x16_bf16 v[0:15], v[88:91], v[100:103], v[0:15]
	s_waitcnt lgkmcnt(2)
	v_mfma_f32_32x32x16_bf16 v[16:31], v[96:99], v[100:103], v[16:31]
	s_waitcnt lgkmcnt(1)
	v_mfma_f32_32x32x16_bf16 v[0:15], v[80:83], v[92:95], v[0:15]
	v_add_f32_e32 v221, v132, v133
	v_cmp_lt_f32_e32 vcc, s59, v221
	v_add_f32_e32 v102, v86, v221
	s_waitcnt lgkmcnt(0)
	v_mfma_f32_32x32x16_bf16 v[16:31], v[104:107], v[92:95], v[16:31]
	s_waitcnt vmcnt(0)
	s_barrier
	ds_read_b128 v[80:83], v181 offset:39936
	ds_read_b128 v[96:99], v181 offset:46592
	s_cbranch_vccz .LBB0_990
	v_mov_b32_e32 v222, v221
	v_mov_b32_e32 v223, v221
	s_nop 1
	v_permlane32_swap_b32_e32 v222, v223
	v_add_f32_e32 v222, v222, v223
	v_log_f32_e32 v222, v222
	s_nop 0
	v_max_f32_e32 v33, 0, v222
	v_exp_f32_e64 v34, -v33
	v_add_f32_e32 v212, v212, v33
	v_xor_b32_e32 v32, 0x80000000, v212
	v_sub_f32_e32 v127, v127, v33
	v_pk_mul_f32 v[14:15], v[14:15], v[34:35] op_sel_hi:[1,0]
	v_pk_mul_f32 v[12:13], v[12:13], v[34:35] op_sel_hi:[1,0]
	v_pk_mul_f32 v[10:11], v[10:11], v[34:35] op_sel_hi:[1,0]
	v_pk_mul_f32 v[8:9], v[8:9], v[34:35] op_sel_hi:[1,0]
	v_pk_mul_f32 v[6:7], v[6:7], v[34:35] op_sel_hi:[1,0]
	v_pk_mul_f32 v[4:5], v[4:5], v[34:35] op_sel_hi:[1,0]
	v_pk_mul_f32 v[2:3], v[2:3], v[34:35] op_sel_hi:[1,0]
	v_pk_mul_f32 v[0:1], v[0:1], v[34:35] op_sel_hi:[1,0]
	v_pk_mul_f32 v[30:31], v[30:31], v[34:35] op_sel_hi:[1,0]
	v_pk_mul_f32 v[28:29], v[28:29], v[34:35] op_sel_hi:[1,0]
	v_pk_mul_f32 v[26:27], v[26:27], v[34:35] op_sel_hi:[1,0]
	v_pk_mul_f32 v[24:25], v[24:25], v[34:35] op_sel_hi:[1,0]
	v_pk_mul_f32 v[22:23], v[22:23], v[34:35] op_sel_hi:[1,0]
	v_pk_mul_f32 v[20:21], v[20:21], v[34:35] op_sel_hi:[1,0]
	v_pk_mul_f32 v[18:19], v[18:19], v[34:35] op_sel_hi:[1,0]
	v_pk_mul_f32 v[16:17], v[16:17], v[34:35] op_sel_hi:[1,0]
	v_sub_f32_e32 v126, v126, v33
	v_sub_f32_e32 v125, v125, v33
	v_sub_f32_e32 v124, v124, v33
	v_sub_f32_e32 v123, v123, v33
	v_sub_f32_e32 v122, v122, v33
	v_sub_f32_e32 v121, v121, v33
	v_sub_f32_e32 v120, v120, v33
	v_sub_f32_e32 v119, v119, v33
	v_sub_f32_e32 v118, v118, v33
	v_sub_f32_e32 v117, v117, v33
	v_sub_f32_e32 v116, v116, v33
	v_sub_f32_e32 v115, v115, v33
	v_sub_f32_e32 v114, v114, v33
	v_sub_f32_e32 v113, v113, v33
	v_sub_f32_e32 v112, v112, v33
	v_sub_f32_e32 v79, v79, v33
	v_sub_f32_e32 v78, v78, v33
	v_sub_f32_e32 v77, v77, v33
	v_sub_f32_e32 v76, v76, v33
	v_sub_f32_e32 v75, v75, v33
	v_sub_f32_e32 v74, v74, v33
	v_sub_f32_e32 v73, v73, v33
	v_sub_f32_e32 v72, v72, v33
	v_sub_f32_e32 v71, v71, v33
	v_sub_f32_e32 v70, v70, v33
	v_sub_f32_e32 v69, v69, v33
	v_sub_f32_e32 v68, v68, v33
	v_sub_f32_e32 v67, v67, v33
	v_sub_f32_e32 v66, v66, v33
	v_sub_f32_e32 v65, v65, v33
	v_sub_f32_e32 v64, v64, v33
	v_mul_f32_e32 v102, v102, v34
	v_mov_b32_e32 v33, v32
	v_mov_b32_e32 v34, v32
	v_mov_b32_e32 v35, v32
	v_mov_b32_e32 v36, v32
	v_mov_b32_e32 v37, v32
	v_mov_b32_e32 v38, v32
	v_mov_b32_e32 v39, v32
	v_mov_b32_e32 v40, v32
	v_mov_b32_e32 v41, v32
	v_mov_b32_e32 v42, v32
	v_mov_b32_e32 v43, v32
	v_mov_b32_e32 v44, v32
	v_mov_b32_e32 v45, v32
	v_mov_b32_e32 v46, v32
	v_mov_b32_e32 v47, v32
	v_mov_b32_e32 v48, v32
	v_mov_b32_e32 v49, v32
	v_mov_b32_e32 v50, v32
	v_mov_b32_e32 v51, v32
	v_mov_b32_e32 v52, v32
	v_mov_b32_e32 v53, v32
	v_mov_b32_e32 v54, v32
	v_mov_b32_e32 v55, v32
	v_mov_b32_e32 v56, v32
	v_mov_b32_e32 v57, v32
	v_mov_b32_e32 v58, v32
	v_mov_b32_e32 v59, v32
	v_mov_b32_e32 v60, v32
	v_mov_b32_e32 v61, v32
	v_mov_b32_e32 v62, v32
	v_mov_b32_e32 v63, v32

; __device__ __forceinline__ unsigned pk2(float lo, float hi) { return pg8::cvt_pk_bf16(lo, hi); }
; template <int LO, int HI> __device__ __forceinline__ void g_exp(f32x16& X) {
; #pragma unroll
;     for (int r = LO; r < HI; ++r) X[r] = __builtin_amdgcn_exp2f(X[r]);
; }
; template <int LO, int HI> __device__ __forceinline__ void g_sumpk(const f32x16& X, float& psa, float& psb, u32x4& pwlo, u32x4& pwhi) {
; #pragma unroll
;     for (int r = LO; r < HI; r += 2) { psa += X[r]; psb += X[r + 1]; const unsigned w = pk2(X[r], X[r + 1]); if (r < 8) pwlo[(r >> 1) & 3] = w; else pwhi[(r >> 1) & 3] = w; }
;     asm volatile("" : "+v"(psa), "+v"(psb));
; }
.LBB0_994:
	ds_read_b128 v[104:107], v181 offset:39968
	ds_read_b128 v[108:111], v181 offset:46624
	s_waitcnt lgkmcnt(3)
	v_mfma_f32_32x32x16_bf16 v[128:143], v[80:83], v[144:147], v[32:47]
	v_exp_f32_e32 v103, v112
	v_exp_f32_e32 v213, v113
	v_exp_f32_e32 v214, v114
	v_exp_f32_e32 v215, v115
	v_exp_f32_e32 v116, v116
	v_exp_f32_e32 v117, v117
	s_waitcnt lgkmcnt(2)
	v_mfma_f32_32x32x16_bf16 v[80:95], v[96:99], v[144:147], v[32:47]
	ds_read_b128 v[96:99], v181 offset:40000
	ds_read_b128 v[112:115], v181 offset:46656
	s_waitcnt lgkmcnt(3)
	v_mfma_f32_32x32x16_bf16 v[128:143], v[104:107], v[148:151], v[128:143]
	v_cvt_pk_bf16_f32 v104, v103, v213
	v_add_f32_e32 v103, v214, v103
	v_add_f32_e32 v106, v215, v213
	v_add_f32_e32 v103, v116, v103
	s_waitcnt lgkmcnt(2)
	v_mfma_f32_32x32x16_bf16 v[80:95], v[108:111], v[148:151], v[80:95]
	v_add_f32_e32 v107, v117, v106
	v_exp_f32_e32 v216, v118
	v_exp_f32_e32 v217, v119
	v_exp_f32_e32 v120, v120
	v_exp_f32_e32 v121, v121
	v_exp_f32_e32 v122, v122
	v_exp_f32_e32 v123, v123
	v_cvt_pk_bf16_f32 v105, v214, v215
	v_cvt_pk_bf16_f32 v106, v116, v117
	ds_read_b128 v[108:111], v181 offset:40032
	ds_read_b128 v[116:119], v181 offset:46688
	s_waitcnt lgkmcnt(3)
	v_mfma_f32_32x32x16_bf16 v[128:143], v[96:99], v[152:155], v[128:143]
	v_add_f32_e32 v96, v216, v103
	v_add_f32_e32 v97, v217, v107
	v_add_f32_e32 v98, v120, v96
	v_add_f32_e32 v97, v121, v97
	v_add_f32_e32 v98, v122, v98
	v_add_f32_e32 v99, v123, v97
	s_waitcnt lgkmcnt(2)
	v_mfma_f32_32x32x16_bf16 v[80:95], v[112:115], v[152:155], v[80:95]
	v_exp_f32_e32 v124, v124
	v_exp_f32_e32 v125, v125
	v_exp_f32_e32 v126, v126
	v_exp_f32_e32 v127, v127
	v_cvt_pk_bf16_f32 v107, v216, v217
	v_cvt_pk_bf16_f32 v96, v120, v121
	v_cvt_pk_bf16_f32 v97, v122, v123
	ds_read_b128 v[112:115], v181 offset:40064
	ds_read_b128 v[120:123], v181 offset:46720
	s_waitcnt lgkmcnt(3)
	v_mfma_f32_32x32x16_bf16 v[128:143], v[108:111], v[156:159], v[128:143]
	v_exp_f32_e32 v103, v64
	v_exp_f32_e32 v213, v65
	v_add_f32_e32 v64, v124, v98
	v_add_f32_e32 v65, v125, v99
	v_exp_f32_e32 v216, v68
	v_exp_f32_e32 v217, v69
	s_waitcnt lgkmcnt(2)
	v_mfma_f32_32x32x16_bf16 v[80:95], v[116:119], v[156:159], v[80:95]
	v_add_f32_e32 v68, v126, v64
	v_add_f32_e32 v69, v127, v65
	v_exp_f32_e32 v214, v66
	v_exp_f32_e32 v215, v67
	v_cvt_pk_bf16_f32 v98, v124, v125
	v_cvt_pk_bf16_f32 v99, v126, v127
	ds_read_b128 v[64:67], v181 offset:40096
	ds_read_b128 v[108:111], v181 offset:46752
	s_waitcnt lgkmcnt(3)
	v_mfma_f32_32x32x16_bf16 v[128:143], v[112:115], v[160:163], v[128:143]
	v_exp_f32_e32 v118, v73
	v_exp_f32_e32 v116, v70
	v_add_f32_e32 v70, v103, v68
	v_add_f32_e32 v69, v213, v69
	v_exp_f32_e32 v117, v72
	v_add_f32_e32 v70, v214, v70
	s_waitcnt lgkmcnt(2)
	v_mfma_f32_32x32x16_bf16 v[80:95], v[120:123], v[160:163], v[80:95]
	v_add_f32_e32 v72, v215, v69
	v_cvt_pk_bf16_f32 v68, v103, v213
	v_add_f32_e32 v103, v216, v70
	v_add_f32_e32 v120, v217, v72
	v_exp_f32_e32 v71, v71
	v_exp_f32_e32 v119, v74
	v_exp_f32_e32 v124, v75
	v_cvt_pk_bf16_f32 v69, v214, v215
	v_cvt_pk_bf16_f32 v70, v216, v217
	ds_read_b128 v[72:75], v211 offset:18432
	ds_read_b128 v[112:115], v211 offset:23040
	s_waitcnt lgkmcnt(3)
	v_mfma_f32_32x32x16_bf16 v[128:143], v[64:67], v[164:167], v[128:143]
	v_add_f32_e32 v64, v116, v103
	v_add_f32_e32 v65, v71, v120
	v_add_f32_e32 v66, v117, v64
	v_add_f32_e32 v65, v118, v65
	v_add_f32_e32 v66, v119, v66
	v_add_f32_e32 v67, v124, v65
	s_waitcnt lgkmcnt(2)
	v_mfma_f32_32x32x16_bf16 v[80:95], v[108:111], v[164:167], v[80:95]
	v_exp_f32_e32 v121, v76
	v_exp_f32_e32 v122, v77
	v_exp_f32_e32 v123, v78
	v_exp_f32_e32 v125, v79
	v_cvt_pk_bf16_f32 v71, v116, v71
	v_cvt_pk_bf16_f32 v64, v117, v118
	v_cvt_pk_bf16_f32 v65, v119, v124
	ds_read_b128 v[76:79], v211 offset:18464
	ds_read_b128 v[108:111], v211 offset:23072
	s_waitcnt lgkmcnt(3)
	v_mfma_f32_32x32x16_bf16 v[0:15], v[72:75], v[104:107], v[0:15]
	v_add_f32_e32 v72, v121, v66
	v_add_f32_e32 v67, v122, v67
	v_add_f32_e32 v103, v123, v72
	v_add_f32_e32 v116, v125, v67
	v_cvt_pk_bf16_f32 v66, v121, v122
	v_cvt_pk_bf16_f32 v67, v123, v125
	s_waitcnt lgkmcnt(2)
	v_mfma_f32_32x32x16_bf16 v[16:31], v[112:115], v[104:107], v[16:31]
	ds_read_b128 v[72:75], v211 offset:18496
	s_waitcnt lgkmcnt(2)
	v_mfma_f32_32x32x16_bf16 v[0:15], v[76:79], v[96:99], v[0:15]
	ds_read_b128 v[76:79], v211 offset:23104
	s_waitcnt lgkmcnt(2)
	v_mfma_f32_32x32x16_bf16 v[16:31], v[108:111], v[96:99], v[16:31]
	ds_read_b128 v[96:99], v211 offset:18528
	ds_read_b128 v[104:107], v211 offset:23136
	s_waitcnt lgkmcnt(3)
	v_mfma_f32_32x32x16_bf16 v[0:15], v[72:75], v[68:71], v[0:15]
	s_waitcnt lgkmcnt(2)
	v_mfma_f32_32x32x16_bf16 v[16:31], v[76:79], v[68:71], v[16:31]
	s_waitcnt lgkmcnt(1)
	v_mfma_f32_32x32x16_bf16 v[0:15], v[96:99], v[64:67], v[0:15]
	v_add_f32_e32 v221, v103, v116
	v_cmp_lt_f32_e32 vcc, s59, v221
	v_add_f32_e32 v118, v102, v221
	s_waitcnt lgkmcnt(0)
	v_mfma_f32_32x32x16_bf16 v[16:31], v[104:107], v[64:67], v[16:31]
	ds_read_b128 v[64:67], v181
	ds_read_b128 v[112:115], v181 offset:6656
	s_cbranch_vccz .LBB0_996
	v_mov_b32_e32 v222, v221
	v_mov_b32_e32 v223, v221
	s_nop 1
	v_permlane32_swap_b32_e32 v222, v223
	v_add_f32_e32 v222, v222, v223
	v_log_f32_e32 v222, v222
	s_nop 0
	v_max_f32_e32 v33, 0, v222
	v_exp_f32_e64 v34, -v33
	v_add_f32_e32 v212, v212, v33
	v_xor_b32_e32 v32, 0x80000000, v212
	v_sub_f32_e32 v143, v143, v33
	v_pk_mul_f32 v[14:15], v[14:15], v[34:35] op_sel_hi:[1,0]
	v_pk_mul_f32 v[12:13], v[12:13], v[34:35] op_sel_hi:[1,0]
	v_pk_mul_f32 v[10:11], v[10:11], v[34:35] op_sel_hi:[1,0]
	v_pk_mul_f32 v[8:9], v[8:9], v[34:35] op_sel_hi:[1,0]
	v_pk_mul_f32 v[6:7], v[6:7], v[34:35] op_sel_hi:[1,0]
	v_pk_mul_f32 v[4:5], v[4:5], v[34:35] op_sel_hi:[1,0]
	v_pk_mul_f32 v[2:3], v[2:3], v[34:35] op_sel_hi:[1,0]
	v_pk_mul_f32 v[0:1], v[0:1], v[34:35] op_sel_hi:[1,0]
	v_pk_mul_f32 v[30:31], v[30:31], v[34:35] op_sel_hi:[1,0]
	v_pk_mul_f32 v[28:29], v[28:29], v[34:35] op_sel_hi:[1,0]
	v_pk_mul_f32 v[26:27], v[26:27], v[34:35] op_sel_hi:[1,0]
	v_pk_mul_f32 v[24:25], v[24:25], v[34:35] op_sel_hi:[1,0]
	v_pk_mul_f32 v[22:23], v[22:23], v[34:35] op_sel_hi:[1,0]
	v_pk_mul_f32 v[20:21], v[20:21], v[34:35] op_sel_hi:[1,0]
	v_pk_mul_f32 v[18:19], v[18:19], v[34:35] op_sel_hi:[1,0]
	v_pk_mul_f32 v[16:17], v[16:17], v[34:35] op_sel_hi:[1,0]
	v_sub_f32_e32 v142, v142, v33
	v_sub_f32_e32 v141, v141, v33
	v_sub_f32_e32 v140, v140, v33
	v_sub_f32_e32 v139, v139, v33
	v_sub_f32_e32 v138, v138, v33
	v_sub_f32_e32 v137, v137, v33
	v_sub_f32_e32 v136, v136, v33
	v_sub_f32_e32 v135, v135, v33
	v_sub_f32_e32 v134, v134, v33
	v_sub_f32_e32 v133, v133, v33
	v_sub_f32_e32 v132, v132, v33
	v_sub_f32_e32 v131, v131, v33
	v_sub_f32_e32 v130, v130, v33
	v_sub_f32_e32 v129, v129, v33
	v_sub_f32_e32 v128, v128, v33
	v_sub_f32_e32 v95, v95, v33
	v_sub_f32_e32 v94, v94, v33
	v_sub_f32_e32 v93, v93, v33
	v_sub_f32_e32 v92, v92, v33
	v_sub_f32_e32 v91, v91, v33
	v_sub_f32_e32 v90, v90, v33
	v_sub_f32_e32 v89, v89, v33
	v_sub_f32_e32 v88, v88, v33
	v_sub_f32_e32 v87, v87, v33
	v_sub_f32_e32 v86, v86, v33
	v_sub_f32_e32 v85, v85, v33
	v_sub_f32_e32 v84, v84, v33
	v_sub_f32_e32 v83, v83, v33
	v_sub_f32_e32 v82, v82, v33
	v_sub_f32_e32 v81, v81, v33
	v_sub_f32_e32 v80, v80, v33
	v_mul_f32_e32 v118, v118, v34
	v_mov_b32_e32 v33, v32
	v_mov_b32_e32 v34, v32
	v_mov_b32_e32 v35, v32
	v_mov_b32_e32 v36, v32
	v_mov_b32_e32 v37, v32
	v_mov_b32_e32 v38, v32
	v_mov_b32_e32 v39, v32
	v_mov_b32_e32 v40, v32
	v_mov_b32_e32 v41, v32
	v_mov_b32_e32 v42, v32
	v_mov_b32_e32 v43, v32
	v_mov_b32_e32 v44, v32
	v_mov_b32_e32 v45, v32
	v_mov_b32_e32 v46, v32
	v_mov_b32_e32 v47, v32
	v_mov_b32_e32 v48, v32
	v_mov_b32_e32 v49, v32
	v_mov_b32_e32 v50, v32
	v_mov_b32_e32 v51, v32
	v_mov_b32_e32 v52, v32
	v_mov_b32_e32 v53, v32
	v_mov_b32_e32 v54, v32
	v_mov_b32_e32 v55, v32
	v_mov_b32_e32 v56, v32
	v_mov_b32_e32 v57, v32
	v_mov_b32_e32 v58, v32
	v_mov_b32_e32 v59, v32
	v_mov_b32_e32 v60, v32
	v_mov_b32_e32 v61, v32
	v_mov_b32_e32 v62, v32
	v_mov_b32_e32 v63, v32

; __device__ __forceinline__ unsigned pk2(float lo, float hi) { return pg8::cvt_pk_bf16(lo, hi); }
; template <int LO, int HI> __device__ __forceinline__ void g_exp(f32x16& X) {
; #pragma unroll
;     for (int r = LO; r < HI; ++r) X[r] = __builtin_amdgcn_exp2f(X[r]);
; }
; template <int LO, int HI> __device__ __forceinline__ void g_sumpk(const f32x16& X, float& psa, float& psb, u32x4& pwlo, u32x4& pwhi) {
; #pragma unroll
;     for (int r = LO; r < HI; r += 2) { psa += X[r]; psb += X[r + 1]; const unsigned w = pk2(X[r], X[r + 1]); if (r < 8) pwlo[(r >> 1) & 3] = w; else pwhi[(r >> 1) & 3] = w; }
;     asm volatile("" : "+v"(psa), "+v"(psb));
; }
.LBB0_1000:
	ds_read_b128 v[120:123], v181 offset:32
	ds_read_b128 v[124:127], v181 offset:6688
	s_waitcnt lgkmcnt(3)
	v_mfma_f32_32x32x16_bf16 v[96:111], v[64:67], v[144:147], v[32:47]
	v_exp_f32_e32 v119, v128
	v_exp_f32_e32 v213, v129
	v_exp_f32_e32 v214, v130
	v_exp_f32_e32 v215, v131
	v_exp_f32_e32 v132, v132
	v_exp_f32_e32 v133, v133
	s_waitcnt lgkmcnt(2)
	v_mfma_f32_32x32x16_bf16 v[64:79], v[112:115], v[144:147], v[32:47]
	ds_read_b128 v[112:115], v181 offset:64
	ds_read_b128 v[128:131], v181 offset:6720
	s_waitcnt lgkmcnt(3)
	v_mfma_f32_32x32x16_bf16 v[96:111], v[120:123], v[148:151], v[96:111]
	v_cvt_pk_bf16_f32 v120, v119, v213
	v_add_f32_e32 v119, v214, v119
	v_add_f32_e32 v122, v215, v213
	v_add_f32_e32 v119, v132, v119
	s_waitcnt lgkmcnt(2)
	v_mfma_f32_32x32x16_bf16 v[64:79], v[124:127], v[148:151], v[64:79]
	v_add_f32_e32 v123, v133, v122
	v_exp_f32_e32 v216, v134
	v_exp_f32_e32 v217, v135
	v_exp_f32_e32 v136, v136
	v_exp_f32_e32 v137, v137
	v_exp_f32_e32 v138, v138
	v_exp_f32_e32 v139, v139
	v_cvt_pk_bf16_f32 v121, v214, v215
	v_cvt_pk_bf16_f32 v122, v132, v133
	ds_read_b128 v[124:127], v181 offset:96
	ds_read_b128 v[132:135], v181 offset:6752
	s_waitcnt lgkmcnt(3)
	v_mfma_f32_32x32x16_bf16 v[96:111], v[112:115], v[152:155], v[96:111]
	v_add_f32_e32 v112, v216, v119
	v_add_f32_e32 v113, v217, v123
	v_add_f32_e32 v114, v136, v112
	v_add_f32_e32 v113, v137, v113
	v_add_f32_e32 v114, v138, v114
	v_add_f32_e32 v115, v139, v113
	s_waitcnt lgkmcnt(2)
	v_mfma_f32_32x32x16_bf16 v[64:79], v[128:131], v[152:155], v[64:79]
	v_exp_f32_e32 v140, v140
	v_exp_f32_e32 v141, v141
	v_exp_f32_e32 v142, v142
	v_exp_f32_e32 v143, v143
	v_cvt_pk_bf16_f32 v123, v216, v217
	v_cvt_pk_bf16_f32 v112, v136, v137
	v_cvt_pk_bf16_f32 v113, v138, v139
	ds_read_b128 v[128:131], v181 offset:128
	ds_read_b128 v[136:139], v181 offset:6784
	s_waitcnt lgkmcnt(3)
	v_mfma_f32_32x32x16_bf16 v[96:111], v[124:127], v[156:159], v[96:111]
	v_exp_f32_e32 v119, v80
	v_exp_f32_e32 v213, v81
	v_add_f32_e32 v80, v140, v114
	v_add_f32_e32 v81, v141, v115
	v_exp_f32_e32 v216, v84
	v_exp_f32_e32 v217, v85
	s_waitcnt lgkmcnt(2)
	v_mfma_f32_32x32x16_bf16 v[64:79], v[132:135], v[156:159], v[64:79]
	v_add_f32_e32 v84, v142, v80
	v_add_f32_e32 v85, v143, v81
	v_exp_f32_e32 v214, v82
	v_exp_f32_e32 v215, v83
	v_cvt_pk_bf16_f32 v114, v140, v141
	v_cvt_pk_bf16_f32 v115, v142, v143
	ds_read_b128 v[80:83], v181 offset:160
	ds_read_b128 v[124:127], v181 offset:6816
	s_waitcnt lgkmcnt(3)
	v_mfma_f32_32x32x16_bf16 v[96:111], v[128:131], v[160:163], v[96:111]
	v_exp_f32_e32 v132, v86
	v_add_f32_e32 v86, v119, v84
	v_add_f32_e32 v85, v213, v85
	v_exp_f32_e32 v133, v88
	v_add_f32_e32 v86, v214, v86
	v_add_f32_e32 v88, v215, v85
	s_waitcnt lgkmcnt(2)
	v_mfma_f32_32x32x16_bf16 v[64:79], v[136:139], v[160:163], v[64:79]
	v_cvt_pk_bf16_f32 v84, v119, v213
	v_add_f32_e32 v119, v216, v86
	v_add_f32_e32 v136, v217, v88
	v_exp_f32_e32 v87, v87
	v_exp_f32_e32 v134, v89
	v_exp_f32_e32 v135, v90
	v_exp_f32_e32 v140, v91
	v_cvt_pk_bf16_f32 v85, v214, v215
	v_cvt_pk_bf16_f32 v86, v216, v217
	ds_read_b128 v[88:91], v211 offset:27648
	ds_read_b128 v[128:131], v211 offset:32256
	s_waitcnt lgkmcnt(3)
	v_mfma_f32_32x32x16_bf16 v[96:111], v[80:83], v[164:167], v[96:111]
	v_add_f32_e32 v80, v132, v119
	v_add_f32_e32 v81, v87, v136
	v_add_f32_e32 v82, v133, v80
	v_add_f32_e32 v81, v134, v81
	v_add_f32_e32 v82, v135, v82
	v_add_f32_e32 v83, v140, v81
	s_waitcnt lgkmcnt(2)
	v_mfma_f32_32x32x16_bf16 v[64:79], v[124:127], v[164:167], v[64:79]
	v_exp_f32_e32 v137, v92
	v_exp_f32_e32 v138, v93
	v_exp_f32_e32 v139, v94
	v_exp_f32_e32 v141, v95
	v_cvt_pk_bf16_f32 v87, v132, v87
	v_cvt_pk_bf16_f32 v80, v133, v134
	v_cvt_pk_bf16_f32 v81, v135, v140
	ds_read_b128 v[92:95], v211 offset:27680
	ds_read_b128 v[124:127], v211 offset:32288
	s_waitcnt lgkmcnt(3)
	v_mfma_f32_32x32x16_bf16 v[0:15], v[88:91], v[120:123], v[0:15]
	v_add_f32_e32 v88, v137, v82
	v_add_f32_e32 v83, v138, v83
	v_add_f32_e32 v119, v139, v88
	v_add_f32_e32 v132, v141, v83
	v_cvt_pk_bf16_f32 v82, v137, v138
	v_cvt_pk_bf16_f32 v83, v139, v141
	s_waitcnt lgkmcnt(2)
	v_mfma_f32_32x32x16_bf16 v[16:31], v[128:131], v[120:123], v[16:31]
	ds_read_b128 v[88:91], v211 offset:27712
	s_waitcnt lgkmcnt(2)
	v_mfma_f32_32x32x16_bf16 v[0:15], v[92:95], v[112:115], v[0:15]
	ds_read_b128 v[92:95], v211 offset:32320
	s_waitcnt lgkmcnt(2)
	v_mfma_f32_32x32x16_bf16 v[16:31], v[124:127], v[112:115], v[16:31]
	ds_read_b128 v[112:115], v211 offset:27744
	ds_read_b128 v[120:123], v211 offset:32352
	s_waitcnt lgkmcnt(3)
	v_mfma_f32_32x32x16_bf16 v[0:15], v[88:91], v[84:87], v[0:15]
	s_waitcnt lgkmcnt(2)
	v_mfma_f32_32x32x16_bf16 v[16:31], v[92:95], v[84:87], v[16:31]
	s_waitcnt lgkmcnt(1)
	v_mfma_f32_32x32x16_bf16 v[0:15], v[112:115], v[80:83], v[0:15]
	v_add_f32_e32 v221, v119, v132
	v_cmp_lt_f32_e32 vcc, s59, v221
	v_add_f32_e32 v118, v118, v221
	s_waitcnt lgkmcnt(0)
	v_mfma_f32_32x32x16_bf16 v[16:31], v[120:123], v[80:83], v[16:31]
	s_waitcnt vmcnt(0)
	s_barrier
	ds_read_b128 v[80:83], v181 offset:13312
	ds_read_b128 v[112:115], v181 offset:19968
	s_cbranch_vccz .LBB0_1002
	v_mov_b32_e32 v222, v221
	v_mov_b32_e32 v223, v221
	s_nop 1
	v_permlane32_swap_b32_e32 v222, v223
	v_add_f32_e32 v222, v222, v223
	v_log_f32_e32 v222, v222
	s_nop 0
	v_max_f32_e32 v33, 0, v222
	v_exp_f32_e64 v34, -v33
	v_add_f32_e32 v212, v212, v33
	v_xor_b32_e32 v32, 0x80000000, v212
	v_sub_f32_e32 v111, v111, v33
	v_pk_mul_f32 v[14:15], v[14:15], v[34:35] op_sel_hi:[1,0]
	v_pk_mul_f32 v[12:13], v[12:13], v[34:35] op_sel_hi:[1,0]
	v_pk_mul_f32 v[10:11], v[10:11], v[34:35] op_sel_hi:[1,0]
	v_pk_mul_f32 v[8:9], v[8:9], v[34:35] op_sel_hi:[1,0]
	v_pk_mul_f32 v[6:7], v[6:7], v[34:35] op_sel_hi:[1,0]
	v_pk_mul_f32 v[4:5], v[4:5], v[34:35] op_sel_hi:[1,0]
	v_pk_mul_f32 v[2:3], v[2:3], v[34:35] op_sel_hi:[1,0]
	v_pk_mul_f32 v[0:1], v[0:1], v[34:35] op_sel_hi:[1,0]
	v_pk_mul_f32 v[30:31], v[30:31], v[34:35] op_sel_hi:[1,0]
	v_pk_mul_f32 v[28:29], v[28:29], v[34:35] op_sel_hi:[1,0]
	v_pk_mul_f32 v[26:27], v[26:27], v[34:35] op_sel_hi:[1,0]
	v_pk_mul_f32 v[24:25], v[24:25], v[34:35] op_sel_hi:[1,0]
	v_pk_mul_f32 v[22:23], v[22:23], v[34:35] op_sel_hi:[1,0]
	v_pk_mul_f32 v[20:21], v[20:21], v[34:35] op_sel_hi:[1,0]
	v_pk_mul_f32 v[18:19], v[18:19], v[34:35] op_sel_hi:[1,0]
	v_pk_mul_f32 v[16:17], v[16:17], v[34:35] op_sel_hi:[1,0]
	v_sub_f32_e32 v110, v110, v33
	v_sub_f32_e32 v109, v109, v33
	v_sub_f32_e32 v108, v108, v33
	v_sub_f32_e32 v107, v107, v33
	v_sub_f32_e32 v106, v106, v33
	v_sub_f32_e32 v105, v105, v33
	v_sub_f32_e32 v104, v104, v33
	v_sub_f32_e32 v103, v103, v33
	v_sub_f32_e32 v102, v102, v33
	v_sub_f32_e32 v101, v101, v33
	v_sub_f32_e32 v100, v100, v33
	v_sub_f32_e32 v99, v99, v33
	v_sub_f32_e32 v98, v98, v33
	v_sub_f32_e32 v97, v97, v33
	v_sub_f32_e32 v96, v96, v33
	v_sub_f32_e32 v79, v79, v33
	v_sub_f32_e32 v78, v78, v33
	v_sub_f32_e32 v77, v77, v33
	v_sub_f32_e32 v76, v76, v33
	v_sub_f32_e32 v75, v75, v33
	v_sub_f32_e32 v74, v74, v33
	v_sub_f32_e32 v73, v73, v33
	v_sub_f32_e32 v72, v72, v33
	v_sub_f32_e32 v71, v71, v33
	v_sub_f32_e32 v70, v70, v33
	v_sub_f32_e32 v69, v69, v33
	v_sub_f32_e32 v68, v68, v33
	v_sub_f32_e32 v67, v67, v33
	v_sub_f32_e32 v66, v66, v33
	v_sub_f32_e32 v65, v65, v33
	v_sub_f32_e32 v64, v64, v33
	v_mul_f32_e32 v118, v118, v34
	v_mov_b32_e32 v33, v32
	v_mov_b32_e32 v34, v32
	v_mov_b32_e32 v35, v32
	v_mov_b32_e32 v36, v32
	v_mov_b32_e32 v37, v32
	v_mov_b32_e32 v38, v32
	v_mov_b32_e32 v39, v32
	v_mov_b32_e32 v40, v32
	v_mov_b32_e32 v41, v32
	v_mov_b32_e32 v42, v32
	v_mov_b32_e32 v43, v32
	v_mov_b32_e32 v44, v32
	v_mov_b32_e32 v45, v32
	v_mov_b32_e32 v46, v32
	v_mov_b32_e32 v47, v32
	v_mov_b32_e32 v48, v32
	v_mov_b32_e32 v49, v32
	v_mov_b32_e32 v50, v32
	v_mov_b32_e32 v51, v32
	v_mov_b32_e32 v52, v32
	v_mov_b32_e32 v53, v32
	v_mov_b32_e32 v54, v32
	v_mov_b32_e32 v55, v32
	v_mov_b32_e32 v56, v32
	v_mov_b32_e32 v57, v32
	v_mov_b32_e32 v58, v32
	v_mov_b32_e32 v59, v32
	v_mov_b32_e32 v60, v32
	v_mov_b32_e32 v61, v32
	v_mov_b32_e32 v62, v32
	v_mov_b32_e32 v63, v32

; __device__ __forceinline__ unsigned pk2(float lo, float hi) { return pg8::cvt_pk_bf16(lo, hi); }
; template <int LO, int HI> __device__ __forceinline__ void g_exp(f32x16& X) {
; #pragma unroll
;     for (int r = LO; r < HI; ++r) X[r] = __builtin_amdgcn_exp2f(X[r]);
; }
; template <int LO, int HI> __device__ __forceinline__ void g_sumpk(const f32x16& X, float& psa, float& psb, u32x4& pwlo, u32x4& pwhi) {
; #pragma unroll
;     for (int r = LO; r < HI; r += 2) { psa += X[r]; psb += X[r + 1]; const unsigned w = pk2(X[r], X[r + 1]); if (r < 8) pwlo[(r >> 1) & 3] = w; else pwhi[(r >> 1) & 3] = w; }
;     asm volatile("" : "+v"(psa), "+v"(psb));
; }
.LBB0_1006:
	ds_read_b128 v[138:141], v181 offset:13344
	ds_read_b128 v[214:217], v181 offset:20000
	s_waitcnt lgkmcnt(3)
	v_mfma_f32_32x32x16_bf16 v[122:137], v[80:83], v[144:147], v[32:47]
	v_exp_f32_e32 v116, v96
	v_exp_f32_e32 v117, v97
	v_exp_f32_e32 v119, v98
	v_exp_f32_e32 v120, v99
	v_exp_f32_e32 v121, v100
	v_exp_f32_e32 v142, v101
	s_waitcnt lgkmcnt(2)
	v_mfma_f32_32x32x16_bf16 v[80:95], v[112:115], v[144:147], v[32:47]
	ds_read_b128 v[96:99], v181 offset:13376
	ds_read_b128 v[112:115], v181 offset:20032
	s_waitcnt lgkmcnt(3)
	v_mfma_f32_32x32x16_bf16 v[122:137], v[138:141], v[148:151], v[122:137]
	v_exp_f32_e32 v143, v102
	v_exp_f32_e32 v213, v104
	v_add_f32_e32 v104, v119, v116
	v_add_f32_e32 v102, v120, v117
	s_waitcnt lgkmcnt(2)
	v_mfma_f32_32x32x16_bf16 v[80:95], v[214:217], v[148:151], v[80:95]
	v_cvt_pk_bf16_f32 v100, v116, v117
	v_add_f32_e32 v116, v121, v104
	v_add_f32_e32 v117, v142, v102
	v_exp_f32_e32 v103, v103
	v_exp_f32_e32 v218, v105
	v_exp_f32_e32 v219, v106
	v_exp_f32_e32 v220, v107
	v_cvt_pk_bf16_f32 v101, v119, v120
	v_cvt_pk_bf16_f32 v102, v121, v142
	ds_read_b128 v[104:107], v181 offset:13408
	ds_read_b128 v[138:141], v181 offset:20064
	s_waitcnt lgkmcnt(3)
	v_mfma_f32_32x32x16_bf16 v[122:137], v[96:99], v[152:155], v[122:137]
	v_add_f32_e32 v96, v143, v116
	v_add_f32_e32 v97, v103, v117
	v_add_f32_e32 v98, v213, v96
	v_add_f32_e32 v97, v218, v97
	v_add_f32_e32 v98, v219, v98
	v_add_f32_e32 v99, v220, v97
	s_waitcnt lgkmcnt(2)
	v_mfma_f32_32x32x16_bf16 v[80:95], v[112:115], v[152:155], v[80:95]
	v_exp_f32_e32 v119, v108
	v_exp_f32_e32 v120, v109
	v_exp_f32_e32 v121, v110
	v_exp_f32_e32 v142, v111
	v_cvt_pk_bf16_f32 v103, v143, v103
	v_cvt_pk_bf16_f32 v96, v213, v218
	v_cvt_pk_bf16_f32 v97, v219, v220
	ds_read_b128 v[108:111], v181 offset:13440
	ds_read_b128 v[112:115], v181 offset:20096
	s_waitcnt lgkmcnt(3)
	v_mfma_f32_32x32x16_bf16 v[122:137], v[104:107], v[156:159], v[122:137]
	v_exp_f32_e32 v116, v64
	v_exp_f32_e32 v117, v65
	v_add_f32_e32 v64, v119, v98
	v_add_f32_e32 v65, v120, v99
	v_exp_f32_e32 v214, v68
	v_exp_f32_e32 v215, v69
	s_waitcnt lgkmcnt(2)
	v_mfma_f32_32x32x16_bf16 v[80:95], v[138:141], v[156:159], v[80:95]
	v_add_f32_e32 v68, v121, v64
	v_add_f32_e32 v69, v142, v65
	v_exp_f32_e32 v143, v66
	v_exp_f32_e32 v213, v67
	v_cvt_pk_bf16_f32 v98, v119, v120
	v_cvt_pk_bf16_f32 v99, v121, v142
	ds_read_b128 v[64:67], v181 offset:13472
	ds_read_b128 v[104:107], v181 offset:20128
	s_waitcnt lgkmcnt(3)
	v_mfma_f32_32x32x16_bf16 v[122:137], v[108:111], v[160:163], v[122:137]
	v_exp_f32_e32 v119, v70
	v_add_f32_e32 v70, v116, v68
	v_add_f32_e32 v69, v117, v69
	v_exp_f32_e32 v120, v72
	v_add_f32_e32 v70, v143, v70
	v_add_f32_e32 v72, v213, v69
	s_waitcnt lgkmcnt(2)
	v_mfma_f32_32x32x16_bf16 v[80:95], v[112:115], v[160:163], v[80:95]
	v_add_f32_e32 v112, v214, v70
	v_add_f32_e32 v113, v215, v72
	v_exp_f32_e32 v71, v71
	v_exp_f32_e32 v121, v73
	v_exp_f32_e32 v138, v74
	v_exp_f32_e32 v139, v75
	v_cvt_pk_bf16_f32 v68, v116, v117
	v_cvt_pk_bf16_f32 v69, v143, v213
	v_cvt_pk_bf16_f32 v70, v214, v215
	ds_read_b128 v[72:75], v210 offset:53248
	ds_read_b128 v[108:111], v210 offset:57856
	s_waitcnt lgkmcnt(3)
	v_mfma_f32_32x32x16_bf16 v[122:137], v[64:67], v[164:167], v[122:137]
	v_add_f32_e32 v64, v119, v112
	v_add_f32_e32 v65, v71, v113
	v_add_f32_e32 v66, v120, v64
	v_add_f32_e32 v65, v121, v65
	v_add_f32_e32 v66, v138, v66
	v_add_f32_e32 v67, v139, v65
	s_waitcnt lgkmcnt(2)
	v_mfma_f32_32x32x16_bf16 v[80:95], v[104:107], v[164:167], v[80:95]
	v_exp_f32_e32 v114, v76
	v_exp_f32_e32 v115, v77
	v_exp_f32_e32 v116, v78
	v_exp_f32_e32 v117, v79
	v_cvt_pk_bf16_f32 v71, v119, v71
	v_cvt_pk_bf16_f32 v64, v120, v121
	v_cvt_pk_bf16_f32 v65, v138, v139
	ds_read_b128 v[76:79], v210 offset:53280
	ds_read_b128 v[104:107], v210 offset:57888
	s_waitcnt lgkmcnt(3)
	v_mfma_f32_32x32x16_bf16 v[0:15], v[72:75], v[100:103], v[0:15]
	v_add_f32_e32 v72, v114, v66
	v_add_f32_e32 v67, v115, v67
	v_add_f32_e32 v112, v116, v72
	v_add_f32_e32 v113, v117, v67
	v_cvt_pk_bf16_f32 v66, v114, v115
	v_cvt_pk_bf16_f32 v67, v116, v117
	s_waitcnt lgkmcnt(2)
	v_mfma_f32_32x32x16_bf16 v[16:31], v[108:111], v[100:103], v[16:31]
	ds_read_b128 v[72:75], v210 offset:53312
	s_waitcnt lgkmcnt(2)
	v_mfma_f32_32x32x16_bf16 v[0:15], v[76:79], v[96:99], v[0:15]
	ds_read_b128 v[76:79], v210 offset:57920
	s_waitcnt lgkmcnt(2)
	v_mfma_f32_32x32x16_bf16 v[16:31], v[104:107], v[96:99], v[16:31]
	ds_read_b128 v[96:99], v210 offset:53344
	ds_read_b128 v[102:105], v210 offset:57952
	s_waitcnt lgkmcnt(3)
	v_mfma_f32_32x32x16_bf16 v[0:15], v[72:75], v[68:71], v[0:15]
	s_waitcnt lgkmcnt(2)
	v_mfma_f32_32x32x16_bf16 v[16:31], v[76:79], v[68:71], v[16:31]
	s_waitcnt lgkmcnt(1)
	v_mfma_f32_32x32x16_bf16 v[0:15], v[96:99], v[64:67], v[0:15]
	v_add_f32_e32 v221, v112, v113
	v_cmp_lt_f32_e32 vcc, s59, v221
	v_add_f32_e32 v100, v118, v221
	s_waitcnt lgkmcnt(0)
	v_mfma_f32_32x32x16_bf16 v[16:31], v[102:105], v[64:67], v[16:31]
	ds_read_b128 v[64:67], v181 offset:26624
	ds_read_b128 v[96:99], v181 offset:33280
	s_cbranch_vccz .LBB0_1008
	v_mov_b32_e32 v222, v221
	v_mov_b32_e32 v223, v221
	s_nop 1
	v_permlane32_swap_b32_e32 v222, v223
	v_add_f32_e32 v222, v222, v223
	v_log_f32_e32 v222, v222
	s_nop 0
	v_max_f32_e32 v33, 0, v222
	v_exp_f32_e64 v34, -v33
	v_add_f32_e32 v212, v212, v33
	v_xor_b32_e32 v32, 0x80000000, v212
	v_sub_f32_e32 v137, v137, v33
	v_pk_mul_f32 v[14:15], v[14:15], v[34:35] op_sel_hi:[1,0]
	v_pk_mul_f32 v[12:13], v[12:13], v[34:35] op_sel_hi:[1,0]
	v_pk_mul_f32 v[10:11], v[10:11], v[34:35] op_sel_hi:[1,0]
	v_pk_mul_f32 v[8:9], v[8:9], v[34:35] op_sel_hi:[1,0]
	v_pk_mul_f32 v[6:7], v[6:7], v[34:35] op_sel_hi:[1,0]
	v_pk_mul_f32 v[4:5], v[4:5], v[34:35] op_sel_hi:[1,0]
	v_pk_mul_f32 v[2:3], v[2:3], v[34:35] op_sel_hi:[1,0]
	v_pk_mul_f32 v[0:1], v[0:1], v[34:35] op_sel_hi:[1,0]
	v_pk_mul_f32 v[30:31], v[30:31], v[34:35] op_sel_hi:[1,0]
	v_pk_mul_f32 v[28:29], v[28:29], v[34:35] op_sel_hi:[1,0]
	v_pk_mul_f32 v[26:27], v[26:27], v[34:35] op_sel_hi:[1,0]
	v_pk_mul_f32 v[24:25], v[24:25], v[34:35] op_sel_hi:[1,0]
	v_pk_mul_f32 v[22:23], v[22:23], v[34:35] op_sel_hi:[1,0]
	v_pk_mul_f32 v[20:21], v[20:21], v[34:35] op_sel_hi:[1,0]
	v_pk_mul_f32 v[18:19], v[18:19], v[34:35] op_sel_hi:[1,0]
	v_pk_mul_f32 v[16:17], v[16:17], v[34:35] op_sel_hi:[1,0]
	v_sub_f32_e32 v136, v136, v33
	v_sub_f32_e32 v135, v135, v33
	v_sub_f32_e32 v134, v134, v33
	v_sub_f32_e32 v133, v133, v33
	v_sub_f32_e32 v132, v132, v33
	v_sub_f32_e32 v131, v131, v33
	v_sub_f32_e32 v130, v130, v33
	v_sub_f32_e32 v129, v129, v33
	v_sub_f32_e32 v128, v128, v33
	v_sub_f32_e32 v127, v127, v33
	v_sub_f32_e32 v126, v126, v33
	v_sub_f32_e32 v125, v125, v33
	v_sub_f32_e32 v124, v124, v33
	v_sub_f32_e32 v123, v123, v33
	v_sub_f32_e32 v122, v122, v33
	v_sub_f32_e32 v95, v95, v33
	v_sub_f32_e32 v94, v94, v33
	v_sub_f32_e32 v93, v93, v33
	v_sub_f32_e32 v92, v92, v33
	v_sub_f32_e32 v91, v91, v33
	v_sub_f32_e32 v90, v90, v33
	v_sub_f32_e32 v89, v89, v33
	v_sub_f32_e32 v88, v88, v33
	v_sub_f32_e32 v87, v87, v33
	v_sub_f32_e32 v86, v86, v33
	v_sub_f32_e32 v85, v85, v33
	v_sub_f32_e32 v84, v84, v33
	v_sub_f32_e32 v83, v83, v33
	v_sub_f32_e32 v82, v82, v33
	v_sub_f32_e32 v81, v81, v33
	v_sub_f32_e32 v80, v80, v33
	v_mul_f32_e32 v100, v100, v34
	v_mov_b32_e32 v33, v32
	v_mov_b32_e32 v34, v32
	v_mov_b32_e32 v35, v32
	v_mov_b32_e32 v36, v32
	v_mov_b32_e32 v37, v32
	v_mov_b32_e32 v38, v32
	v_mov_b32_e32 v39, v32
	v_mov_b32_e32 v40, v32
	v_mov_b32_e32 v41, v32
	v_mov_b32_e32 v42, v32
	v_mov_b32_e32 v43, v32
	v_mov_b32_e32 v44, v32
	v_mov_b32_e32 v45, v32
	v_mov_b32_e32 v46, v32
	v_mov_b32_e32 v47, v32
	v_mov_b32_e32 v48, v32
	v_mov_b32_e32 v49, v32
	v_mov_b32_e32 v50, v32
	v_mov_b32_e32 v51, v32
	v_mov_b32_e32 v52, v32
	v_mov_b32_e32 v53, v32
	v_mov_b32_e32 v54, v32
	v_mov_b32_e32 v55, v32
	v_mov_b32_e32 v56, v32
	v_mov_b32_e32 v57, v32
	v_mov_b32_e32 v58, v32
	v_mov_b32_e32 v59, v32
	v_mov_b32_e32 v60, v32
	v_mov_b32_e32 v61, v32
	v_mov_b32_e32 v62, v32
	v_mov_b32_e32 v63, v32

; __device__ __forceinline__ unsigned pk2(float lo, float hi) { return pg8::cvt_pk_bf16(lo, hi); }
; template <int LO, int HI> __device__ __forceinline__ void g_exp(f32x16& X) {
; #pragma unroll
;     for (int r = LO; r < HI; ++r) X[r] = __builtin_amdgcn_exp2f(X[r]);
; }
; template <int LO, int HI> __device__ __forceinline__ void g_sumpk(const f32x16& X, float& psa, float& psb, u32x4& pwlo, u32x4& pwhi) {
; #pragma unroll
;     for (int r = LO; r < HI; r += 2) { psa += X[r]; psb += X[r + 1]; const unsigned w = pk2(X[r], X[r + 1]); if (r < 8) pwlo[(r >> 1) & 3] = w; else pwhi[(r >> 1) & 3] = w; }
;     asm volatile("" : "+v"(psa), "+v"(psb));
; }
.LBB0_1012:
	ds_read_b128 v[102:105], v181 offset:26656
	ds_read_b128 v[138:141], v181 offset:33312
	s_waitcnt lgkmcnt(3)
	v_mfma_f32_32x32x16_bf16 v[106:121], v[64:67], v[144:147], v[32:47]
	v_exp_f32_e32 v101, v122
	v_exp_f32_e32 v142, v123
	v_exp_f32_e32 v143, v124
	v_exp_f32_e32 v202, v125
	v_exp_f32_e32 v126, v126
	v_exp_f32_e32 v127, v127
	s_waitcnt lgkmcnt(2)
	v_mfma_f32_32x32x16_bf16 v[64:79], v[96:99], v[144:147], v[32:47]
	ds_read_b128 v[96:99], v181 offset:26688
	ds_read_b128 v[122:125], v181 offset:33344
	s_waitcnt lgkmcnt(3)
	v_mfma_f32_32x32x16_bf16 v[106:121], v[102:105], v[148:151], v[106:121]
	v_cvt_pk_bf16_f32 v102, v101, v142
	v_add_f32_e32 v101, v143, v101
	v_add_f32_e32 v104, v202, v142
	v_add_f32_e32 v101, v126, v101
	s_waitcnt lgkmcnt(2)
	v_mfma_f32_32x32x16_bf16 v[64:79], v[138:141], v[148:151], v[64:79]
	v_add_f32_e32 v105, v127, v104
	v_exp_f32_e32 v203, v128
	v_exp_f32_e32 v204, v129
	v_exp_f32_e32 v205, v130
	v_exp_f32_e32 v213, v131
	v_exp_f32_e32 v214, v132
	v_exp_f32_e32 v215, v133
	v_cvt_pk_bf16_f32 v103, v143, v202
	v_cvt_pk_bf16_f32 v104, v126, v127
	ds_read_b128 v[126:129], v181 offset:26720
	ds_read_b128 v[130:133], v181 offset:33376
	s_waitcnt lgkmcnt(3)
	v_mfma_f32_32x32x16_bf16 v[106:121], v[96:99], v[152:155], v[106:121]
	v_add_f32_e32 v96, v203, v101
	v_add_f32_e32 v97, v204, v105
	v_add_f32_e32 v98, v205, v96
	v_add_f32_e32 v97, v213, v97
	v_add_f32_e32 v98, v214, v98
	v_add_f32_e32 v99, v215, v97
	s_waitcnt lgkmcnt(2)
	v_mfma_f32_32x32x16_bf16 v[64:79], v[122:125], v[152:155], v[64:79]
	v_exp_f32_e32 v138, v134
	v_exp_f32_e32 v139, v135
	v_exp_f32_e32 v140, v136
	v_exp_f32_e32 v141, v137
	v_cvt_pk_bf16_f32 v105, v203, v204
	v_cvt_pk_bf16_f32 v96, v205, v213
	v_cvt_pk_bf16_f32 v97, v214, v215
	ds_read_b128 v[122:125], v181 offset:26752
	ds_read_b128 v[134:137], v181 offset:33408
	s_waitcnt lgkmcnt(3)
	v_mfma_f32_32x32x16_bf16 v[106:121], v[126:129], v[156:159], v[106:121]
	v_exp_f32_e32 v101, v80
	v_exp_f32_e32 v142, v81
	v_add_f32_e32 v80, v138, v98
	v_add_f32_e32 v81, v139, v99
	v_exp_f32_e32 v203, v84
	v_exp_f32_e32 v204, v85
	s_waitcnt lgkmcnt(2)
	v_mfma_f32_32x32x16_bf16 v[64:79], v[130:133], v[156:159], v[64:79]
	v_add_f32_e32 v84, v140, v80
	v_add_f32_e32 v85, v141, v81
	v_exp_f32_e32 v143, v82
	v_exp_f32_e32 v202, v83
	v_cvt_pk_bf16_f32 v98, v138, v139
	v_cvt_pk_bf16_f32 v99, v140, v141
	ds_read_b128 v[80:83], v181 offset:26784
	ds_read_b128 v[126:129], v181 offset:33440
	s_waitcnt lgkmcnt(3)
	v_mfma_f32_32x32x16_bf16 v[106:121], v[122:125], v[160:163], v[106:121]
	v_exp_f32_e32 v87, v87
	v_exp_f32_e32 v130, v86
	v_add_f32_e32 v86, v101, v84
	v_add_f32_e32 v85, v142, v85
	v_exp_f32_e32 v131, v88
	v_add_f32_e32 v86, v143, v86
	s_waitcnt lgkmcnt(2)
	v_mfma_f32_32x32x16_bf16 v[64:79], v[134:137], v[160:163], v[64:79]
	v_add_f32_e32 v88, v202, v85
	v_cvt_pk_bf16_f32 v84, v101, v142
	v_add_f32_e32 v101, v203, v86
	v_add_f32_e32 v134, v204, v88
	v_exp_f32_e32 v132, v89
	v_exp_f32_e32 v133, v90
	v_exp_f32_e32 v138, v91
	v_cvt_pk_bf16_f32 v85, v143, v202
	v_cvt_pk_bf16_f32 v86, v203, v204
	ds_read_b128 v[88:91], v210 offset:62464
	ds_read_b128 v[122:125], v211 offset:13824
	s_waitcnt lgkmcnt(3)
	v_mfma_f32_32x32x16_bf16 v[106:121], v[80:83], v[164:167], v[106:121]
	v_add_f32_e32 v80, v130, v101
	v_add_f32_e32 v81, v87, v134
	v_add_f32_e32 v82, v131, v80
	v_add_f32_e32 v81, v132, v81
	v_add_f32_e32 v82, v133, v82
	v_add_f32_e32 v83, v138, v81
	s_waitcnt lgkmcnt(2)
	v_mfma_f32_32x32x16_bf16 v[64:79], v[126:129], v[164:167], v[64:79]
	v_exp_f32_e32 v135, v92
	v_exp_f32_e32 v136, v93
	v_exp_f32_e32 v137, v94
	v_exp_f32_e32 v139, v95
	v_cvt_pk_bf16_f32 v87, v130, v87
	v_cvt_pk_bf16_f32 v80, v131, v132
	v_cvt_pk_bf16_f32 v81, v133, v138
	ds_read_b128 v[92:95], v210 offset:62496
	ds_read_b128 v[126:129], v211 offset:13856
	s_waitcnt lgkmcnt(3)
	v_mfma_f32_32x32x16_bf16 v[0:15], v[88:91], v[102:105], v[0:15]
	v_add_f32_e32 v88, v135, v82
	v_add_f32_e32 v83, v136, v83
	v_add_f32_e32 v101, v137, v88
	v_add_f32_e32 v130, v139, v83
	v_cvt_pk_bf16_f32 v82, v135, v136
	v_cvt_pk_bf16_f32 v83, v137, v139
	s_waitcnt lgkmcnt(2)
	v_mfma_f32_32x32x16_bf16 v[16:31], v[122:125], v[102:105], v[16:31]
	ds_read_b128 v[88:91], v210 offset:62528
	s_waitcnt lgkmcnt(2)
	v_mfma_f32_32x32x16_bf16 v[0:15], v[92:95], v[96:99], v[0:15]
	ds_read_b128 v[92:95], v211 offset:13888
	s_waitcnt lgkmcnt(2)
	v_mfma_f32_32x32x16_bf16 v[16:31], v[126:129], v[96:99], v[16:31]
	ds_read_b128 v[96:99], v210 offset:62560
	ds_read_b128 v[102:105], v211 offset:13920
	s_waitcnt lgkmcnt(3)
	v_mfma_f32_32x32x16_bf16 v[0:15], v[88:91], v[84:87], v[0:15]
	s_waitcnt lgkmcnt(2)
	v_mfma_f32_32x32x16_bf16 v[16:31], v[92:95], v[84:87], v[16:31]
	s_waitcnt lgkmcnt(1)
	v_mfma_f32_32x32x16_bf16 v[0:15], v[96:99], v[80:83], v[0:15]
	v_add_f32_e32 v221, v101, v130
	v_cmp_lt_f32_e32 vcc, s59, v221
	v_add_f32_e32 v88, v100, v221
	s_waitcnt lgkmcnt(0)
	v_mfma_f32_32x32x16_bf16 v[16:31], v[102:105], v[80:83], v[16:31]
	s_waitcnt vmcnt(0)
	s_barrier
	ds_read_b128 v[84:87], v181 offset:39936
	ds_read_b128 v[80:83], v181 offset:46592
	s_cbranch_vccz .LBB0_1014
	v_mov_b32_e32 v222, v221
	v_mov_b32_e32 v223, v221
	s_nop 1
	v_permlane32_swap_b32_e32 v222, v223
	v_add_f32_e32 v222, v222, v223
	v_log_f32_e32 v222, v222
	s_nop 0
	v_max_f32_e32 v33, 0, v222
	v_exp_f32_e64 v34, -v33
	v_add_f32_e32 v212, v212, v33
	v_xor_b32_e32 v32, 0x80000000, v212
	v_sub_f32_e32 v121, v121, v33
	v_pk_mul_f32 v[14:15], v[14:15], v[34:35] op_sel_hi:[1,0]
	v_pk_mul_f32 v[12:13], v[12:13], v[34:35] op_sel_hi:[1,0]
	v_pk_mul_f32 v[10:11], v[10:11], v[34:35] op_sel_hi:[1,0]
	v_pk_mul_f32 v[8:9], v[8:9], v[34:35] op_sel_hi:[1,0]
	v_pk_mul_f32 v[6:7], v[6:7], v[34:35] op_sel_hi:[1,0]
	v_pk_mul_f32 v[4:5], v[4:5], v[34:35] op_sel_hi:[1,0]
	v_pk_mul_f32 v[2:3], v[2:3], v[34:35] op_sel_hi:[1,0]
	v_pk_mul_f32 v[0:1], v[0:1], v[34:35] op_sel_hi:[1,0]
	v_pk_mul_f32 v[30:31], v[30:31], v[34:35] op_sel_hi:[1,0]
	v_pk_mul_f32 v[28:29], v[28:29], v[34:35] op_sel_hi:[1,0]
	v_pk_mul_f32 v[26:27], v[26:27], v[34:35] op_sel_hi:[1,0]
	v_pk_mul_f32 v[24:25], v[24:25], v[34:35] op_sel_hi:[1,0]
	v_pk_mul_f32 v[22:23], v[22:23], v[34:35] op_sel_hi:[1,0]
	v_pk_mul_f32 v[20:21], v[20:21], v[34:35] op_sel_hi:[1,0]
	v_pk_mul_f32 v[18:19], v[18:19], v[34:35] op_sel_hi:[1,0]
	v_pk_mul_f32 v[16:17], v[16:17], v[34:35] op_sel_hi:[1,0]
	v_sub_f32_e32 v120, v120, v33
	v_sub_f32_e32 v119, v119, v33
	v_sub_f32_e32 v118, v118, v33
	v_sub_f32_e32 v117, v117, v33
	v_sub_f32_e32 v116, v116, v33
	v_sub_f32_e32 v115, v115, v33
	v_sub_f32_e32 v114, v114, v33
	v_sub_f32_e32 v113, v113, v33
	v_sub_f32_e32 v112, v112, v33
	v_sub_f32_e32 v111, v111, v33
	v_sub_f32_e32 v110, v110, v33
	v_sub_f32_e32 v109, v109, v33
	v_sub_f32_e32 v108, v108, v33
	v_sub_f32_e32 v107, v107, v33
	v_sub_f32_e32 v106, v106, v33
	v_sub_f32_e32 v79, v79, v33
	v_sub_f32_e32 v78, v78, v33
	v_sub_f32_e32 v77, v77, v33
	v_sub_f32_e32 v76, v76, v33
	v_sub_f32_e32 v75, v75, v33
	v_sub_f32_e32 v74, v74, v33
	v_sub_f32_e32 v73, v73, v33
	v_sub_f32_e32 v72, v72, v33
	v_sub_f32_e32 v71, v71, v33
	v_sub_f32_e32 v70, v70, v33
	v_sub_f32_e32 v69, v69, v33
	v_sub_f32_e32 v68, v68, v33
	v_sub_f32_e32 v67, v67, v33
	v_sub_f32_e32 v66, v66, v33
	v_sub_f32_e32 v65, v65, v33
	v_sub_f32_e32 v64, v64, v33
	v_mul_f32_e32 v88, v88, v34
	v_mov_b32_e32 v33, v32
	v_mov_b32_e32 v34, v32
	v_mov_b32_e32 v35, v32
	v_mov_b32_e32 v36, v32
	v_mov_b32_e32 v37, v32
	v_mov_b32_e32 v38, v32
	v_mov_b32_e32 v39, v32
	v_mov_b32_e32 v40, v32
	v_mov_b32_e32 v41, v32
	v_mov_b32_e32 v42, v32
	v_mov_b32_e32 v43, v32
	v_mov_b32_e32 v44, v32
	v_mov_b32_e32 v45, v32
	v_mov_b32_e32 v46, v32
	v_mov_b32_e32 v47, v32
	v_mov_b32_e32 v48, v32
	v_mov_b32_e32 v49, v32
	v_mov_b32_e32 v50, v32
	v_mov_b32_e32 v51, v32
	v_mov_b32_e32 v52, v32
	v_mov_b32_e32 v53, v32
	v_mov_b32_e32 v54, v32
	v_mov_b32_e32 v55, v32
	v_mov_b32_e32 v56, v32
	v_mov_b32_e32 v57, v32
	v_mov_b32_e32 v58, v32
	v_mov_b32_e32 v59, v32
	v_mov_b32_e32 v60, v32
	v_mov_b32_e32 v61, v32
	v_mov_b32_e32 v62, v32
	v_mov_b32_e32 v63, v32

; __device__ __forceinline__ unsigned pk2(float lo, float hi) { return pg8::cvt_pk_bf16(lo, hi); }
; template <int LO, int HI> __device__ __forceinline__ void g_exp(f32x16& X) {
; #pragma unroll
;     for (int r = LO; r < HI; ++r) X[r] = __builtin_amdgcn_exp2f(X[r]);
; }
; template <int LO, int HI> __device__ __forceinline__ void g_sumpk(const f32x16& X, float& psa, float& psb, u32x4& pwlo, u32x4& pwhi) {
; #pragma unroll
;     for (int r = LO; r < HI; r += 2) { psa += X[r]; psb += X[r + 1]; const unsigned w = pk2(X[r], X[r + 1]); if (r < 8) pwlo[(r >> 1) & 3] = w; else pwhi[(r >> 1) & 3] = w; }
;     asm volatile("" : "+v"(psa), "+v"(psb));
; }
.LBB0_1018:
	s_waitcnt lgkmcnt(1)
	v_mfma_f32_32x32x16_bf16 v[122:137], v[84:87], v[144:147], v[32:47]
	v_exp_f32_e32 v89, v106
	v_exp_f32_e32 v94, v107
	v_exp_f32_e32 v95, v108
	v_exp_f32_e32 v142, v109
	v_exp_f32_e32 v143, v110
	v_exp_f32_e32 v202, v111
	ds_read_b128 v[84:87], v181 offset:39968
	ds_read_b128 v[90:93], v181 offset:46624
	s_waitcnt lgkmcnt(2)
	v_mfma_f32_32x32x16_bf16 v[96:111], v[80:83], v[144:147], v[32:47]
	ds_read_b128 v[80:83], v181 offset:40000
	ds_read_b128 v[138:141], v181 offset:46656
	s_waitcnt lgkmcnt(3)
	v_mfma_f32_32x32x16_bf16 v[122:137], v[84:87], v[148:151], v[122:137]
	v_exp_f32_e32 v116, v116
	v_add_f32_e32 v87, v95, v89
	v_add_f32_e32 v86, v142, v94
	v_cvt_pk_bf16_f32 v84, v89, v94
	s_waitcnt lgkmcnt(2)
	v_mfma_f32_32x32x16_bf16 v[96:111], v[90:93], v[148:151], v[96:111]
	v_add_f32_e32 v87, v143, v87
	v_add_f32_e32 v89, v202, v86
	v_exp_f32_e32 v203, v112
	v_exp_f32_e32 v204, v113
	v_exp_f32_e32 v205, v114
	v_exp_f32_e32 v213, v115
	v_exp_f32_e32 v117, v117
	v_cvt_pk_bf16_f32 v85, v95, v142
	v_cvt_pk_bf16_f32 v86, v143, v202
	ds_read_b128 v[90:93], v181 offset:40032
	ds_read_b128 v[112:115], v181 offset:46688
	s_waitcnt lgkmcnt(3)
	v_mfma_f32_32x32x16_bf16 v[122:137], v[80:83], v[152:155], v[122:137]
	v_add_f32_e32 v80, v203, v87
	v_add_f32_e32 v81, v204, v89
	v_add_f32_e32 v82, v205, v80
	v_add_f32_e32 v81, v213, v81
	v_add_f32_e32 v82, v116, v82
	v_add_f32_e32 v83, v117, v81
	s_waitcnt lgkmcnt(2)
	v_mfma_f32_32x32x16_bf16 v[96:111], v[138:141], v[152:155], v[96:111]
	v_exp_f32_e32 v94, v118
	v_exp_f32_e32 v95, v119
	v_exp_f32_e32 v120, v120
	v_exp_f32_e32 v121, v121
	v_cvt_pk_bf16_f32 v87, v203, v204
	v_cvt_pk_bf16_f32 v80, v205, v213
	v_cvt_pk_bf16_f32 v81, v116, v117
	ds_read_b128 v[116:119], v181 offset:40064
	ds_read_b128 v[138:141], v181 offset:46720
	s_waitcnt lgkmcnt(3)
	v_mfma_f32_32x32x16_bf16 v[122:137], v[90:93], v[156:159], v[122:137]
	v_exp_f32_e32 v89, v64
	v_exp_f32_e32 v142, v65
	v_add_f32_e32 v64, v94, v82
	v_add_f32_e32 v65, v95, v83
	v_exp_f32_e32 v203, v68
	v_exp_f32_e32 v204, v69
	s_waitcnt lgkmcnt(2)
	v_mfma_f32_32x32x16_bf16 v[96:111], v[112:115], v[156:159], v[96:111]
	v_add_f32_e32 v68, v120, v64
	v_add_f32_e32 v69, v121, v65
	v_exp_f32_e32 v143, v66
	v_exp_f32_e32 v202, v67
	v_cvt_pk_bf16_f32 v82, v94, v95
	v_cvt_pk_bf16_f32 v83, v120, v121
	ds_read_b128 v[64:67], v181 offset:40096
	ds_read_b128 v[90:93], v181 offset:46752
	s_waitcnt lgkmcnt(3)
	v_mfma_f32_32x32x16_bf16 v[122:137], v[116:119], v[160:163], v[122:137]
	v_exp_f32_e32 v116, v74
	v_exp_f32_e32 v94, v70
	v_add_f32_e32 v70, v89, v68
	v_add_f32_e32 v69, v142, v69
	v_exp_f32_e32 v95, v72
	v_add_f32_e32 v70, v143, v70
	s_waitcnt lgkmcnt(2)
	v_mfma_f32_32x32x16_bf16 v[96:111], v[138:141], v[160:163], v[96:111]
	v_add_f32_e32 v72, v202, v69
	v_cvt_pk_bf16_f32 v68, v89, v142
	v_add_f32_e32 v89, v203, v70
	v_add_f32_e32 v118, v204, v72
	v_exp_f32_e32 v71, v71
	v_exp_f32_e32 v120, v73
	v_exp_f32_e32 v117, v75
	v_cvt_pk_bf16_f32 v69, v143, v202
	v_cvt_pk_bf16_f32 v70, v203, v204
	ds_read_b128 v[72:75], v211 offset:18432
	ds_read_b128 v[112:115], v211 offset:23040
	s_waitcnt lgkmcnt(3)
	v_mfma_f32_32x32x16_bf16 v[122:137], v[64:67], v[164:167], v[122:137]
	v_add_f32_e32 v64, v94, v89
	v_add_f32_e32 v65, v71, v118
	v_add_f32_e32 v66, v95, v64
	v_add_f32_e32 v65, v120, v65
	v_add_f32_e32 v66, v116, v66
	v_add_f32_e32 v67, v117, v65
	s_waitcnt lgkmcnt(2)
	v_mfma_f32_32x32x16_bf16 v[96:111], v[90:93], v[164:167], v[96:111]
	v_exp_f32_e32 v119, v76
	v_exp_f32_e32 v121, v77
	v_exp_f32_e32 v138, v78
	v_exp_f32_e32 v139, v79
	v_cvt_pk_bf16_f32 v71, v94, v71
	v_cvt_pk_bf16_f32 v64, v95, v120
	v_cvt_pk_bf16_f32 v65, v116, v117
	ds_read_b128 v[76:79], v211 offset:18464
	ds_read_b128 v[90:93], v211 offset:23072
	s_waitcnt lgkmcnt(3)
	v_mfma_f32_32x32x16_bf16 v[0:15], v[72:75], v[84:87], v[0:15]
	v_add_f32_e32 v72, v119, v66
	v_add_f32_e32 v67, v121, v67
	v_add_f32_e32 v89, v138, v72
	v_add_f32_e32 v94, v139, v67
	v_cvt_pk_bf16_f32 v66, v119, v121
	v_cvt_pk_bf16_f32 v67, v138, v139
	s_waitcnt lgkmcnt(2)
	v_mfma_f32_32x32x16_bf16 v[16:31], v[112:115], v[84:87], v[16:31]
	ds_read_b128 v[72:75], v211 offset:18496
	s_waitcnt lgkmcnt(2)
	v_mfma_f32_32x32x16_bf16 v[0:15], v[76:79], v[80:83], v[0:15]
	ds_read_b128 v[76:79], v211 offset:23104
	s_waitcnt lgkmcnt(2)
	v_mfma_f32_32x32x16_bf16 v[16:31], v[90:93], v[80:83], v[16:31]
	ds_read_b128 v[80:83], v211 offset:18528
	ds_read_b128 v[84:87], v211 offset:23136
	s_waitcnt lgkmcnt(3)
	v_mfma_f32_32x32x16_bf16 v[0:15], v[72:75], v[68:71], v[0:15]
	s_waitcnt lgkmcnt(2)
	v_mfma_f32_32x32x16_bf16 v[16:31], v[76:79], v[68:71], v[16:31]
	s_waitcnt lgkmcnt(1)
	v_mfma_f32_32x32x16_bf16 v[0:15], v[80:83], v[64:67], v[0:15]
	v_add_f32_e32 v221, v89, v94
	v_cmp_lt_f32_e32 vcc, s59, v221
	v_add_f32_e32 v116, v88, v221
	s_waitcnt lgkmcnt(0)
	v_mfma_f32_32x32x16_bf16 v[16:31], v[84:87], v[64:67], v[16:31]
	ds_read_b128 v[64:67], v181
	ds_read_b128 v[112:115], v181 offset:6656
	s_cbranch_vccz .LBB0_1020
	v_mov_b32_e32 v222, v221
	v_mov_b32_e32 v223, v221
	s_nop 1
	v_permlane32_swap_b32_e32 v222, v223
	v_add_f32_e32 v222, v222, v223
	v_log_f32_e32 v222, v222
	s_nop 0
	v_max_f32_e32 v33, 0, v222
	v_exp_f32_e64 v34, -v33
	v_add_f32_e32 v212, v212, v33
	v_xor_b32_e32 v32, 0x80000000, v212
	v_sub_f32_e32 v137, v137, v33
	v_pk_mul_f32 v[14:15], v[14:15], v[34:35] op_sel_hi:[1,0]
	v_pk_mul_f32 v[12:13], v[12:13], v[34:35] op_sel_hi:[1,0]
	v_pk_mul_f32 v[10:11], v[10:11], v[34:35] op_sel_hi:[1,0]
	v_pk_mul_f32 v[8:9], v[8:9], v[34:35] op_sel_hi:[1,0]
	v_pk_mul_f32 v[6:7], v[6:7], v[34:35] op_sel_hi:[1,0]
	v_pk_mul_f32 v[4:5], v[4:5], v[34:35] op_sel_hi:[1,0]
	v_pk_mul_f32 v[2:3], v[2:3], v[34:35] op_sel_hi:[1,0]
	v_pk_mul_f32 v[0:1], v[0:1], v[34:35] op_sel_hi:[1,0]
	v_pk_mul_f32 v[30:31], v[30:31], v[34:35] op_sel_hi:[1,0]
	v_pk_mul_f32 v[28:29], v[28:29], v[34:35] op_sel_hi:[1,0]
	v_pk_mul_f32 v[26:27], v[26:27], v[34:35] op_sel_hi:[1,0]
	v_pk_mul_f32 v[24:25], v[24:25], v[34:35] op_sel_hi:[1,0]
	v_pk_mul_f32 v[22:23], v[22:23], v[34:35] op_sel_hi:[1,0]
	v_pk_mul_f32 v[20:21], v[20:21], v[34:35] op_sel_hi:[1,0]
	v_pk_mul_f32 v[18:19], v[18:19], v[34:35] op_sel_hi:[1,0]
	v_pk_mul_f32 v[16:17], v[16:17], v[34:35] op_sel_hi:[1,0]
	v_sub_f32_e32 v136, v136, v33
	v_sub_f32_e32 v135, v135, v33
	v_sub_f32_e32 v134, v134, v33
	v_sub_f32_e32 v133, v133, v33
	v_sub_f32_e32 v132, v132, v33
	v_sub_f32_e32 v131, v131, v33
	v_sub_f32_e32 v130, v130, v33
	v_sub_f32_e32 v129, v129, v33
	v_sub_f32_e32 v128, v128, v33
	v_sub_f32_e32 v127, v127, v33
	v_sub_f32_e32 v126, v126, v33
	v_sub_f32_e32 v125, v125, v33
	v_sub_f32_e32 v124, v124, v33
	v_sub_f32_e32 v123, v123, v33
	v_sub_f32_e32 v122, v122, v33
	v_sub_f32_e32 v111, v111, v33
	v_sub_f32_e32 v110, v110, v33
	v_sub_f32_e32 v109, v109, v33
	v_sub_f32_e32 v108, v108, v33
	v_sub_f32_e32 v107, v107, v33
	v_sub_f32_e32 v106, v106, v33
	v_sub_f32_e32 v105, v105, v33
	v_sub_f32_e32 v104, v104, v33
	v_sub_f32_e32 v103, v103, v33
	v_sub_f32_e32 v102, v102, v33
	v_sub_f32_e32 v101, v101, v33
	v_sub_f32_e32 v100, v100, v33
	v_sub_f32_e32 v99, v99, v33
	v_sub_f32_e32 v98, v98, v33
	v_sub_f32_e32 v97, v97, v33
	v_sub_f32_e32 v96, v96, v33
	v_mul_f32_e32 v116, v116, v34
	v_mov_b32_e32 v33, v32
	v_mov_b32_e32 v34, v32
	v_mov_b32_e32 v35, v32
	v_mov_b32_e32 v36, v32
	v_mov_b32_e32 v37, v32
	v_mov_b32_e32 v38, v32
	v_mov_b32_e32 v39, v32
	v_mov_b32_e32 v40, v32
	v_mov_b32_e32 v41, v32
	v_mov_b32_e32 v42, v32
	v_mov_b32_e32 v43, v32
	v_mov_b32_e32 v44, v32
	v_mov_b32_e32 v45, v32
	v_mov_b32_e32 v46, v32
	v_mov_b32_e32 v47, v32
	v_mov_b32_e32 v48, v32
	v_mov_b32_e32 v49, v32
	v_mov_b32_e32 v50, v32
	v_mov_b32_e32 v51, v32
	v_mov_b32_e32 v52, v32
	v_mov_b32_e32 v53, v32
	v_mov_b32_e32 v54, v32
	v_mov_b32_e32 v55, v32
	v_mov_b32_e32 v56, v32
	v_mov_b32_e32 v57, v32
	v_mov_b32_e32 v58, v32
	v_mov_b32_e32 v59, v32
	v_mov_b32_e32 v60, v32
	v_mov_b32_e32 v61, v32
	v_mov_b32_e32 v62, v32
	v_mov_b32_e32 v63, v32
